# P6 epilogues: per-item counted vmcnt waits and rolling item-level prefetch (loads for item b+2 issued as soon as item b is done)
# baseline (speedup 1.0000x reference)
.LBB0_1757:
	s_cmp_eq_u32 s46, 0
	s_cbranch_scc1 .Lp6e_nop
	s_load_dwordx2 s[2:3], s[62:63], 0xc0
	v_lshrrev_b32_e32 v164, 8, v208
	v_and_b32_e32 v165, 15, v208
	v_lshl_add_u32 v164, v164, 6, v165
	v_bfe_u32 v165, v208, 6, 2
	v_bfe_u32 v166, v208, 4, 2
	v_lshlrev_b32_e32 v165, 6, v165
	v_lshl_add_u32 v165, v166, 4, v165
	v_lshl_add_u32 v216, v164, 9, v165
	v_lshl_add_u32 v221, v164, 11, v165
	s_mul_i32 s0, s48, 49
	s_lshl_b32 s19, s46, 2
	s_add_i32 s0, s0, s19
	s_add_i32 s0, s0, s47
	s_add_i32 s0, s0, 29
	s_lshl_b32 s0, s0, 17
	s_lshl_b32 s19, s48, 19
	s_lshl_b32 s32, s47, 9
	s_add_i32 s19, s19, s32
	s_mov_b32 s60, 0xbfb8aa3b
	s_mov_b32 s61, 0xbfb8aa3b
	s_mov_b32 s78, 1.0
	s_mov_b32 s79, 1.0
	s_waitcnt lgkmcnt(0)
	s_add_u32 s24, s2, 0x74c2800
	s_addc_u32 s25, s3, 0
	s_add_u32 s24, s24, s0
	s_addc_u32 s25, s25, 0
	s_add_u32 s26, s2, 0x244c2800
	s_addc_u32 s27, s3, 0
	s_add_u32 s26, s26, s19
	s_addc_u32 s27, s27, 0
	s_add_u32 s8, s24, 0x0
	s_addc_u32 s9, s25, 0
	global_load_dwordx4 v[132:135], v216, s[8:9]
	s_add_u32 s8, s26, 0x0
	s_addc_u32 s9, s27, 0
	global_load_dwordx4 v[148:151], v221, s[8:9]
	s_add_u32 s8, s24, 0x0
	s_addc_u32 s9, s25, 0
	global_load_dwordx4 v[136:139], v216, s[8:9] offset:256
	s_add_u32 s8, s26, 0x0
	s_addc_u32 s9, s27, 0
	global_load_dwordx4 v[152:155], v221, s[8:9] offset:256
	s_add_u32 s8, s24, 0x2000
	s_addc_u32 s9, s25, 0
	global_load_dwordx4 v[140:143], v216, s[8:9]
	s_add_u32 s8, s26, 0x8000
	s_addc_u32 s9, s27, 0
	global_load_dwordx4 v[156:159], v221, s[8:9]
	s_add_u32 s8, s24, 0x2000
	s_addc_u32 s9, s25, 0
	global_load_dwordx4 v[144:147], v216, s[8:9] offset:256
	s_add_u32 s8, s26, 0x8000
	s_addc_u32 s9, s27, 0
	global_load_dwordx4 v[160:163], v221, s[8:9] offset:256
	s_add_u32 s8, s24, 0x4000
	s_addc_u32 s9, s25, 0
	global_load_dwordx4 v[224:227], v216, s[8:9]
	s_add_u32 s8, s26, 0x10000
	s_addc_u32 s9, s27, 0
	global_load_dwordx4 v[194:197], v221, s[8:9]
	s_add_u32 s8, s24, 0x4000
	s_addc_u32 s9, s25, 0
	global_load_dwordx4 v[228:231], v216, s[8:9] offset:256
	s_add_u32 s8, s26, 0x10000
	s_addc_u32 s9, s27, 0
	global_load_dwordx4 v[198:201], v221, s[8:9] offset:256
	s_add_u32 s8, s24, 0x6000
	s_addc_u32 s9, s25, 0
	global_load_dwordx4 v[232:235], v216, s[8:9]
	s_add_u32 s8, s26, 0x18000
	s_addc_u32 s9, s27, 0
	global_load_dwordx4 v[202:205], v221, s[8:9]
	s_add_u32 s8, s24, 0x6000
	s_addc_u32 s9, s25, 0
	global_load_dwordx4 v[236:239], v216, s[8:9] offset:256
	s_add_u32 s8, s26, 0x18000
	s_addc_u32 s9, s27, 0
	global_load_dwordx4 v[240:243], v221, s[8:9] offset:256
	s_waitcnt vmcnt(14)
	s_add_u32 s98, s26, 0x0
	s_addc_u32 s99, s27, 0
	v_lshlrev_b32_e32 v164, 16, v132
	v_lshlrev_b32_e32 v170, 16, v133
	v_lshlrev_b32_e32 v172, 16, v134
	v_lshlrev_b32_e32 v206, 16, v135
	v_and_b32_e32 v165, 0xffff0000, v132
	v_and_b32_e32 v171, 0xffff0000, v133
	v_and_b32_e32 v173, 0xffff0000, v134
	v_and_b32_e32 v207, 0xffff0000, v135
	v_pk_mul_f32 v[164:165], v[164:165], s[60:61]
	v_pk_mul_f32 v[170:171], v[170:171], s[60:61]
	v_pk_mul_f32 v[172:173], v[172:173], s[60:61]
	v_pk_mul_f32 v[206:207], v[206:207], s[60:61]
	v_exp_f32_e32 v164, v164
	v_exp_f32_e32 v170, v170
	v_exp_f32_e32 v172, v172
	v_exp_f32_e32 v206, v206
	v_exp_f32_e32 v165, v165
	v_exp_f32_e32 v171, v171
	v_exp_f32_e32 v173, v173
	v_exp_f32_e32 v207, v207
	v_pk_add_f32 v[164:165], v[164:165], s[78:79]
	v_pk_add_f32 v[170:171], v[170:171], s[78:79]
	v_pk_add_f32 v[172:173], v[172:173], s[78:79]
	v_pk_add_f32 v[206:207], v[206:207], s[78:79]
	v_rcp_f32_e32 v164, v164
	v_rcp_f32_e32 v170, v170
	v_rcp_f32_e32 v172, v172
	v_rcp_f32_e32 v206, v206
	v_rcp_f32_e32 v165, v165
	v_rcp_f32_e32 v171, v171
	v_rcp_f32_e32 v173, v173
	v_rcp_f32_e32 v207, v207
	v_lshlrev_b32_e32 v210, 16, v148
	v_lshlrev_b32_e32 v244, 16, v149
	v_lshlrev_b32_e32 v248, 16, v150
	v_lshlrev_b32_e32 v250, 16, v151
	v_and_b32_e32 v211, 0xffff0000, v148
	v_and_b32_e32 v245, 0xffff0000, v149
	v_and_b32_e32 v249, 0xffff0000, v150
	v_and_b32_e32 v251, 0xffff0000, v151
	v_pk_fma_f32 v[128:129], v[128:129], v[164:165], v[210:211]
	v_pk_fma_f32 v[130:131], v[130:131], v[170:171], v[244:245]
	v_pk_fma_f32 v[124:125], v[124:125], v[172:173], v[248:249]
	v_pk_fma_f32 v[126:127], v[126:127], v[206:207], v[250:251]
	v_cvt_pk_bf16_f32 v128, v128, v129
	v_cvt_pk_bf16_f32 v129, v130, v131
	v_cvt_pk_bf16_f32 v130, v124, v125
	v_cvt_pk_bf16_f32 v131, v126, v127
	global_store_dwordx4 v221, v[128:131], s[98:99]
	s_add_u32 s8, s24, 0x10000
	s_addc_u32 s9, s25, 0
	global_load_dwordx4 v[132:135], v216, s[8:9]
	s_add_u32 s8, s26, 0x40000
	s_addc_u32 s9, s27, 0
	global_load_dwordx4 v[148:151], v221, s[8:9]
	s_waitcnt vmcnt(15)
	s_add_u32 s98, s26, 0x0
	s_addc_u32 s99, s27, 0
	v_lshlrev_b32_e32 v164, 16, v136
	v_lshlrev_b32_e32 v170, 16, v137
	v_lshlrev_b32_e32 v172, 16, v138
	v_lshlrev_b32_e32 v206, 16, v139
	v_and_b32_e32 v165, 0xffff0000, v136
	v_and_b32_e32 v171, 0xffff0000, v137
	v_and_b32_e32 v173, 0xffff0000, v138
	v_and_b32_e32 v207, 0xffff0000, v139
	v_pk_mul_f32 v[164:165], v[164:165], s[60:61]
	v_pk_mul_f32 v[170:171], v[170:171], s[60:61]
	v_pk_mul_f32 v[172:173], v[172:173], s[60:61]
	v_pk_mul_f32 v[206:207], v[206:207], s[60:61]
	v_exp_f32_e32 v164, v164
	v_exp_f32_e32 v170, v170
	v_exp_f32_e32 v172, v172
	v_exp_f32_e32 v206, v206
	v_exp_f32_e32 v165, v165
	v_exp_f32_e32 v171, v171
	v_exp_f32_e32 v173, v173
	v_exp_f32_e32 v207, v207
	v_pk_add_f32 v[164:165], v[164:165], s[78:79]
	v_pk_add_f32 v[170:171], v[170:171], s[78:79]
	v_pk_add_f32 v[172:173], v[172:173], s[78:79]
	v_pk_add_f32 v[206:207], v[206:207], s[78:79]
	v_rcp_f32_e32 v164, v164
	v_rcp_f32_e32 v170, v170
	v_rcp_f32_e32 v172, v172
	v_rcp_f32_e32 v206, v206
	v_rcp_f32_e32 v165, v165
	v_rcp_f32_e32 v171, v171
	v_rcp_f32_e32 v173, v173
	v_rcp_f32_e32 v207, v207
	v_lshlrev_b32_e32 v210, 16, v152
	v_lshlrev_b32_e32 v244, 16, v153
	v_lshlrev_b32_e32 v248, 16, v154
	v_lshlrev_b32_e32 v250, 16, v155
	v_and_b32_e32 v211, 0xffff0000, v152
	v_and_b32_e32 v245, 0xffff0000, v153
	v_and_b32_e32 v249, 0xffff0000, v154
	v_and_b32_e32 v251, 0xffff0000, v155
	v_pk_fma_f32 v[120:121], v[120:121], v[164:165], v[210:211]
	v_pk_fma_f32 v[122:123], v[122:123], v[170:171], v[244:245]
	v_pk_fma_f32 v[116:117], v[116:117], v[172:173], v[248:249]
	v_pk_fma_f32 v[118:119], v[118:119], v[206:207], v[250:251]
	v_cvt_pk_bf16_f32 v120, v120, v121
	v_cvt_pk_bf16_f32 v121, v122, v123
	v_cvt_pk_bf16_f32 v122, v116, v117
	v_cvt_pk_bf16_f32 v123, v118, v119
	global_store_dwordx4 v221, v[120:123], s[98:99] offset:256
	s_add_u32 s8, s24, 0x10000
	s_addc_u32 s9, s25, 0
	global_load_dwordx4 v[136:139], v216, s[8:9] offset:256
	s_add_u32 s8, s26, 0x40000
	s_addc_u32 s9, s27, 0
	global_load_dwordx4 v[152:155], v221, s[8:9] offset:256
	s_waitcnt vmcnt(16)
	s_add_u32 s98, s26, 0x8000
	s_addc_u32 s99, s27, 0
	v_lshlrev_b32_e32 v164, 16, v140
	v_lshlrev_b32_e32 v170, 16, v141
	v_lshlrev_b32_e32 v172, 16, v142
	v_lshlrev_b32_e32 v206, 16, v143
	v_and_b32_e32 v165, 0xffff0000, v140
	v_and_b32_e32 v171, 0xffff0000, v141
	v_and_b32_e32 v173, 0xffff0000, v142
	v_and_b32_e32 v207, 0xffff0000, v143
	v_pk_mul_f32 v[164:165], v[164:165], s[60:61]
	v_pk_mul_f32 v[170:171], v[170:171], s[60:61]
	v_pk_mul_f32 v[172:173], v[172:173], s[60:61]
	v_pk_mul_f32 v[206:207], v[206:207], s[60:61]
	v_exp_f32_e32 v164, v164
	v_exp_f32_e32 v170, v170
	v_exp_f32_e32 v172, v172
	v_exp_f32_e32 v206, v206
	v_exp_f32_e32 v165, v165
	v_exp_f32_e32 v171, v171
	v_exp_f32_e32 v173, v173
	v_exp_f32_e32 v207, v207
	v_pk_add_f32 v[164:165], v[164:165], s[78:79]
	v_pk_add_f32 v[170:171], v[170:171], s[78:79]
	v_pk_add_f32 v[172:173], v[172:173], s[78:79]
	v_pk_add_f32 v[206:207], v[206:207], s[78:79]
	v_rcp_f32_e32 v164, v164
	v_rcp_f32_e32 v170, v170
	v_rcp_f32_e32 v172, v172
	v_rcp_f32_e32 v206, v206
	v_rcp_f32_e32 v165, v165
	v_rcp_f32_e32 v171, v171
	v_rcp_f32_e32 v173, v173
	v_rcp_f32_e32 v207, v207
	v_lshlrev_b32_e32 v210, 16, v156
	v_lshlrev_b32_e32 v244, 16, v157
	v_lshlrev_b32_e32 v248, 16, v158
	v_lshlrev_b32_e32 v250, 16, v159
	v_and_b32_e32 v211, 0xffff0000, v156
	v_and_b32_e32 v245, 0xffff0000, v157
	v_and_b32_e32 v249, 0xffff0000, v158
	v_and_b32_e32 v251, 0xffff0000, v159
	v_pk_fma_f32 v[112:113], v[112:113], v[164:165], v[210:211]
	v_pk_fma_f32 v[114:115], v[114:115], v[170:171], v[244:245]
	v_pk_fma_f32 v[108:109], v[108:109], v[172:173], v[248:249]
	v_pk_fma_f32 v[110:111], v[110:111], v[206:207], v[250:251]
	v_cvt_pk_bf16_f32 v112, v112, v113
	v_cvt_pk_bf16_f32 v113, v114, v115
	v_cvt_pk_bf16_f32 v114, v108, v109
	v_cvt_pk_bf16_f32 v115, v110, v111
	global_store_dwordx4 v221, v[112:115], s[98:99]
	s_add_u32 s8, s24, 0x12000
	s_addc_u32 s9, s25, 0
	global_load_dwordx4 v[140:143], v216, s[8:9]
	s_add_u32 s8, s26, 0x48000
	s_addc_u32 s9, s27, 0
	global_load_dwordx4 v[156:159], v221, s[8:9]
	s_waitcnt vmcnt(17)
	s_add_u32 s98, s26, 0x8000
	s_addc_u32 s99, s27, 0
	v_lshlrev_b32_e32 v164, 16, v144
	v_lshlrev_b32_e32 v170, 16, v145
	v_lshlrev_b32_e32 v172, 16, v146
	v_lshlrev_b32_e32 v206, 16, v147
	v_and_b32_e32 v165, 0xffff0000, v144
	v_and_b32_e32 v171, 0xffff0000, v145
	v_and_b32_e32 v173, 0xffff0000, v146
	v_and_b32_e32 v207, 0xffff0000, v147
	v_pk_mul_f32 v[164:165], v[164:165], s[60:61]
	v_pk_mul_f32 v[170:171], v[170:171], s[60:61]
	v_pk_mul_f32 v[172:173], v[172:173], s[60:61]
	v_pk_mul_f32 v[206:207], v[206:207], s[60:61]
	v_exp_f32_e32 v164, v164
	v_exp_f32_e32 v170, v170
	v_exp_f32_e32 v172, v172
	v_exp_f32_e32 v206, v206
	v_exp_f32_e32 v165, v165
	v_exp_f32_e32 v171, v171
	v_exp_f32_e32 v173, v173
	v_exp_f32_e32 v207, v207
	v_pk_add_f32 v[164:165], v[164:165], s[78:79]
	v_pk_add_f32 v[170:171], v[170:171], s[78:79]
	v_pk_add_f32 v[172:173], v[172:173], s[78:79]
	v_pk_add_f32 v[206:207], v[206:207], s[78:79]
	v_rcp_f32_e32 v164, v164
	v_rcp_f32_e32 v170, v170
	v_rcp_f32_e32 v172, v172
	v_rcp_f32_e32 v206, v206
	v_rcp_f32_e32 v165, v165
	v_rcp_f32_e32 v171, v171
	v_rcp_f32_e32 v173, v173
	v_rcp_f32_e32 v207, v207
	v_lshlrev_b32_e32 v210, 16, v160
	v_lshlrev_b32_e32 v244, 16, v161
	v_lshlrev_b32_e32 v248, 16, v162
	v_lshlrev_b32_e32 v250, 16, v163
	v_and_b32_e32 v211, 0xffff0000, v160
	v_and_b32_e32 v245, 0xffff0000, v161
	v_and_b32_e32 v249, 0xffff0000, v162
	v_and_b32_e32 v251, 0xffff0000, v163
	v_pk_fma_f32 v[104:105], v[104:105], v[164:165], v[210:211]
	v_pk_fma_f32 v[106:107], v[106:107], v[170:171], v[244:245]
	v_pk_fma_f32 v[100:101], v[100:101], v[172:173], v[248:249]
	v_pk_fma_f32 v[102:103], v[102:103], v[206:207], v[250:251]
	v_cvt_pk_bf16_f32 v104, v104, v105
	v_cvt_pk_bf16_f32 v105, v106, v107
	v_cvt_pk_bf16_f32 v106, v100, v101
	v_cvt_pk_bf16_f32 v107, v102, v103
	global_store_dwordx4 v221, v[104:107], s[98:99] offset:256
	s_add_u32 s8, s24, 0x12000
	s_addc_u32 s9, s25, 0
	global_load_dwordx4 v[144:147], v216, s[8:9] offset:256
	s_add_u32 s8, s26, 0x48000
	s_addc_u32 s9, s27, 0
	global_load_dwordx4 v[160:163], v221, s[8:9] offset:256
	s_waitcnt vmcnt(18)
	s_add_u32 s98, s26, 0x10000
	s_addc_u32 s99, s27, 0
	v_lshlrev_b32_e32 v164, 16, v224
	v_lshlrev_b32_e32 v170, 16, v225
	v_lshlrev_b32_e32 v172, 16, v226
	v_lshlrev_b32_e32 v206, 16, v227
	v_and_b32_e32 v165, 0xffff0000, v224
	v_and_b32_e32 v171, 0xffff0000, v225
	v_and_b32_e32 v173, 0xffff0000, v226
	v_and_b32_e32 v207, 0xffff0000, v227
	v_pk_mul_f32 v[164:165], v[164:165], s[60:61]
	v_pk_mul_f32 v[170:171], v[170:171], s[60:61]
	v_pk_mul_f32 v[172:173], v[172:173], s[60:61]
	v_pk_mul_f32 v[206:207], v[206:207], s[60:61]
	v_exp_f32_e32 v164, v164
	v_exp_f32_e32 v170, v170
	v_exp_f32_e32 v172, v172
	v_exp_f32_e32 v206, v206
	v_exp_f32_e32 v165, v165
	v_exp_f32_e32 v171, v171
	v_exp_f32_e32 v173, v173
	v_exp_f32_e32 v207, v207
	v_pk_add_f32 v[164:165], v[164:165], s[78:79]
	v_pk_add_f32 v[170:171], v[170:171], s[78:79]
	v_pk_add_f32 v[172:173], v[172:173], s[78:79]
	v_pk_add_f32 v[206:207], v[206:207], s[78:79]
	v_rcp_f32_e32 v164, v164
	v_rcp_f32_e32 v170, v170
	v_rcp_f32_e32 v172, v172
	v_rcp_f32_e32 v206, v206
	v_rcp_f32_e32 v165, v165
	v_rcp_f32_e32 v171, v171
	v_rcp_f32_e32 v173, v173
	v_rcp_f32_e32 v207, v207
	v_lshlrev_b32_e32 v210, 16, v194
	v_lshlrev_b32_e32 v244, 16, v195
	v_lshlrev_b32_e32 v248, 16, v196
	v_lshlrev_b32_e32 v250, 16, v197
	v_and_b32_e32 v211, 0xffff0000, v194
	v_and_b32_e32 v245, 0xffff0000, v195
	v_and_b32_e32 v249, 0xffff0000, v196
	v_and_b32_e32 v251, 0xffff0000, v197
	v_pk_fma_f32 v[96:97], v[96:97], v[164:165], v[210:211]
	v_pk_fma_f32 v[98:99], v[98:99], v[170:171], v[244:245]
	v_pk_fma_f32 v[92:93], v[92:93], v[172:173], v[248:249]
	v_pk_fma_f32 v[94:95], v[94:95], v[206:207], v[250:251]
	v_cvt_pk_bf16_f32 v96, v96, v97
	v_cvt_pk_bf16_f32 v97, v98, v99
	v_cvt_pk_bf16_f32 v98, v92, v93
	v_cvt_pk_bf16_f32 v99, v94, v95
	global_store_dwordx4 v221, v[96:99], s[98:99]
	s_add_u32 s8, s24, 0x14000
	s_addc_u32 s9, s25, 0
	global_load_dwordx4 v[224:227], v216, s[8:9]
	s_add_u32 s8, s26, 0x50000
	s_addc_u32 s9, s27, 0
	global_load_dwordx4 v[194:197], v221, s[8:9]
	s_waitcnt vmcnt(19)
	s_add_u32 s98, s26, 0x10000
	s_addc_u32 s99, s27, 0
	v_lshlrev_b32_e32 v164, 16, v228
	v_lshlrev_b32_e32 v170, 16, v229
	v_lshlrev_b32_e32 v172, 16, v230
	v_lshlrev_b32_e32 v206, 16, v231
	v_and_b32_e32 v165, 0xffff0000, v228
	v_and_b32_e32 v171, 0xffff0000, v229
	v_and_b32_e32 v173, 0xffff0000, v230
	v_and_b32_e32 v207, 0xffff0000, v231
	v_pk_mul_f32 v[164:165], v[164:165], s[60:61]
	v_pk_mul_f32 v[170:171], v[170:171], s[60:61]
	v_pk_mul_f32 v[172:173], v[172:173], s[60:61]
	v_pk_mul_f32 v[206:207], v[206:207], s[60:61]
	v_exp_f32_e32 v164, v164
	v_exp_f32_e32 v170, v170
	v_exp_f32_e32 v172, v172
	v_exp_f32_e32 v206, v206
	v_exp_f32_e32 v165, v165
	v_exp_f32_e32 v171, v171
	v_exp_f32_e32 v173, v173
	v_exp_f32_e32 v207, v207
	v_pk_add_f32 v[164:165], v[164:165], s[78:79]
	v_pk_add_f32 v[170:171], v[170:171], s[78:79]
	v_pk_add_f32 v[172:173], v[172:173], s[78:79]
	v_pk_add_f32 v[206:207], v[206:207], s[78:79]
	v_rcp_f32_e32 v164, v164
	v_rcp_f32_e32 v170, v170
	v_rcp_f32_e32 v172, v172
	v_rcp_f32_e32 v206, v206
	v_rcp_f32_e32 v165, v165
	v_rcp_f32_e32 v171, v171
	v_rcp_f32_e32 v173, v173
	v_rcp_f32_e32 v207, v207
	v_lshlrev_b32_e32 v210, 16, v198
	v_lshlrev_b32_e32 v244, 16, v199
	v_lshlrev_b32_e32 v248, 16, v200
	v_lshlrev_b32_e32 v250, 16, v201
	v_and_b32_e32 v211, 0xffff0000, v198
	v_and_b32_e32 v245, 0xffff0000, v199
	v_and_b32_e32 v249, 0xffff0000, v200
	v_and_b32_e32 v251, 0xffff0000, v201
	v_pk_fma_f32 v[88:89], v[88:89], v[164:165], v[210:211]
	v_pk_fma_f32 v[90:91], v[90:91], v[170:171], v[244:245]
	v_pk_fma_f32 v[84:85], v[84:85], v[172:173], v[248:249]
	v_pk_fma_f32 v[86:87], v[86:87], v[206:207], v[250:251]
	v_cvt_pk_bf16_f32 v88, v88, v89
	v_cvt_pk_bf16_f32 v89, v90, v91
	v_cvt_pk_bf16_f32 v90, v84, v85
	v_cvt_pk_bf16_f32 v91, v86, v87
	global_store_dwordx4 v221, v[88:91], s[98:99] offset:256
	s_add_u32 s8, s24, 0x14000
	s_addc_u32 s9, s25, 0
	global_load_dwordx4 v[228:231], v216, s[8:9] offset:256
	s_add_u32 s8, s26, 0x50000
	s_addc_u32 s9, s27, 0
	global_load_dwordx4 v[198:201], v221, s[8:9] offset:256
	s_waitcnt vmcnt(20)
	s_add_u32 s98, s26, 0x18000
	s_addc_u32 s99, s27, 0
	v_lshlrev_b32_e32 v164, 16, v232
	v_lshlrev_b32_e32 v170, 16, v233
	v_lshlrev_b32_e32 v172, 16, v234
	v_lshlrev_b32_e32 v206, 16, v235
	v_and_b32_e32 v165, 0xffff0000, v232
	v_and_b32_e32 v171, 0xffff0000, v233
	v_and_b32_e32 v173, 0xffff0000, v234
	v_and_b32_e32 v207, 0xffff0000, v235
	v_pk_mul_f32 v[164:165], v[164:165], s[60:61]
	v_pk_mul_f32 v[170:171], v[170:171], s[60:61]
	v_pk_mul_f32 v[172:173], v[172:173], s[60:61]
	v_pk_mul_f32 v[206:207], v[206:207], s[60:61]
	v_exp_f32_e32 v164, v164
	v_exp_f32_e32 v170, v170
	v_exp_f32_e32 v172, v172
	v_exp_f32_e32 v206, v206
	v_exp_f32_e32 v165, v165
	v_exp_f32_e32 v171, v171
	v_exp_f32_e32 v173, v173
	v_exp_f32_e32 v207, v207
	v_pk_add_f32 v[164:165], v[164:165], s[78:79]
	v_pk_add_f32 v[170:171], v[170:171], s[78:79]
	v_pk_add_f32 v[172:173], v[172:173], s[78:79]
	v_pk_add_f32 v[206:207], v[206:207], s[78:79]
	v_rcp_f32_e32 v164, v164
	v_rcp_f32_e32 v170, v170
	v_rcp_f32_e32 v172, v172
	v_rcp_f32_e32 v206, v206
	v_rcp_f32_e32 v165, v165
	v_rcp_f32_e32 v171, v171
	v_rcp_f32_e32 v173, v173
	v_rcp_f32_e32 v207, v207
	v_lshlrev_b32_e32 v210, 16, v202
	v_lshlrev_b32_e32 v244, 16, v203
	v_lshlrev_b32_e32 v248, 16, v204
	v_lshlrev_b32_e32 v250, 16, v205
	v_and_b32_e32 v211, 0xffff0000, v202
	v_and_b32_e32 v245, 0xffff0000, v203
	v_and_b32_e32 v249, 0xffff0000, v204
	v_and_b32_e32 v251, 0xffff0000, v205
	v_pk_fma_f32 v[76:77], v[76:77], v[164:165], v[210:211]
	v_pk_fma_f32 v[78:79], v[78:79], v[170:171], v[244:245]
	v_pk_fma_f32 v[72:73], v[72:73], v[172:173], v[248:249]
	v_pk_fma_f32 v[74:75], v[74:75], v[206:207], v[250:251]
	v_cvt_pk_bf16_f32 v76, v76, v77
	v_cvt_pk_bf16_f32 v77, v78, v79
	v_cvt_pk_bf16_f32 v78, v72, v73
	v_cvt_pk_bf16_f32 v79, v74, v75
	global_store_dwordx4 v221, v[76:79], s[98:99]
	s_add_u32 s8, s24, 0x16000
	s_addc_u32 s9, s25, 0
	global_load_dwordx4 v[232:235], v216, s[8:9]
	s_add_u32 s8, s26, 0x58000
	s_addc_u32 s9, s27, 0
	global_load_dwordx4 v[202:205], v221, s[8:9]
	s_waitcnt vmcnt(21)
	s_add_u32 s98, s26, 0x18000
	s_addc_u32 s99, s27, 0
	v_lshlrev_b32_e32 v164, 16, v236
	v_lshlrev_b32_e32 v170, 16, v237
	v_lshlrev_b32_e32 v172, 16, v238
	v_lshlrev_b32_e32 v206, 16, v239
	v_and_b32_e32 v165, 0xffff0000, v236
	v_and_b32_e32 v171, 0xffff0000, v237
	v_and_b32_e32 v173, 0xffff0000, v238
	v_and_b32_e32 v207, 0xffff0000, v239
	v_pk_mul_f32 v[164:165], v[164:165], s[60:61]
	v_pk_mul_f32 v[170:171], v[170:171], s[60:61]
	v_pk_mul_f32 v[172:173], v[172:173], s[60:61]
	v_pk_mul_f32 v[206:207], v[206:207], s[60:61]
	v_exp_f32_e32 v164, v164
	v_exp_f32_e32 v170, v170
	v_exp_f32_e32 v172, v172
	v_exp_f32_e32 v206, v206
	v_exp_f32_e32 v165, v165
	v_exp_f32_e32 v171, v171
	v_exp_f32_e32 v173, v173
	v_exp_f32_e32 v207, v207
	v_pk_add_f32 v[164:165], v[164:165], s[78:79]
	v_pk_add_f32 v[170:171], v[170:171], s[78:79]
	v_pk_add_f32 v[172:173], v[172:173], s[78:79]
	v_pk_add_f32 v[206:207], v[206:207], s[78:79]
	v_rcp_f32_e32 v164, v164
	v_rcp_f32_e32 v170, v170
	v_rcp_f32_e32 v172, v172
	v_rcp_f32_e32 v206, v206
	v_rcp_f32_e32 v165, v165
	v_rcp_f32_e32 v171, v171
	v_rcp_f32_e32 v173, v173
	v_rcp_f32_e32 v207, v207
	v_lshlrev_b32_e32 v210, 16, v240
	v_lshlrev_b32_e32 v244, 16, v241
	v_lshlrev_b32_e32 v248, 16, v242
	v_lshlrev_b32_e32 v250, 16, v243
	v_and_b32_e32 v211, 0xffff0000, v240
	v_and_b32_e32 v245, 0xffff0000, v241
	v_and_b32_e32 v249, 0xffff0000, v242
	v_and_b32_e32 v251, 0xffff0000, v243
	v_pk_fma_f32 v[68:69], v[68:69], v[164:165], v[210:211]
	v_pk_fma_f32 v[70:71], v[70:71], v[170:171], v[244:245]
	v_pk_fma_f32 v[64:65], v[64:65], v[172:173], v[248:249]
	v_pk_fma_f32 v[66:67], v[66:67], v[206:207], v[250:251]
	v_cvt_pk_bf16_f32 v68, v68, v69
	v_cvt_pk_bf16_f32 v69, v70, v71
	v_cvt_pk_bf16_f32 v70, v64, v65
	v_cvt_pk_bf16_f32 v71, v66, v67
	global_store_dwordx4 v221, v[68:71], s[98:99] offset:256
	s_add_u32 s8, s24, 0x16000
	s_addc_u32 s9, s25, 0
	global_load_dwordx4 v[236:239], v216, s[8:9] offset:256
	s_add_u32 s8, s26, 0x58000
	s_addc_u32 s9, s27, 0
	global_load_dwordx4 v[240:243], v221, s[8:9] offset:256
	s_waitcnt vmcnt(21)
	s_add_u32 s98, s26, 0x40000
	s_addc_u32 s99, s27, 0
	v_lshlrev_b32_e32 v164, 16, v132
	v_lshlrev_b32_e32 v170, 16, v133
	v_lshlrev_b32_e32 v172, 16, v134
	v_lshlrev_b32_e32 v206, 16, v135
	v_and_b32_e32 v165, 0xffff0000, v132
	v_and_b32_e32 v171, 0xffff0000, v133
	v_and_b32_e32 v173, 0xffff0000, v134
	v_and_b32_e32 v207, 0xffff0000, v135
	v_pk_mul_f32 v[164:165], v[164:165], s[60:61]
	v_pk_mul_f32 v[170:171], v[170:171], s[60:61]
	v_pk_mul_f32 v[172:173], v[172:173], s[60:61]
	v_pk_mul_f32 v[206:207], v[206:207], s[60:61]
	v_exp_f32_e32 v164, v164
	v_exp_f32_e32 v170, v170
	v_exp_f32_e32 v172, v172
	v_exp_f32_e32 v206, v206
	v_exp_f32_e32 v165, v165
	v_exp_f32_e32 v171, v171
	v_exp_f32_e32 v173, v173
	v_exp_f32_e32 v207, v207
	v_pk_add_f32 v[164:165], v[164:165], s[78:79]
	v_pk_add_f32 v[170:171], v[170:171], s[78:79]
	v_pk_add_f32 v[172:173], v[172:173], s[78:79]
	v_pk_add_f32 v[206:207], v[206:207], s[78:79]
	v_rcp_f32_e32 v164, v164
	v_rcp_f32_e32 v170, v170
	v_rcp_f32_e32 v172, v172
	v_rcp_f32_e32 v206, v206
	v_rcp_f32_e32 v165, v165
	v_rcp_f32_e32 v171, v171
	v_rcp_f32_e32 v173, v173
	v_rcp_f32_e32 v207, v207
	v_lshlrev_b32_e32 v210, 16, v148
	v_lshlrev_b32_e32 v244, 16, v149
	v_lshlrev_b32_e32 v248, 16, v150
	v_lshlrev_b32_e32 v250, 16, v151
	v_and_b32_e32 v211, 0xffff0000, v148
	v_and_b32_e32 v245, 0xffff0000, v149
	v_and_b32_e32 v249, 0xffff0000, v150
	v_and_b32_e32 v251, 0xffff0000, v151
	v_pk_fma_f32 v[60:61], v[60:61], v[164:165], v[210:211]
	v_pk_fma_f32 v[62:63], v[62:63], v[170:171], v[244:245]
	v_pk_fma_f32 v[56:57], v[56:57], v[172:173], v[248:249]
	v_pk_fma_f32 v[58:59], v[58:59], v[206:207], v[250:251]
	v_cvt_pk_bf16_f32 v60, v60, v61
	v_cvt_pk_bf16_f32 v61, v62, v63
	v_cvt_pk_bf16_f32 v62, v56, v57
	v_cvt_pk_bf16_f32 v63, v58, v59
	global_store_dwordx4 v221, v[60:63], s[98:99]
	s_waitcnt vmcnt(19)
	s_add_u32 s98, s26, 0x40000
	s_addc_u32 s99, s27, 0
	v_lshlrev_b32_e32 v164, 16, v136
	v_lshlrev_b32_e32 v170, 16, v137
	v_lshlrev_b32_e32 v172, 16, v138
	v_lshlrev_b32_e32 v206, 16, v139
	v_and_b32_e32 v165, 0xffff0000, v136
	v_and_b32_e32 v171, 0xffff0000, v137
	v_and_b32_e32 v173, 0xffff0000, v138
	v_and_b32_e32 v207, 0xffff0000, v139
	v_pk_mul_f32 v[164:165], v[164:165], s[60:61]
	v_pk_mul_f32 v[170:171], v[170:171], s[60:61]
	v_pk_mul_f32 v[172:173], v[172:173], s[60:61]
	v_pk_mul_f32 v[206:207], v[206:207], s[60:61]
	v_exp_f32_e32 v164, v164
	v_exp_f32_e32 v170, v170
	v_exp_f32_e32 v172, v172
	v_exp_f32_e32 v206, v206
	v_exp_f32_e32 v165, v165
	v_exp_f32_e32 v171, v171
	v_exp_f32_e32 v173, v173
	v_exp_f32_e32 v207, v207
	v_pk_add_f32 v[164:165], v[164:165], s[78:79]
	v_pk_add_f32 v[170:171], v[170:171], s[78:79]
	v_pk_add_f32 v[172:173], v[172:173], s[78:79]
	v_pk_add_f32 v[206:207], v[206:207], s[78:79]
	v_rcp_f32_e32 v164, v164
	v_rcp_f32_e32 v170, v170
	v_rcp_f32_e32 v172, v172
	v_rcp_f32_e32 v206, v206
	v_rcp_f32_e32 v165, v165
	v_rcp_f32_e32 v171, v171
	v_rcp_f32_e32 v173, v173
	v_rcp_f32_e32 v207, v207
	v_lshlrev_b32_e32 v210, 16, v152
	v_lshlrev_b32_e32 v244, 16, v153
	v_lshlrev_b32_e32 v248, 16, v154
	v_lshlrev_b32_e32 v250, 16, v155
	v_and_b32_e32 v211, 0xffff0000, v152
	v_and_b32_e32 v245, 0xffff0000, v153
	v_and_b32_e32 v249, 0xffff0000, v154
	v_and_b32_e32 v251, 0xffff0000, v155
	v_pk_fma_f32 v[52:53], v[52:53], v[164:165], v[210:211]
	v_pk_fma_f32 v[54:55], v[54:55], v[170:171], v[244:245]
	v_pk_fma_f32 v[48:49], v[48:49], v[172:173], v[248:249]
	v_pk_fma_f32 v[50:51], v[50:51], v[206:207], v[250:251]
	v_cvt_pk_bf16_f32 v52, v52, v53
	v_cvt_pk_bf16_f32 v53, v54, v55
	v_cvt_pk_bf16_f32 v54, v48, v49
	v_cvt_pk_bf16_f32 v55, v50, v51
	global_store_dwordx4 v221, v[52:55], s[98:99] offset:256
	s_waitcnt vmcnt(17)
	s_add_u32 s98, s26, 0x48000
	s_addc_u32 s99, s27, 0
	v_lshlrev_b32_e32 v164, 16, v140
	v_lshlrev_b32_e32 v170, 16, v141
	v_lshlrev_b32_e32 v172, 16, v142
	v_lshlrev_b32_e32 v206, 16, v143
	v_and_b32_e32 v165, 0xffff0000, v140
	v_and_b32_e32 v171, 0xffff0000, v141
	v_and_b32_e32 v173, 0xffff0000, v142
	v_and_b32_e32 v207, 0xffff0000, v143
	v_pk_mul_f32 v[164:165], v[164:165], s[60:61]
	v_pk_mul_f32 v[170:171], v[170:171], s[60:61]
	v_pk_mul_f32 v[172:173], v[172:173], s[60:61]
	v_pk_mul_f32 v[206:207], v[206:207], s[60:61]
	v_exp_f32_e32 v164, v164
	v_exp_f32_e32 v170, v170
	v_exp_f32_e32 v172, v172
	v_exp_f32_e32 v206, v206
	v_exp_f32_e32 v165, v165
	v_exp_f32_e32 v171, v171
	v_exp_f32_e32 v173, v173
	v_exp_f32_e32 v207, v207
	v_pk_add_f32 v[164:165], v[164:165], s[78:79]
	v_pk_add_f32 v[170:171], v[170:171], s[78:79]
	v_pk_add_f32 v[172:173], v[172:173], s[78:79]
	v_pk_add_f32 v[206:207], v[206:207], s[78:79]
	v_rcp_f32_e32 v164, v164
	v_rcp_f32_e32 v170, v170
	v_rcp_f32_e32 v172, v172
	v_rcp_f32_e32 v206, v206
	v_rcp_f32_e32 v165, v165
	v_rcp_f32_e32 v171, v171
	v_rcp_f32_e32 v173, v173
	v_rcp_f32_e32 v207, v207
	v_lshlrev_b32_e32 v210, 16, v156
	v_lshlrev_b32_e32 v244, 16, v157
	v_lshlrev_b32_e32 v248, 16, v158
	v_lshlrev_b32_e32 v250, 16, v159
	v_and_b32_e32 v211, 0xffff0000, v156
	v_and_b32_e32 v245, 0xffff0000, v157
	v_and_b32_e32 v249, 0xffff0000, v158
	v_and_b32_e32 v251, 0xffff0000, v159
	v_pk_fma_f32 v[44:45], v[44:45], v[164:165], v[210:211]
	v_pk_fma_f32 v[46:47], v[46:47], v[170:171], v[244:245]
	v_pk_fma_f32 v[40:41], v[40:41], v[172:173], v[248:249]
	v_pk_fma_f32 v[42:43], v[42:43], v[206:207], v[250:251]
	v_cvt_pk_bf16_f32 v44, v44, v45
	v_cvt_pk_bf16_f32 v45, v46, v47
	v_cvt_pk_bf16_f32 v46, v40, v41
	v_cvt_pk_bf16_f32 v47, v42, v43
	global_store_dwordx4 v221, v[44:47], s[98:99]
	s_waitcnt vmcnt(15)
	s_add_u32 s98, s26, 0x48000
	s_addc_u32 s99, s27, 0
	v_lshlrev_b32_e32 v164, 16, v144
	v_lshlrev_b32_e32 v170, 16, v145
	v_lshlrev_b32_e32 v172, 16, v146
	v_lshlrev_b32_e32 v206, 16, v147
	v_and_b32_e32 v165, 0xffff0000, v144
	v_and_b32_e32 v171, 0xffff0000, v145
	v_and_b32_e32 v173, 0xffff0000, v146
	v_and_b32_e32 v207, 0xffff0000, v147
	v_pk_mul_f32 v[164:165], v[164:165], s[60:61]
	v_pk_mul_f32 v[170:171], v[170:171], s[60:61]
	v_pk_mul_f32 v[172:173], v[172:173], s[60:61]
	v_pk_mul_f32 v[206:207], v[206:207], s[60:61]
	v_exp_f32_e32 v164, v164
	v_exp_f32_e32 v170, v170
	v_exp_f32_e32 v172, v172
	v_exp_f32_e32 v206, v206
	v_exp_f32_e32 v165, v165
	v_exp_f32_e32 v171, v171
	v_exp_f32_e32 v173, v173
	v_exp_f32_e32 v207, v207
	v_pk_add_f32 v[164:165], v[164:165], s[78:79]
	v_pk_add_f32 v[170:171], v[170:171], s[78:79]
	v_pk_add_f32 v[172:173], v[172:173], s[78:79]
	v_pk_add_f32 v[206:207], v[206:207], s[78:79]
	v_rcp_f32_e32 v164, v164
	v_rcp_f32_e32 v170, v170
	v_rcp_f32_e32 v172, v172
	v_rcp_f32_e32 v206, v206
	v_rcp_f32_e32 v165, v165
	v_rcp_f32_e32 v171, v171
	v_rcp_f32_e32 v173, v173
	v_rcp_f32_e32 v207, v207
	v_lshlrev_b32_e32 v210, 16, v160
	v_lshlrev_b32_e32 v244, 16, v161
	v_lshlrev_b32_e32 v248, 16, v162
	v_lshlrev_b32_e32 v250, 16, v163
	v_and_b32_e32 v211, 0xffff0000, v160
	v_and_b32_e32 v245, 0xffff0000, v161
	v_and_b32_e32 v249, 0xffff0000, v162
	v_and_b32_e32 v251, 0xffff0000, v163
	v_pk_fma_f32 v[36:37], v[36:37], v[164:165], v[210:211]
	v_pk_fma_f32 v[38:39], v[38:39], v[170:171], v[244:245]
	v_pk_fma_f32 v[32:33], v[32:33], v[172:173], v[248:249]
	v_pk_fma_f32 v[34:35], v[34:35], v[206:207], v[250:251]
	v_cvt_pk_bf16_f32 v36, v36, v37
	v_cvt_pk_bf16_f32 v37, v38, v39
	v_cvt_pk_bf16_f32 v38, v32, v33
	v_cvt_pk_bf16_f32 v39, v34, v35
	global_store_dwordx4 v221, v[36:39], s[98:99] offset:256
	s_waitcnt vmcnt(13)
	s_add_u32 s98, s26, 0x50000
	s_addc_u32 s99, s27, 0
	v_lshlrev_b32_e32 v164, 16, v224
	v_lshlrev_b32_e32 v170, 16, v225
	v_lshlrev_b32_e32 v172, 16, v226
	v_lshlrev_b32_e32 v206, 16, v227
	v_and_b32_e32 v165, 0xffff0000, v224
	v_and_b32_e32 v171, 0xffff0000, v225
	v_and_b32_e32 v173, 0xffff0000, v226
	v_and_b32_e32 v207, 0xffff0000, v227
	v_pk_mul_f32 v[164:165], v[164:165], s[60:61]
	v_pk_mul_f32 v[170:171], v[170:171], s[60:61]
	v_pk_mul_f32 v[172:173], v[172:173], s[60:61]
	v_pk_mul_f32 v[206:207], v[206:207], s[60:61]
	v_exp_f32_e32 v164, v164
	v_exp_f32_e32 v170, v170
	v_exp_f32_e32 v172, v172
	v_exp_f32_e32 v206, v206
	v_exp_f32_e32 v165, v165
	v_exp_f32_e32 v171, v171
	v_exp_f32_e32 v173, v173
	v_exp_f32_e32 v207, v207
	v_pk_add_f32 v[164:165], v[164:165], s[78:79]
	v_pk_add_f32 v[170:171], v[170:171], s[78:79]
	v_pk_add_f32 v[172:173], v[172:173], s[78:79]
	v_pk_add_f32 v[206:207], v[206:207], s[78:79]
	v_rcp_f32_e32 v164, v164
	v_rcp_f32_e32 v170, v170
	v_rcp_f32_e32 v172, v172
	v_rcp_f32_e32 v206, v206
	v_rcp_f32_e32 v165, v165
	v_rcp_f32_e32 v171, v171
	v_rcp_f32_e32 v173, v173
	v_rcp_f32_e32 v207, v207
	v_lshlrev_b32_e32 v210, 16, v194
	v_lshlrev_b32_e32 v244, 16, v195
	v_lshlrev_b32_e32 v248, 16, v196
	v_lshlrev_b32_e32 v250, 16, v197
	v_and_b32_e32 v211, 0xffff0000, v194
	v_and_b32_e32 v245, 0xffff0000, v195
	v_and_b32_e32 v249, 0xffff0000, v196
	v_and_b32_e32 v251, 0xffff0000, v197
	v_pk_fma_f32 v[28:29], v[28:29], v[164:165], v[210:211]
	v_pk_fma_f32 v[30:31], v[30:31], v[170:171], v[244:245]
	v_pk_fma_f32 v[24:25], v[24:25], v[172:173], v[248:249]
	v_pk_fma_f32 v[26:27], v[26:27], v[206:207], v[250:251]
	v_cvt_pk_bf16_f32 v28, v28, v29
	v_cvt_pk_bf16_f32 v29, v30, v31
	v_cvt_pk_bf16_f32 v30, v24, v25
	v_cvt_pk_bf16_f32 v31, v26, v27
	global_store_dwordx4 v221, v[28:31], s[98:99]
	s_waitcnt vmcnt(11)
	s_add_u32 s98, s26, 0x50000
	s_addc_u32 s99, s27, 0
	v_lshlrev_b32_e32 v164, 16, v228
	v_lshlrev_b32_e32 v170, 16, v229
	v_lshlrev_b32_e32 v172, 16, v230
	v_lshlrev_b32_e32 v206, 16, v231
	v_and_b32_e32 v165, 0xffff0000, v228
	v_and_b32_e32 v171, 0xffff0000, v229
	v_and_b32_e32 v173, 0xffff0000, v230
	v_and_b32_e32 v207, 0xffff0000, v231
	v_pk_mul_f32 v[164:165], v[164:165], s[60:61]
	v_pk_mul_f32 v[170:171], v[170:171], s[60:61]
	v_pk_mul_f32 v[172:173], v[172:173], s[60:61]
	v_pk_mul_f32 v[206:207], v[206:207], s[60:61]
	v_exp_f32_e32 v164, v164
	v_exp_f32_e32 v170, v170
	v_exp_f32_e32 v172, v172
	v_exp_f32_e32 v206, v206
	v_exp_f32_e32 v165, v165
	v_exp_f32_e32 v171, v171
	v_exp_f32_e32 v173, v173
	v_exp_f32_e32 v207, v207
	v_pk_add_f32 v[164:165], v[164:165], s[78:79]
	v_pk_add_f32 v[170:171], v[170:171], s[78:79]
	v_pk_add_f32 v[172:173], v[172:173], s[78:79]
	v_pk_add_f32 v[206:207], v[206:207], s[78:79]
	v_rcp_f32_e32 v164, v164
	v_rcp_f32_e32 v170, v170
	v_rcp_f32_e32 v172, v172
	v_rcp_f32_e32 v206, v206
	v_rcp_f32_e32 v165, v165
	v_rcp_f32_e32 v171, v171
	v_rcp_f32_e32 v173, v173
	v_rcp_f32_e32 v207, v207
	v_lshlrev_b32_e32 v210, 16, v198
	v_lshlrev_b32_e32 v244, 16, v199
	v_lshlrev_b32_e32 v248, 16, v200
	v_lshlrev_b32_e32 v250, 16, v201
	v_and_b32_e32 v211, 0xffff0000, v198
	v_and_b32_e32 v245, 0xffff0000, v199
	v_and_b32_e32 v249, 0xffff0000, v200
	v_and_b32_e32 v251, 0xffff0000, v201
	v_pk_fma_f32 v[20:21], v[20:21], v[164:165], v[210:211]
	v_pk_fma_f32 v[22:23], v[22:23], v[170:171], v[244:245]
	v_pk_fma_f32 v[16:17], v[16:17], v[172:173], v[248:249]
	v_pk_fma_f32 v[18:19], v[18:19], v[206:207], v[250:251]
	v_cvt_pk_bf16_f32 v20, v20, v21
	v_cvt_pk_bf16_f32 v21, v22, v23
	v_cvt_pk_bf16_f32 v22, v16, v17
	v_cvt_pk_bf16_f32 v23, v18, v19
	global_store_dwordx4 v221, v[20:23], s[98:99] offset:256
	s_waitcnt vmcnt(9)
	s_add_u32 s98, s26, 0x58000
	s_addc_u32 s99, s27, 0
	v_lshlrev_b32_e32 v164, 16, v232
	v_lshlrev_b32_e32 v170, 16, v233
	v_lshlrev_b32_e32 v172, 16, v234
	v_lshlrev_b32_e32 v206, 16, v235
	v_and_b32_e32 v165, 0xffff0000, v232
	v_and_b32_e32 v171, 0xffff0000, v233
	v_and_b32_e32 v173, 0xffff0000, v234
	v_and_b32_e32 v207, 0xffff0000, v235
	v_pk_mul_f32 v[164:165], v[164:165], s[60:61]
	v_pk_mul_f32 v[170:171], v[170:171], s[60:61]
	v_pk_mul_f32 v[172:173], v[172:173], s[60:61]
	v_pk_mul_f32 v[206:207], v[206:207], s[60:61]
	v_exp_f32_e32 v164, v164
	v_exp_f32_e32 v170, v170
	v_exp_f32_e32 v172, v172
	v_exp_f32_e32 v206, v206
	v_exp_f32_e32 v165, v165
	v_exp_f32_e32 v171, v171
	v_exp_f32_e32 v173, v173
	v_exp_f32_e32 v207, v207
	v_pk_add_f32 v[164:165], v[164:165], s[78:79]
	v_pk_add_f32 v[170:171], v[170:171], s[78:79]
	v_pk_add_f32 v[172:173], v[172:173], s[78:79]
	v_pk_add_f32 v[206:207], v[206:207], s[78:79]
	v_rcp_f32_e32 v164, v164
	v_rcp_f32_e32 v170, v170
	v_rcp_f32_e32 v172, v172
	v_rcp_f32_e32 v206, v206
	v_rcp_f32_e32 v165, v165
	v_rcp_f32_e32 v171, v171
	v_rcp_f32_e32 v173, v173
	v_rcp_f32_e32 v207, v207
	v_lshlrev_b32_e32 v210, 16, v202
	v_lshlrev_b32_e32 v244, 16, v203
	v_lshlrev_b32_e32 v248, 16, v204
	v_lshlrev_b32_e32 v250, 16, v205
	v_and_b32_e32 v211, 0xffff0000, v202
	v_and_b32_e32 v245, 0xffff0000, v203
	v_and_b32_e32 v249, 0xffff0000, v204
	v_and_b32_e32 v251, 0xffff0000, v205
	v_pk_fma_f32 v[12:13], v[12:13], v[164:165], v[210:211]
	v_pk_fma_f32 v[14:15], v[14:15], v[170:171], v[244:245]
	v_pk_fma_f32 v[8:9], v[8:9], v[172:173], v[248:249]
	v_pk_fma_f32 v[10:11], v[10:11], v[206:207], v[250:251]
	v_cvt_pk_bf16_f32 v12, v12, v13
	v_cvt_pk_bf16_f32 v13, v14, v15
	v_cvt_pk_bf16_f32 v14, v8, v9
	v_cvt_pk_bf16_f32 v15, v10, v11
	global_store_dwordx4 v221, v[12:15], s[98:99]
	s_waitcnt vmcnt(7)
	s_add_u32 s98, s26, 0x58000
	s_addc_u32 s99, s27, 0
	v_lshlrev_b32_e32 v164, 16, v236
	v_lshlrev_b32_e32 v170, 16, v237
	v_lshlrev_b32_e32 v172, 16, v238
	v_lshlrev_b32_e32 v206, 16, v239
	v_and_b32_e32 v165, 0xffff0000, v236
	v_and_b32_e32 v171, 0xffff0000, v237
	v_and_b32_e32 v173, 0xffff0000, v238
	v_and_b32_e32 v207, 0xffff0000, v239
	v_pk_mul_f32 v[164:165], v[164:165], s[60:61]
	v_pk_mul_f32 v[170:171], v[170:171], s[60:61]
	v_pk_mul_f32 v[172:173], v[172:173], s[60:61]
	v_pk_mul_f32 v[206:207], v[206:207], s[60:61]
	v_exp_f32_e32 v164, v164
	v_exp_f32_e32 v170, v170
	v_exp_f32_e32 v172, v172
	v_exp_f32_e32 v206, v206
	v_exp_f32_e32 v165, v165
	v_exp_f32_e32 v171, v171
	v_exp_f32_e32 v173, v173
	v_exp_f32_e32 v207, v207
	v_pk_add_f32 v[164:165], v[164:165], s[78:79]
	v_pk_add_f32 v[170:171], v[170:171], s[78:79]
	v_pk_add_f32 v[172:173], v[172:173], s[78:79]
	v_pk_add_f32 v[206:207], v[206:207], s[78:79]
	v_rcp_f32_e32 v164, v164
	v_rcp_f32_e32 v170, v170
	v_rcp_f32_e32 v172, v172
	v_rcp_f32_e32 v206, v206
	v_rcp_f32_e32 v165, v165
	v_rcp_f32_e32 v171, v171
	v_rcp_f32_e32 v173, v173
	v_rcp_f32_e32 v207, v207
	v_lshlrev_b32_e32 v210, 16, v240
	v_lshlrev_b32_e32 v244, 16, v241
	v_lshlrev_b32_e32 v248, 16, v242
	v_lshlrev_b32_e32 v250, 16, v243
	v_and_b32_e32 v211, 0xffff0000, v240
	v_and_b32_e32 v245, 0xffff0000, v241
	v_and_b32_e32 v249, 0xffff0000, v242
	v_and_b32_e32 v251, 0xffff0000, v243
	v_pk_fma_f32 v[4:5], v[4:5], v[164:165], v[210:211]
	v_pk_fma_f32 v[6:7], v[6:7], v[170:171], v[244:245]
	v_pk_fma_f32 v[0:1], v[0:1], v[172:173], v[248:249]
	v_pk_fma_f32 v[2:3], v[2:3], v[206:207], v[250:251]
	v_cvt_pk_bf16_f32 v4, v4, v5
	v_cvt_pk_bf16_f32 v5, v6, v7
	v_cvt_pk_bf16_f32 v6, v0, v1
	v_cvt_pk_bf16_f32 v7, v2, v3
	global_store_dwordx4 v221, v[4:7], s[98:99] offset:256
	s_branch .Lp6e_done
.Lp6e_nop:
	s_load_dwordx2 s[2:3], s[62:63], 0xc0
	v_lshrrev_b32_e32 v164, 8, v208
	v_and_b32_e32 v165, 15, v208
	v_lshl_add_u32 v164, v164, 6, v165
	v_bfe_u32 v165, v208, 6, 2
	v_bfe_u32 v166, v208, 4, 2
	v_lshlrev_b32_e32 v165, 6, v165
	v_lshl_add_u32 v165, v166, 4, v165
	v_lshl_add_u32 v216, v164, 9, v165
	v_lshl_add_u32 v221, v164, 11, v165
	s_mul_i32 s0, s48, 49
	s_lshl_b32 s19, s46, 2
	s_add_i32 s0, s0, s19
	s_add_i32 s0, s0, s47
	s_add_i32 s0, s0, 29
	s_lshl_b32 s0, s0, 17
	s_lshl_b32 s19, s48, 19
	s_lshl_b32 s32, s47, 9
	s_add_i32 s19, s19, s32
	s_mov_b32 s60, 0xbfb8aa3b
	s_mov_b32 s61, 0xbfb8aa3b
	s_mov_b32 s78, 1.0
	s_mov_b32 s79, 1.0
	s_waitcnt lgkmcnt(0)
	s_add_u32 s24, s2, 0x74c2800
	s_addc_u32 s25, s3, 0
	s_add_u32 s24, s24, s0
	s_addc_u32 s25, s25, 0
	s_add_u32 s26, s2, 0x244c2800
	s_addc_u32 s27, s3, 0
	s_add_u32 s26, s26, s19
	s_addc_u32 s27, s27, 0
	s_add_u32 s8, s24, 0x0
	s_addc_u32 s9, s25, 0
	global_load_dwordx4 v[132:135], v216, s[8:9]
	s_add_u32 s8, s24, 0x0
	s_addc_u32 s9, s25, 0
	global_load_dwordx4 v[136:139], v216, s[8:9] offset:256
	s_add_u32 s8, s24, 0x2000
	s_addc_u32 s9, s25, 0
	global_load_dwordx4 v[140:143], v216, s[8:9]
	s_add_u32 s8, s24, 0x2000
	s_addc_u32 s9, s25, 0
	global_load_dwordx4 v[144:147], v216, s[8:9] offset:256
	s_add_u32 s8, s24, 0x4000
	s_addc_u32 s9, s25, 0
	global_load_dwordx4 v[224:227], v216, s[8:9]
	s_add_u32 s8, s24, 0x4000
	s_addc_u32 s9, s25, 0
	global_load_dwordx4 v[228:231], v216, s[8:9] offset:256
	s_add_u32 s8, s24, 0x6000
	s_addc_u32 s9, s25, 0
	global_load_dwordx4 v[232:235], v216, s[8:9]
	s_add_u32 s8, s24, 0x6000
	s_addc_u32 s9, s25, 0
	global_load_dwordx4 v[236:239], v216, s[8:9] offset:256
	s_waitcnt vmcnt(7)
	s_add_u32 s98, s26, 0x0
	s_addc_u32 s99, s27, 0
	v_lshlrev_b32_e32 v164, 16, v132
	v_lshlrev_b32_e32 v170, 16, v133
	v_lshlrev_b32_e32 v172, 16, v134
	v_lshlrev_b32_e32 v206, 16, v135
	v_and_b32_e32 v165, 0xffff0000, v132
	v_and_b32_e32 v171, 0xffff0000, v133
	v_and_b32_e32 v173, 0xffff0000, v134
	v_and_b32_e32 v207, 0xffff0000, v135
	v_pk_mul_f32 v[164:165], v[164:165], s[60:61]
	v_pk_mul_f32 v[170:171], v[170:171], s[60:61]
	v_pk_mul_f32 v[172:173], v[172:173], s[60:61]
	v_pk_mul_f32 v[206:207], v[206:207], s[60:61]
	v_exp_f32_e32 v164, v164
	v_exp_f32_e32 v170, v170
	v_exp_f32_e32 v172, v172
	v_exp_f32_e32 v206, v206
	v_exp_f32_e32 v165, v165
	v_exp_f32_e32 v171, v171
	v_exp_f32_e32 v173, v173
	v_exp_f32_e32 v207, v207
	v_pk_add_f32 v[164:165], v[164:165], s[78:79]
	v_pk_add_f32 v[170:171], v[170:171], s[78:79]
	v_pk_add_f32 v[172:173], v[172:173], s[78:79]
	v_pk_add_f32 v[206:207], v[206:207], s[78:79]
	v_rcp_f32_e32 v164, v164
	v_rcp_f32_e32 v170, v170
	v_rcp_f32_e32 v172, v172
	v_rcp_f32_e32 v206, v206
	v_rcp_f32_e32 v165, v165
	v_rcp_f32_e32 v171, v171
	v_rcp_f32_e32 v173, v173
	v_rcp_f32_e32 v207, v207
	s_nop 0
	v_pk_mul_f32 v[128:129], v[128:129], v[164:165]
	v_pk_mul_f32 v[130:131], v[130:131], v[170:171]
	v_pk_mul_f32 v[124:125], v[124:125], v[172:173]
	v_pk_mul_f32 v[126:127], v[126:127], v[206:207]
	v_cvt_pk_bf16_f32 v128, v128, v129
	v_cvt_pk_bf16_f32 v129, v130, v131
	v_cvt_pk_bf16_f32 v130, v124, v125
	v_cvt_pk_bf16_f32 v131, v126, v127
	global_store_dwordx4 v221, v[128:131], s[98:99]
	s_add_u32 s8, s24, 0x10000
	s_addc_u32 s9, s25, 0
	global_load_dwordx4 v[132:135], v216, s[8:9]
	s_waitcnt vmcnt(8)
	s_add_u32 s98, s26, 0x0
	s_addc_u32 s99, s27, 0
	v_lshlrev_b32_e32 v164, 16, v136
	v_lshlrev_b32_e32 v170, 16, v137
	v_lshlrev_b32_e32 v172, 16, v138
	v_lshlrev_b32_e32 v206, 16, v139
	v_and_b32_e32 v165, 0xffff0000, v136
	v_and_b32_e32 v171, 0xffff0000, v137
	v_and_b32_e32 v173, 0xffff0000, v138
	v_and_b32_e32 v207, 0xffff0000, v139
	v_pk_mul_f32 v[164:165], v[164:165], s[60:61]
	v_pk_mul_f32 v[170:171], v[170:171], s[60:61]
	v_pk_mul_f32 v[172:173], v[172:173], s[60:61]
	v_pk_mul_f32 v[206:207], v[206:207], s[60:61]
	v_exp_f32_e32 v164, v164
	v_exp_f32_e32 v170, v170
	v_exp_f32_e32 v172, v172
	v_exp_f32_e32 v206, v206
	v_exp_f32_e32 v165, v165
	v_exp_f32_e32 v171, v171
	v_exp_f32_e32 v173, v173
	v_exp_f32_e32 v207, v207
	v_pk_add_f32 v[164:165], v[164:165], s[78:79]
	v_pk_add_f32 v[170:171], v[170:171], s[78:79]
	v_pk_add_f32 v[172:173], v[172:173], s[78:79]
	v_pk_add_f32 v[206:207], v[206:207], s[78:79]
	v_rcp_f32_e32 v164, v164
	v_rcp_f32_e32 v170, v170
	v_rcp_f32_e32 v172, v172
	v_rcp_f32_e32 v206, v206
	v_rcp_f32_e32 v165, v165
	v_rcp_f32_e32 v171, v171
	v_rcp_f32_e32 v173, v173
	v_rcp_f32_e32 v207, v207
	s_nop 0
	v_pk_mul_f32 v[120:121], v[120:121], v[164:165]
	v_pk_mul_f32 v[122:123], v[122:123], v[170:171]
	v_pk_mul_f32 v[116:117], v[116:117], v[172:173]
	v_pk_mul_f32 v[118:119], v[118:119], v[206:207]
	v_cvt_pk_bf16_f32 v120, v120, v121
	v_cvt_pk_bf16_f32 v121, v122, v123
	v_cvt_pk_bf16_f32 v122, v116, v117
	v_cvt_pk_bf16_f32 v123, v118, v119
	global_store_dwordx4 v221, v[120:123], s[98:99] offset:256
	s_add_u32 s8, s24, 0x10000
	s_addc_u32 s9, s25, 0
	global_load_dwordx4 v[136:139], v216, s[8:9] offset:256
	s_waitcnt vmcnt(9)
	s_add_u32 s98, s26, 0x8000
	s_addc_u32 s99, s27, 0
	v_lshlrev_b32_e32 v164, 16, v140
	v_lshlrev_b32_e32 v170, 16, v141
	v_lshlrev_b32_e32 v172, 16, v142
	v_lshlrev_b32_e32 v206, 16, v143
	v_and_b32_e32 v165, 0xffff0000, v140
	v_and_b32_e32 v171, 0xffff0000, v141
	v_and_b32_e32 v173, 0xffff0000, v142
	v_and_b32_e32 v207, 0xffff0000, v143
	v_pk_mul_f32 v[164:165], v[164:165], s[60:61]
	v_pk_mul_f32 v[170:171], v[170:171], s[60:61]
	v_pk_mul_f32 v[172:173], v[172:173], s[60:61]
	v_pk_mul_f32 v[206:207], v[206:207], s[60:61]
	v_exp_f32_e32 v164, v164
	v_exp_f32_e32 v170, v170
	v_exp_f32_e32 v172, v172
	v_exp_f32_e32 v206, v206
	v_exp_f32_e32 v165, v165
	v_exp_f32_e32 v171, v171
	v_exp_f32_e32 v173, v173
	v_exp_f32_e32 v207, v207
	v_pk_add_f32 v[164:165], v[164:165], s[78:79]
	v_pk_add_f32 v[170:171], v[170:171], s[78:79]
	v_pk_add_f32 v[172:173], v[172:173], s[78:79]
	v_pk_add_f32 v[206:207], v[206:207], s[78:79]
	v_rcp_f32_e32 v164, v164
	v_rcp_f32_e32 v170, v170
	v_rcp_f32_e32 v172, v172
	v_rcp_f32_e32 v206, v206
	v_rcp_f32_e32 v165, v165
	v_rcp_f32_e32 v171, v171
	v_rcp_f32_e32 v173, v173
	v_rcp_f32_e32 v207, v207
	s_nop 0
	v_pk_mul_f32 v[112:113], v[112:113], v[164:165]
	v_pk_mul_f32 v[114:115], v[114:115], v[170:171]
	v_pk_mul_f32 v[108:109], v[108:109], v[172:173]
	v_pk_mul_f32 v[110:111], v[110:111], v[206:207]
	v_cvt_pk_bf16_f32 v112, v112, v113
	v_cvt_pk_bf16_f32 v113, v114, v115
	v_cvt_pk_bf16_f32 v114, v108, v109
	v_cvt_pk_bf16_f32 v115, v110, v111
	global_store_dwordx4 v221, v[112:115], s[98:99]
	s_add_u32 s8, s24, 0x12000
	s_addc_u32 s9, s25, 0
	global_load_dwordx4 v[140:143], v216, s[8:9]
	s_waitcnt vmcnt(10)
	s_add_u32 s98, s26, 0x8000
	s_addc_u32 s99, s27, 0
	v_lshlrev_b32_e32 v164, 16, v144
	v_lshlrev_b32_e32 v170, 16, v145
	v_lshlrev_b32_e32 v172, 16, v146
	v_lshlrev_b32_e32 v206, 16, v147
	v_and_b32_e32 v165, 0xffff0000, v144
	v_and_b32_e32 v171, 0xffff0000, v145
	v_and_b32_e32 v173, 0xffff0000, v146
	v_and_b32_e32 v207, 0xffff0000, v147
	v_pk_mul_f32 v[164:165], v[164:165], s[60:61]
	v_pk_mul_f32 v[170:171], v[170:171], s[60:61]
	v_pk_mul_f32 v[172:173], v[172:173], s[60:61]
	v_pk_mul_f32 v[206:207], v[206:207], s[60:61]
	v_exp_f32_e32 v164, v164
	v_exp_f32_e32 v170, v170
	v_exp_f32_e32 v172, v172
	v_exp_f32_e32 v206, v206
	v_exp_f32_e32 v165, v165
	v_exp_f32_e32 v171, v171
	v_exp_f32_e32 v173, v173
	v_exp_f32_e32 v207, v207
	v_pk_add_f32 v[164:165], v[164:165], s[78:79]
	v_pk_add_f32 v[170:171], v[170:171], s[78:79]
	v_pk_add_f32 v[172:173], v[172:173], s[78:79]
	v_pk_add_f32 v[206:207], v[206:207], s[78:79]
	v_rcp_f32_e32 v164, v164
	v_rcp_f32_e32 v170, v170
	v_rcp_f32_e32 v172, v172
	v_rcp_f32_e32 v206, v206
	v_rcp_f32_e32 v165, v165
	v_rcp_f32_e32 v171, v171
	v_rcp_f32_e32 v173, v173
	v_rcp_f32_e32 v207, v207
	s_nop 0
	v_pk_mul_f32 v[104:105], v[104:105], v[164:165]
	v_pk_mul_f32 v[106:107], v[106:107], v[170:171]
	v_pk_mul_f32 v[100:101], v[100:101], v[172:173]
	v_pk_mul_f32 v[102:103], v[102:103], v[206:207]
	v_cvt_pk_bf16_f32 v104, v104, v105
	v_cvt_pk_bf16_f32 v105, v106, v107
	v_cvt_pk_bf16_f32 v106, v100, v101
	v_cvt_pk_bf16_f32 v107, v102, v103
	global_store_dwordx4 v221, v[104:107], s[98:99] offset:256
	s_add_u32 s8, s24, 0x12000
	s_addc_u32 s9, s25, 0
	global_load_dwordx4 v[144:147], v216, s[8:9] offset:256
	s_waitcnt vmcnt(11)
	s_add_u32 s98, s26, 0x10000
	s_addc_u32 s99, s27, 0
	v_lshlrev_b32_e32 v164, 16, v224
	v_lshlrev_b32_e32 v170, 16, v225
	v_lshlrev_b32_e32 v172, 16, v226
	v_lshlrev_b32_e32 v206, 16, v227
	v_and_b32_e32 v165, 0xffff0000, v224
	v_and_b32_e32 v171, 0xffff0000, v225
	v_and_b32_e32 v173, 0xffff0000, v226
	v_and_b32_e32 v207, 0xffff0000, v227
	v_pk_mul_f32 v[164:165], v[164:165], s[60:61]
	v_pk_mul_f32 v[170:171], v[170:171], s[60:61]
	v_pk_mul_f32 v[172:173], v[172:173], s[60:61]
	v_pk_mul_f32 v[206:207], v[206:207], s[60:61]
	v_exp_f32_e32 v164, v164
	v_exp_f32_e32 v170, v170
	v_exp_f32_e32 v172, v172
	v_exp_f32_e32 v206, v206
	v_exp_f32_e32 v165, v165
	v_exp_f32_e32 v171, v171
	v_exp_f32_e32 v173, v173
	v_exp_f32_e32 v207, v207
	v_pk_add_f32 v[164:165], v[164:165], s[78:79]
	v_pk_add_f32 v[170:171], v[170:171], s[78:79]
	v_pk_add_f32 v[172:173], v[172:173], s[78:79]
	v_pk_add_f32 v[206:207], v[206:207], s[78:79]
	v_rcp_f32_e32 v164, v164
	v_rcp_f32_e32 v170, v170
	v_rcp_f32_e32 v172, v172
	v_rcp_f32_e32 v206, v206
	v_rcp_f32_e32 v165, v165
	v_rcp_f32_e32 v171, v171
	v_rcp_f32_e32 v173, v173
	v_rcp_f32_e32 v207, v207
	s_nop 0
	v_pk_mul_f32 v[96:97], v[96:97], v[164:165]
	v_pk_mul_f32 v[98:99], v[98:99], v[170:171]
	v_pk_mul_f32 v[92:93], v[92:93], v[172:173]
	v_pk_mul_f32 v[94:95], v[94:95], v[206:207]
	v_cvt_pk_bf16_f32 v96, v96, v97
	v_cvt_pk_bf16_f32 v97, v98, v99
	v_cvt_pk_bf16_f32 v98, v92, v93
	v_cvt_pk_bf16_f32 v99, v94, v95
	global_store_dwordx4 v221, v[96:99], s[98:99]
	s_add_u32 s8, s24, 0x14000
	s_addc_u32 s9, s25, 0
	global_load_dwordx4 v[224:227], v216, s[8:9]
	s_waitcnt vmcnt(12)
	s_add_u32 s98, s26, 0x10000
	s_addc_u32 s99, s27, 0
	v_lshlrev_b32_e32 v164, 16, v228
	v_lshlrev_b32_e32 v170, 16, v229
	v_lshlrev_b32_e32 v172, 16, v230
	v_lshlrev_b32_e32 v206, 16, v231
	v_and_b32_e32 v165, 0xffff0000, v228
	v_and_b32_e32 v171, 0xffff0000, v229
	v_and_b32_e32 v173, 0xffff0000, v230
	v_and_b32_e32 v207, 0xffff0000, v231
	v_pk_mul_f32 v[164:165], v[164:165], s[60:61]
	v_pk_mul_f32 v[170:171], v[170:171], s[60:61]
	v_pk_mul_f32 v[172:173], v[172:173], s[60:61]
	v_pk_mul_f32 v[206:207], v[206:207], s[60:61]
	v_exp_f32_e32 v164, v164
	v_exp_f32_e32 v170, v170
	v_exp_f32_e32 v172, v172
	v_exp_f32_e32 v206, v206
	v_exp_f32_e32 v165, v165
	v_exp_f32_e32 v171, v171
	v_exp_f32_e32 v173, v173
	v_exp_f32_e32 v207, v207
	v_pk_add_f32 v[164:165], v[164:165], s[78:79]
	v_pk_add_f32 v[170:171], v[170:171], s[78:79]
	v_pk_add_f32 v[172:173], v[172:173], s[78:79]
	v_pk_add_f32 v[206:207], v[206:207], s[78:79]
	v_rcp_f32_e32 v164, v164
	v_rcp_f32_e32 v170, v170
	v_rcp_f32_e32 v172, v172
	v_rcp_f32_e32 v206, v206
	v_rcp_f32_e32 v165, v165
	v_rcp_f32_e32 v171, v171
	v_rcp_f32_e32 v173, v173
	v_rcp_f32_e32 v207, v207
	s_nop 0
	v_pk_mul_f32 v[88:89], v[88:89], v[164:165]
	v_pk_mul_f32 v[90:91], v[90:91], v[170:171]
	v_pk_mul_f32 v[84:85], v[84:85], v[172:173]
	v_pk_mul_f32 v[86:87], v[86:87], v[206:207]
	v_cvt_pk_bf16_f32 v88, v88, v89
	v_cvt_pk_bf16_f32 v89, v90, v91
	v_cvt_pk_bf16_f32 v90, v84, v85
	v_cvt_pk_bf16_f32 v91, v86, v87
	global_store_dwordx4 v221, v[88:91], s[98:99] offset:256
	s_add_u32 s8, s24, 0x14000
	s_addc_u32 s9, s25, 0
	global_load_dwordx4 v[228:231], v216, s[8:9] offset:256
	s_waitcnt vmcnt(13)
	s_add_u32 s98, s26, 0x18000
	s_addc_u32 s99, s27, 0
	v_lshlrev_b32_e32 v164, 16, v232
	v_lshlrev_b32_e32 v170, 16, v233
	v_lshlrev_b32_e32 v172, 16, v234
	v_lshlrev_b32_e32 v206, 16, v235
	v_and_b32_e32 v165, 0xffff0000, v232
	v_and_b32_e32 v171, 0xffff0000, v233
	v_and_b32_e32 v173, 0xffff0000, v234
	v_and_b32_e32 v207, 0xffff0000, v235
	v_pk_mul_f32 v[164:165], v[164:165], s[60:61]
	v_pk_mul_f32 v[170:171], v[170:171], s[60:61]
	v_pk_mul_f32 v[172:173], v[172:173], s[60:61]
	v_pk_mul_f32 v[206:207], v[206:207], s[60:61]
	v_exp_f32_e32 v164, v164
	v_exp_f32_e32 v170, v170
	v_exp_f32_e32 v172, v172
	v_exp_f32_e32 v206, v206
	v_exp_f32_e32 v165, v165
	v_exp_f32_e32 v171, v171
	v_exp_f32_e32 v173, v173
	v_exp_f32_e32 v207, v207
	v_pk_add_f32 v[164:165], v[164:165], s[78:79]
	v_pk_add_f32 v[170:171], v[170:171], s[78:79]
	v_pk_add_f32 v[172:173], v[172:173], s[78:79]
	v_pk_add_f32 v[206:207], v[206:207], s[78:79]
	v_rcp_f32_e32 v164, v164
	v_rcp_f32_e32 v170, v170
	v_rcp_f32_e32 v172, v172
	v_rcp_f32_e32 v206, v206
	v_rcp_f32_e32 v165, v165
	v_rcp_f32_e32 v171, v171
	v_rcp_f32_e32 v173, v173
	v_rcp_f32_e32 v207, v207
	s_nop 0
	v_pk_mul_f32 v[76:77], v[76:77], v[164:165]
	v_pk_mul_f32 v[78:79], v[78:79], v[170:171]
	v_pk_mul_f32 v[72:73], v[72:73], v[172:173]
	v_pk_mul_f32 v[74:75], v[74:75], v[206:207]
	v_cvt_pk_bf16_f32 v76, v76, v77
	v_cvt_pk_bf16_f32 v77, v78, v79
	v_cvt_pk_bf16_f32 v78, v72, v73
	v_cvt_pk_bf16_f32 v79, v74, v75
	global_store_dwordx4 v221, v[76:79], s[98:99]
	s_add_u32 s8, s24, 0x16000
	s_addc_u32 s9, s25, 0
	global_load_dwordx4 v[232:235], v216, s[8:9]
	s_waitcnt vmcnt(14)
	s_add_u32 s98, s26, 0x18000
	s_addc_u32 s99, s27, 0
	v_lshlrev_b32_e32 v164, 16, v236
	v_lshlrev_b32_e32 v170, 16, v237
	v_lshlrev_b32_e32 v172, 16, v238
	v_lshlrev_b32_e32 v206, 16, v239
	v_and_b32_e32 v165, 0xffff0000, v236
	v_and_b32_e32 v171, 0xffff0000, v237
	v_and_b32_e32 v173, 0xffff0000, v238
	v_and_b32_e32 v207, 0xffff0000, v239
	v_pk_mul_f32 v[164:165], v[164:165], s[60:61]
	v_pk_mul_f32 v[170:171], v[170:171], s[60:61]
	v_pk_mul_f32 v[172:173], v[172:173], s[60:61]
	v_pk_mul_f32 v[206:207], v[206:207], s[60:61]
	v_exp_f32_e32 v164, v164
	v_exp_f32_e32 v170, v170
	v_exp_f32_e32 v172, v172
	v_exp_f32_e32 v206, v206
	v_exp_f32_e32 v165, v165
	v_exp_f32_e32 v171, v171
	v_exp_f32_e32 v173, v173
	v_exp_f32_e32 v207, v207
	v_pk_add_f32 v[164:165], v[164:165], s[78:79]
	v_pk_add_f32 v[170:171], v[170:171], s[78:79]
	v_pk_add_f32 v[172:173], v[172:173], s[78:79]
	v_pk_add_f32 v[206:207], v[206:207], s[78:79]
	v_rcp_f32_e32 v164, v164
	v_rcp_f32_e32 v170, v170
	v_rcp_f32_e32 v172, v172
	v_rcp_f32_e32 v206, v206
	v_rcp_f32_e32 v165, v165
	v_rcp_f32_e32 v171, v171
	v_rcp_f32_e32 v173, v173
	v_rcp_f32_e32 v207, v207
	s_nop 0
	v_pk_mul_f32 v[68:69], v[68:69], v[164:165]
	v_pk_mul_f32 v[70:71], v[70:71], v[170:171]
	v_pk_mul_f32 v[64:65], v[64:65], v[172:173]
	v_pk_mul_f32 v[66:67], v[66:67], v[206:207]
	v_cvt_pk_bf16_f32 v68, v68, v69
	v_cvt_pk_bf16_f32 v69, v70, v71
	v_cvt_pk_bf16_f32 v70, v64, v65
	v_cvt_pk_bf16_f32 v71, v66, v67
	global_store_dwordx4 v221, v[68:71], s[98:99] offset:256
	s_add_u32 s8, s24, 0x16000
	s_addc_u32 s9, s25, 0
	global_load_dwordx4 v[236:239], v216, s[8:9] offset:256
	s_waitcnt vmcnt(14)
	s_add_u32 s98, s26, 0x40000
	s_addc_u32 s99, s27, 0
	v_lshlrev_b32_e32 v164, 16, v132
	v_lshlrev_b32_e32 v170, 16, v133
	v_lshlrev_b32_e32 v172, 16, v134
	v_lshlrev_b32_e32 v206, 16, v135
	v_and_b32_e32 v165, 0xffff0000, v132
	v_and_b32_e32 v171, 0xffff0000, v133
	v_and_b32_e32 v173, 0xffff0000, v134
	v_and_b32_e32 v207, 0xffff0000, v135
	v_pk_mul_f32 v[164:165], v[164:165], s[60:61]
	v_pk_mul_f32 v[170:171], v[170:171], s[60:61]
	v_pk_mul_f32 v[172:173], v[172:173], s[60:61]
	v_pk_mul_f32 v[206:207], v[206:207], s[60:61]
	v_exp_f32_e32 v164, v164
	v_exp_f32_e32 v170, v170
	v_exp_f32_e32 v172, v172
	v_exp_f32_e32 v206, v206
	v_exp_f32_e32 v165, v165
	v_exp_f32_e32 v171, v171
	v_exp_f32_e32 v173, v173
	v_exp_f32_e32 v207, v207
	v_pk_add_f32 v[164:165], v[164:165], s[78:79]
	v_pk_add_f32 v[170:171], v[170:171], s[78:79]
	v_pk_add_f32 v[172:173], v[172:173], s[78:79]
	v_pk_add_f32 v[206:207], v[206:207], s[78:79]
	v_rcp_f32_e32 v164, v164
	v_rcp_f32_e32 v170, v170
	v_rcp_f32_e32 v172, v172
	v_rcp_f32_e32 v206, v206
	v_rcp_f32_e32 v165, v165
	v_rcp_f32_e32 v171, v171
	v_rcp_f32_e32 v173, v173
	v_rcp_f32_e32 v207, v207
	s_nop 0
	v_pk_mul_f32 v[60:61], v[60:61], v[164:165]
	v_pk_mul_f32 v[62:63], v[62:63], v[170:171]
	v_pk_mul_f32 v[56:57], v[56:57], v[172:173]
	v_pk_mul_f32 v[58:59], v[58:59], v[206:207]
	v_cvt_pk_bf16_f32 v60, v60, v61
	v_cvt_pk_bf16_f32 v61, v62, v63
	v_cvt_pk_bf16_f32 v62, v56, v57
	v_cvt_pk_bf16_f32 v63, v58, v59
	global_store_dwordx4 v221, v[60:63], s[98:99]
	s_waitcnt vmcnt(13)
	s_add_u32 s98, s26, 0x40000
	s_addc_u32 s99, s27, 0
	v_lshlrev_b32_e32 v164, 16, v136
	v_lshlrev_b32_e32 v170, 16, v137
	v_lshlrev_b32_e32 v172, 16, v138
	v_lshlrev_b32_e32 v206, 16, v139
	v_and_b32_e32 v165, 0xffff0000, v136
	v_and_b32_e32 v171, 0xffff0000, v137
	v_and_b32_e32 v173, 0xffff0000, v138
	v_and_b32_e32 v207, 0xffff0000, v139
	v_pk_mul_f32 v[164:165], v[164:165], s[60:61]
	v_pk_mul_f32 v[170:171], v[170:171], s[60:61]
	v_pk_mul_f32 v[172:173], v[172:173], s[60:61]
	v_pk_mul_f32 v[206:207], v[206:207], s[60:61]
	v_exp_f32_e32 v164, v164
	v_exp_f32_e32 v170, v170
	v_exp_f32_e32 v172, v172
	v_exp_f32_e32 v206, v206
	v_exp_f32_e32 v165, v165
	v_exp_f32_e32 v171, v171
	v_exp_f32_e32 v173, v173
	v_exp_f32_e32 v207, v207
	v_pk_add_f32 v[164:165], v[164:165], s[78:79]
	v_pk_add_f32 v[170:171], v[170:171], s[78:79]
	v_pk_add_f32 v[172:173], v[172:173], s[78:79]
	v_pk_add_f32 v[206:207], v[206:207], s[78:79]
	v_rcp_f32_e32 v164, v164
	v_rcp_f32_e32 v170, v170
	v_rcp_f32_e32 v172, v172
	v_rcp_f32_e32 v206, v206
	v_rcp_f32_e32 v165, v165
	v_rcp_f32_e32 v171, v171
	v_rcp_f32_e32 v173, v173
	v_rcp_f32_e32 v207, v207
	s_nop 0
	v_pk_mul_f32 v[52:53], v[52:53], v[164:165]
	v_pk_mul_f32 v[54:55], v[54:55], v[170:171]
	v_pk_mul_f32 v[48:49], v[48:49], v[172:173]
	v_pk_mul_f32 v[50:51], v[50:51], v[206:207]
	v_cvt_pk_bf16_f32 v52, v52, v53
	v_cvt_pk_bf16_f32 v53, v54, v55
	v_cvt_pk_bf16_f32 v54, v48, v49
	v_cvt_pk_bf16_f32 v55, v50, v51
	global_store_dwordx4 v221, v[52:55], s[98:99] offset:256
	s_waitcnt vmcnt(12)
	s_add_u32 s98, s26, 0x48000
	s_addc_u32 s99, s27, 0
	v_lshlrev_b32_e32 v164, 16, v140
	v_lshlrev_b32_e32 v170, 16, v141
	v_lshlrev_b32_e32 v172, 16, v142
	v_lshlrev_b32_e32 v206, 16, v143
	v_and_b32_e32 v165, 0xffff0000, v140
	v_and_b32_e32 v171, 0xffff0000, v141
	v_and_b32_e32 v173, 0xffff0000, v142
	v_and_b32_e32 v207, 0xffff0000, v143
	v_pk_mul_f32 v[164:165], v[164:165], s[60:61]
	v_pk_mul_f32 v[170:171], v[170:171], s[60:61]
	v_pk_mul_f32 v[172:173], v[172:173], s[60:61]
	v_pk_mul_f32 v[206:207], v[206:207], s[60:61]
	v_exp_f32_e32 v164, v164
	v_exp_f32_e32 v170, v170
	v_exp_f32_e32 v172, v172
	v_exp_f32_e32 v206, v206
	v_exp_f32_e32 v165, v165
	v_exp_f32_e32 v171, v171
	v_exp_f32_e32 v173, v173
	v_exp_f32_e32 v207, v207
	v_pk_add_f32 v[164:165], v[164:165], s[78:79]
	v_pk_add_f32 v[170:171], v[170:171], s[78:79]
	v_pk_add_f32 v[172:173], v[172:173], s[78:79]
	v_pk_add_f32 v[206:207], v[206:207], s[78:79]
	v_rcp_f32_e32 v164, v164
	v_rcp_f32_e32 v170, v170
	v_rcp_f32_e32 v172, v172
	v_rcp_f32_e32 v206, v206
	v_rcp_f32_e32 v165, v165
	v_rcp_f32_e32 v171, v171
	v_rcp_f32_e32 v173, v173
	v_rcp_f32_e32 v207, v207
	s_nop 0
	v_pk_mul_f32 v[44:45], v[44:45], v[164:165]
	v_pk_mul_f32 v[46:47], v[46:47], v[170:171]
	v_pk_mul_f32 v[40:41], v[40:41], v[172:173]
	v_pk_mul_f32 v[42:43], v[42:43], v[206:207]
	v_cvt_pk_bf16_f32 v44, v44, v45
	v_cvt_pk_bf16_f32 v45, v46, v47
	v_cvt_pk_bf16_f32 v46, v40, v41
	v_cvt_pk_bf16_f32 v47, v42, v43
	global_store_dwordx4 v221, v[44:47], s[98:99]
	s_waitcnt vmcnt(11)
	s_add_u32 s98, s26, 0x48000
	s_addc_u32 s99, s27, 0
	v_lshlrev_b32_e32 v164, 16, v144
	v_lshlrev_b32_e32 v170, 16, v145
	v_lshlrev_b32_e32 v172, 16, v146
	v_lshlrev_b32_e32 v206, 16, v147
	v_and_b32_e32 v165, 0xffff0000, v144
	v_and_b32_e32 v171, 0xffff0000, v145
	v_and_b32_e32 v173, 0xffff0000, v146
	v_and_b32_e32 v207, 0xffff0000, v147
	v_pk_mul_f32 v[164:165], v[164:165], s[60:61]
	v_pk_mul_f32 v[170:171], v[170:171], s[60:61]
	v_pk_mul_f32 v[172:173], v[172:173], s[60:61]
	v_pk_mul_f32 v[206:207], v[206:207], s[60:61]
	v_exp_f32_e32 v164, v164
	v_exp_f32_e32 v170, v170
	v_exp_f32_e32 v172, v172
	v_exp_f32_e32 v206, v206
	v_exp_f32_e32 v165, v165
	v_exp_f32_e32 v171, v171
	v_exp_f32_e32 v173, v173
	v_exp_f32_e32 v207, v207
	v_pk_add_f32 v[164:165], v[164:165], s[78:79]
	v_pk_add_f32 v[170:171], v[170:171], s[78:79]
	v_pk_add_f32 v[172:173], v[172:173], s[78:79]
	v_pk_add_f32 v[206:207], v[206:207], s[78:79]
	v_rcp_f32_e32 v164, v164
	v_rcp_f32_e32 v170, v170
	v_rcp_f32_e32 v172, v172
	v_rcp_f32_e32 v206, v206
	v_rcp_f32_e32 v165, v165
	v_rcp_f32_e32 v171, v171
	v_rcp_f32_e32 v173, v173
	v_rcp_f32_e32 v207, v207
	s_nop 0
	v_pk_mul_f32 v[36:37], v[36:37], v[164:165]
	v_pk_mul_f32 v[38:39], v[38:39], v[170:171]
	v_pk_mul_f32 v[32:33], v[32:33], v[172:173]
	v_pk_mul_f32 v[34:35], v[34:35], v[206:207]
	v_cvt_pk_bf16_f32 v36, v36, v37
	v_cvt_pk_bf16_f32 v37, v38, v39
	v_cvt_pk_bf16_f32 v38, v32, v33
	v_cvt_pk_bf16_f32 v39, v34, v35
	global_store_dwordx4 v221, v[36:39], s[98:99] offset:256
	s_waitcnt vmcnt(10)
	s_add_u32 s98, s26, 0x50000
	s_addc_u32 s99, s27, 0
	v_lshlrev_b32_e32 v164, 16, v224
	v_lshlrev_b32_e32 v170, 16, v225
	v_lshlrev_b32_e32 v172, 16, v226
	v_lshlrev_b32_e32 v206, 16, v227
	v_and_b32_e32 v165, 0xffff0000, v224
	v_and_b32_e32 v171, 0xffff0000, v225
	v_and_b32_e32 v173, 0xffff0000, v226
	v_and_b32_e32 v207, 0xffff0000, v227
	v_pk_mul_f32 v[164:165], v[164:165], s[60:61]
	v_pk_mul_f32 v[170:171], v[170:171], s[60:61]
	v_pk_mul_f32 v[172:173], v[172:173], s[60:61]
	v_pk_mul_f32 v[206:207], v[206:207], s[60:61]
	v_exp_f32_e32 v164, v164
	v_exp_f32_e32 v170, v170
	v_exp_f32_e32 v172, v172
	v_exp_f32_e32 v206, v206
	v_exp_f32_e32 v165, v165
	v_exp_f32_e32 v171, v171
	v_exp_f32_e32 v173, v173
	v_exp_f32_e32 v207, v207
	v_pk_add_f32 v[164:165], v[164:165], s[78:79]
	v_pk_add_f32 v[170:171], v[170:171], s[78:79]
	v_pk_add_f32 v[172:173], v[172:173], s[78:79]
	v_pk_add_f32 v[206:207], v[206:207], s[78:79]
	v_rcp_f32_e32 v164, v164
	v_rcp_f32_e32 v170, v170
	v_rcp_f32_e32 v172, v172
	v_rcp_f32_e32 v206, v206
	v_rcp_f32_e32 v165, v165
	v_rcp_f32_e32 v171, v171
	v_rcp_f32_e32 v173, v173
	v_rcp_f32_e32 v207, v207
	s_nop 0
	v_pk_mul_f32 v[28:29], v[28:29], v[164:165]
	v_pk_mul_f32 v[30:31], v[30:31], v[170:171]
	v_pk_mul_f32 v[24:25], v[24:25], v[172:173]
	v_pk_mul_f32 v[26:27], v[26:27], v[206:207]
	v_cvt_pk_bf16_f32 v28, v28, v29
	v_cvt_pk_bf16_f32 v29, v30, v31
	v_cvt_pk_bf16_f32 v30, v24, v25
	v_cvt_pk_bf16_f32 v31, v26, v27
	global_store_dwordx4 v221, v[28:31], s[98:99]
	s_waitcnt vmcnt(9)
	s_add_u32 s98, s26, 0x50000
	s_addc_u32 s99, s27, 0
	v_lshlrev_b32_e32 v164, 16, v228
	v_lshlrev_b32_e32 v170, 16, v229
	v_lshlrev_b32_e32 v172, 16, v230
	v_lshlrev_b32_e32 v206, 16, v231
	v_and_b32_e32 v165, 0xffff0000, v228
	v_and_b32_e32 v171, 0xffff0000, v229
	v_and_b32_e32 v173, 0xffff0000, v230
	v_and_b32_e32 v207, 0xffff0000, v231
	v_pk_mul_f32 v[164:165], v[164:165], s[60:61]
	v_pk_mul_f32 v[170:171], v[170:171], s[60:61]
	v_pk_mul_f32 v[172:173], v[172:173], s[60:61]
	v_pk_mul_f32 v[206:207], v[206:207], s[60:61]
	v_exp_f32_e32 v164, v164
	v_exp_f32_e32 v170, v170
	v_exp_f32_e32 v172, v172
	v_exp_f32_e32 v206, v206
	v_exp_f32_e32 v165, v165
	v_exp_f32_e32 v171, v171
	v_exp_f32_e32 v173, v173
	v_exp_f32_e32 v207, v207
	v_pk_add_f32 v[164:165], v[164:165], s[78:79]
	v_pk_add_f32 v[170:171], v[170:171], s[78:79]
	v_pk_add_f32 v[172:173], v[172:173], s[78:79]
	v_pk_add_f32 v[206:207], v[206:207], s[78:79]
	v_rcp_f32_e32 v164, v164
	v_rcp_f32_e32 v170, v170
	v_rcp_f32_e32 v172, v172
	v_rcp_f32_e32 v206, v206
	v_rcp_f32_e32 v165, v165
	v_rcp_f32_e32 v171, v171
	v_rcp_f32_e32 v173, v173
	v_rcp_f32_e32 v207, v207
	s_nop 0
	v_pk_mul_f32 v[20:21], v[20:21], v[164:165]
	v_pk_mul_f32 v[22:23], v[22:23], v[170:171]
	v_pk_mul_f32 v[16:17], v[16:17], v[172:173]
	v_pk_mul_f32 v[18:19], v[18:19], v[206:207]
	v_cvt_pk_bf16_f32 v20, v20, v21
	v_cvt_pk_bf16_f32 v21, v22, v23
	v_cvt_pk_bf16_f32 v22, v16, v17
	v_cvt_pk_bf16_f32 v23, v18, v19
	global_store_dwordx4 v221, v[20:23], s[98:99] offset:256
	s_waitcnt vmcnt(8)
	s_add_u32 s98, s26, 0x58000
	s_addc_u32 s99, s27, 0
	v_lshlrev_b32_e32 v164, 16, v232
	v_lshlrev_b32_e32 v170, 16, v233
	v_lshlrev_b32_e32 v172, 16, v234
	v_lshlrev_b32_e32 v206, 16, v235
	v_and_b32_e32 v165, 0xffff0000, v232
	v_and_b32_e32 v171, 0xffff0000, v233
	v_and_b32_e32 v173, 0xffff0000, v234
	v_and_b32_e32 v207, 0xffff0000, v235
	v_pk_mul_f32 v[164:165], v[164:165], s[60:61]
	v_pk_mul_f32 v[170:171], v[170:171], s[60:61]
	v_pk_mul_f32 v[172:173], v[172:173], s[60:61]
	v_pk_mul_f32 v[206:207], v[206:207], s[60:61]
	v_exp_f32_e32 v164, v164
	v_exp_f32_e32 v170, v170
	v_exp_f32_e32 v172, v172
	v_exp_f32_e32 v206, v206
	v_exp_f32_e32 v165, v165
	v_exp_f32_e32 v171, v171
	v_exp_f32_e32 v173, v173
	v_exp_f32_e32 v207, v207
	v_pk_add_f32 v[164:165], v[164:165], s[78:79]
	v_pk_add_f32 v[170:171], v[170:171], s[78:79]
	v_pk_add_f32 v[172:173], v[172:173], s[78:79]
	v_pk_add_f32 v[206:207], v[206:207], s[78:79]
	v_rcp_f32_e32 v164, v164
	v_rcp_f32_e32 v170, v170
	v_rcp_f32_e32 v172, v172
	v_rcp_f32_e32 v206, v206
	v_rcp_f32_e32 v165, v165
	v_rcp_f32_e32 v171, v171
	v_rcp_f32_e32 v173, v173
	v_rcp_f32_e32 v207, v207
	s_nop 0
	v_pk_mul_f32 v[12:13], v[12:13], v[164:165]
	v_pk_mul_f32 v[14:15], v[14:15], v[170:171]
	v_pk_mul_f32 v[8:9], v[8:9], v[172:173]
	v_pk_mul_f32 v[10:11], v[10:11], v[206:207]
	v_cvt_pk_bf16_f32 v12, v12, v13
	v_cvt_pk_bf16_f32 v13, v14, v15
	v_cvt_pk_bf16_f32 v14, v8, v9
	v_cvt_pk_bf16_f32 v15, v10, v11
	global_store_dwordx4 v221, v[12:15], s[98:99]
	s_waitcnt vmcnt(7)
	s_add_u32 s98, s26, 0x58000
	s_addc_u32 s99, s27, 0
	v_lshlrev_b32_e32 v164, 16, v236
	v_lshlrev_b32_e32 v170, 16, v237
	v_lshlrev_b32_e32 v172, 16, v238
	v_lshlrev_b32_e32 v206, 16, v239
	v_and_b32_e32 v165, 0xffff0000, v236
	v_and_b32_e32 v171, 0xffff0000, v237
	v_and_b32_e32 v173, 0xffff0000, v238
	v_and_b32_e32 v207, 0xffff0000, v239
	v_pk_mul_f32 v[164:165], v[164:165], s[60:61]
	v_pk_mul_f32 v[170:171], v[170:171], s[60:61]
	v_pk_mul_f32 v[172:173], v[172:173], s[60:61]
	v_pk_mul_f32 v[206:207], v[206:207], s[60:61]
	v_exp_f32_e32 v164, v164
	v_exp_f32_e32 v170, v170
	v_exp_f32_e32 v172, v172
	v_exp_f32_e32 v206, v206
	v_exp_f32_e32 v165, v165
	v_exp_f32_e32 v171, v171
	v_exp_f32_e32 v173, v173
	v_exp_f32_e32 v207, v207
	v_pk_add_f32 v[164:165], v[164:165], s[78:79]
	v_pk_add_f32 v[170:171], v[170:171], s[78:79]
	v_pk_add_f32 v[172:173], v[172:173], s[78:79]
	v_pk_add_f32 v[206:207], v[206:207], s[78:79]
	v_rcp_f32_e32 v164, v164
	v_rcp_f32_e32 v170, v170
	v_rcp_f32_e32 v172, v172
	v_rcp_f32_e32 v206, v206
	v_rcp_f32_e32 v165, v165
	v_rcp_f32_e32 v171, v171
	v_rcp_f32_e32 v173, v173
	v_rcp_f32_e32 v207, v207
	s_nop 0
	v_pk_mul_f32 v[4:5], v[4:5], v[164:165]
	v_pk_mul_f32 v[6:7], v[6:7], v[170:171]
	v_pk_mul_f32 v[0:1], v[0:1], v[172:173]
	v_pk_mul_f32 v[2:3], v[2:3], v[206:207]
	v_cvt_pk_bf16_f32 v4, v4, v5
	v_cvt_pk_bf16_f32 v5, v6, v7
	v_cvt_pk_bf16_f32 v6, v0, v1
	v_cvt_pk_bf16_f32 v7, v2, v3
	global_store_dwordx4 v221, v[4:7], s[98:99] offset:256
	s_branch .Lp6e_done
	s_lshl_b32 s9, s46, 2
	s_mul_i32 s8, s48, 49
	s_add_i32 s9, s47, s9
	s_add_i32 s8, s9, s8
	s_add_i32 s8, s8, 29
	v_lshl_add_u32 v196, s48, 8, v169
	s_ashr_i32 s9, s8, 31
	s_lshl_b64 s[8:9], s[8:9], 17
	v_lshlrev_b32_e32 v132, 9, v196
	v_lshl_add_u64 v[198:199], v[188:189], 0, s[8:9]
	v_and_b32_e32 v166, 0x19e00, v132
	v_lshl_add_u64 v[134:135], v[198:199], 0, v[166:167]
	global_load_dwordx4 v[158:161], v[134:135], off
	v_lshl_or_b32 v194, s47, 8, v219
	v_ashrrev_i32_e32 v195, 31, v194
	v_ashrrev_i32_e32 v197, 31, v196
	v_lshl_add_u64 v[200:201], v[194:195], 1, v[176:177]
	s_cmp_gt_i32 s46, 0
	v_lshlrev_b64 v[204:205], 11, v[196:197]
	s_cselect_b64 s[24:25], -1, 0
	s_cmp_lt_i32 s46, 1
	v_lshl_add_u64 v[132:133], v[200:201], 0, v[204:205]
	s_cbranch_scc1 .LBB0_1759
	global_load_dwordx4 v[162:165], v[132:133], off
	s_branch .LBB0_1760

.LBB0_1797:
	s_load_dwordx2 s[98:99], s[62:63], 0xc0
	v_lshrrev_b32_e32 v170, 8, v208
	v_and_b32_e32 v171, 15, v208
	v_lshl_add_u32 v170, v170, 6, v171
	v_bfe_u32 v171, v208, 6, 2
	v_bfe_u32 v172, v208, 4, 2
	v_lshlrev_b32_e32 v171, 6, v171
	v_lshl_add_u32 v171, v172, 4, v171
	v_lshl_add_u32 v216, v170, 9, v171
	v_lshl_add_u32 v166, v170, 11, v171
	s_mul_i32 s0, s43, 49
	s_add_i32 s0, s0, s42
	s_add_i32 s0, s0, 45
	s_lshl_b32 s0, s0, 17
	s_lshl_b32 s32, s43, 19
	s_lshl_b32 s46, s42, 9
	s_add_i32 s32, s32, s46
	s_mov_b32 s60, 0xbfb8aa3b
	s_mov_b32 s61, 0xbfb8aa3b
	s_mov_b32 s78, 1.0
	s_mov_b32 s79, 1.0
	s_waitcnt lgkmcnt(0)
	s_add_u32 s18, s98, 0x74c2800
	s_addc_u32 s19, s99, 0
	s_add_u32 s18, s18, s0
	s_addc_u32 s19, s19, 0
	s_add_u32 s20, s98, 0x244c2800
	s_addc_u32 s21, s99, 0
	s_add_u32 s20, s20, s32
	s_addc_u32 s21, s21, 0
	s_add_u32 s48, s98, 0x5300000
	s_addc_u32 s49, s99, 0
	s_add_u32 s48, s48, s32
	s_addc_u32 s49, s49, 0
	s_add_u32 s42, s18, 0x0
	s_addc_u32 s43, s19, 0
	global_load_dwordx4 v[132:135], v216, s[42:43]
	s_add_u32 s42, s20, 0x0
	s_addc_u32 s43, s21, 0
	global_load_dwordx4 v[148:151], v166, s[42:43]
	s_add_u32 s42, s18, 0x0
	s_addc_u32 s43, s19, 0
	global_load_dwordx4 v[136:139], v216, s[42:43] offset:256
	s_add_u32 s42, s20, 0x0
	s_addc_u32 s43, s21, 0
	global_load_dwordx4 v[152:155], v166, s[42:43] offset:256
	s_add_u32 s42, s18, 0x2000
	s_addc_u32 s43, s19, 0
	global_load_dwordx4 v[140:143], v216, s[42:43]
	s_add_u32 s42, s20, 0x8000
	s_addc_u32 s43, s21, 0
	global_load_dwordx4 v[184:187], v166, s[42:43]
	s_add_u32 s42, s18, 0x2000
	s_addc_u32 s43, s19, 0
	global_load_dwordx4 v[144:147], v216, s[42:43] offset:256
	s_add_u32 s42, s20, 0x8000
	s_addc_u32 s43, s21, 0
	global_load_dwordx4 v[188:191], v166, s[42:43] offset:256
	s_add_u32 s42, s18, 0x4000
	s_addc_u32 s43, s19, 0
	global_load_dwordx4 v[224:227], v216, s[42:43]
	s_add_u32 s42, s20, 0x10000
	s_addc_u32 s43, s21, 0
	global_load_dwordx4 v[192:195], v166, s[42:43]
	s_add_u32 s42, s18, 0x4000
	s_addc_u32 s43, s19, 0
	global_load_dwordx4 v[228:231], v216, s[42:43] offset:256
	s_add_u32 s42, s20, 0x10000
	s_addc_u32 s43, s21, 0
	global_load_dwordx4 v[200:203], v166, s[42:43] offset:256
	s_add_u32 s42, s18, 0x6000
	s_addc_u32 s43, s19, 0
	global_load_dwordx4 v[232:235], v216, s[42:43]
	s_add_u32 s42, s20, 0x18000
	s_addc_u32 s43, s21, 0
	global_load_dwordx4 v[204:207], v166, s[42:43]
	s_add_u32 s42, s18, 0x6000
	s_addc_u32 s43, s19, 0
	global_load_dwordx4 v[236:239], v216, s[42:43] offset:256
	s_add_u32 s42, s20, 0x18000
	s_addc_u32 s43, s21, 0
	global_load_dwordx4 v[240:243], v166, s[42:43] offset:256
	s_waitcnt vmcnt(14)
	s_add_u32 s98, s48, 0x0
	s_addc_u32 s99, s49, 0
	v_lshlrev_b32_e32 v170, 16, v132
	v_lshlrev_b32_e32 v172, 16, v133
	v_lshlrev_b32_e32 v210, 16, v134
	v_lshlrev_b32_e32 v218, 16, v135
	v_and_b32_e32 v171, 0xffff0000, v132
	v_and_b32_e32 v173, 0xffff0000, v133
	v_and_b32_e32 v211, 0xffff0000, v134
	v_and_b32_e32 v219, 0xffff0000, v135
	v_pk_mul_f32 v[170:171], v[170:171], s[60:61]
	v_pk_mul_f32 v[172:173], v[172:173], s[60:61]
	v_pk_mul_f32 v[210:211], v[210:211], s[60:61]
	v_pk_mul_f32 v[218:219], v[218:219], s[60:61]
	v_exp_f32_e32 v170, v170
	v_exp_f32_e32 v172, v172
	v_exp_f32_e32 v210, v210
	v_exp_f32_e32 v218, v218
	v_exp_f32_e32 v171, v171
	v_exp_f32_e32 v173, v173
	v_exp_f32_e32 v211, v211
	v_exp_f32_e32 v219, v219
	v_pk_add_f32 v[170:171], v[170:171], s[78:79]
	v_pk_add_f32 v[172:173], v[172:173], s[78:79]
	v_pk_add_f32 v[210:211], v[210:211], s[78:79]
	v_pk_add_f32 v[218:219], v[218:219], s[78:79]
	v_rcp_f32_e32 v170, v170
	v_rcp_f32_e32 v172, v172
	v_rcp_f32_e32 v210, v210
	v_rcp_f32_e32 v218, v218
	v_rcp_f32_e32 v171, v171
	v_rcp_f32_e32 v173, v173
	v_rcp_f32_e32 v211, v211
	v_rcp_f32_e32 v219, v219
	v_lshlrev_b32_e32 v220, 16, v148
	v_lshlrev_b32_e32 v244, 16, v149
	v_lshlrev_b32_e32 v248, 16, v150
	v_lshlrev_b32_e32 v250, 16, v151
	v_and_b32_e32 v221, 0xffff0000, v148
	v_and_b32_e32 v245, 0xffff0000, v149
	v_and_b32_e32 v249, 0xffff0000, v150
	v_and_b32_e32 v251, 0xffff0000, v151
	v_pk_fma_f32 v[128:129], v[128:129], v[170:171], v[220:221]
	v_pk_fma_f32 v[130:131], v[130:131], v[172:173], v[244:245]
	v_pk_fma_f32 v[124:125], v[124:125], v[210:211], v[248:249]
	v_pk_fma_f32 v[126:127], v[126:127], v[218:219], v[250:251]
	v_cvt_pk_bf16_f32 v128, v128, v129
	v_cvt_pk_bf16_f32 v129, v130, v131
	v_cvt_pk_bf16_f32 v130, v124, v125
	v_cvt_pk_bf16_f32 v131, v126, v127
	global_store_dwordx4 v166, v[128:131], s[98:99]
	s_add_u32 s42, s18, 0x10000
	s_addc_u32 s43, s19, 0
	global_load_dwordx4 v[132:135], v216, s[42:43]
	s_add_u32 s42, s20, 0x40000
	s_addc_u32 s43, s21, 0
	global_load_dwordx4 v[148:151], v166, s[42:43]
	s_waitcnt vmcnt(15)
	s_add_u32 s98, s48, 0x0
	s_addc_u32 s99, s49, 0
	v_lshlrev_b32_e32 v170, 16, v136
	v_lshlrev_b32_e32 v172, 16, v137
	v_lshlrev_b32_e32 v210, 16, v138
	v_lshlrev_b32_e32 v218, 16, v139
	v_and_b32_e32 v171, 0xffff0000, v136
	v_and_b32_e32 v173, 0xffff0000, v137
	v_and_b32_e32 v211, 0xffff0000, v138
	v_and_b32_e32 v219, 0xffff0000, v139
	v_pk_mul_f32 v[170:171], v[170:171], s[60:61]
	v_pk_mul_f32 v[172:173], v[172:173], s[60:61]
	v_pk_mul_f32 v[210:211], v[210:211], s[60:61]
	v_pk_mul_f32 v[218:219], v[218:219], s[60:61]
	v_exp_f32_e32 v170, v170
	v_exp_f32_e32 v172, v172
	v_exp_f32_e32 v210, v210
	v_exp_f32_e32 v218, v218
	v_exp_f32_e32 v171, v171
	v_exp_f32_e32 v173, v173
	v_exp_f32_e32 v211, v211
	v_exp_f32_e32 v219, v219
	v_pk_add_f32 v[170:171], v[170:171], s[78:79]
	v_pk_add_f32 v[172:173], v[172:173], s[78:79]
	v_pk_add_f32 v[210:211], v[210:211], s[78:79]
	v_pk_add_f32 v[218:219], v[218:219], s[78:79]
	v_rcp_f32_e32 v170, v170
	v_rcp_f32_e32 v172, v172
	v_rcp_f32_e32 v210, v210
	v_rcp_f32_e32 v218, v218
	v_rcp_f32_e32 v171, v171
	v_rcp_f32_e32 v173, v173
	v_rcp_f32_e32 v211, v211
	v_rcp_f32_e32 v219, v219
	v_lshlrev_b32_e32 v220, 16, v152
	v_lshlrev_b32_e32 v244, 16, v153
	v_lshlrev_b32_e32 v248, 16, v154
	v_lshlrev_b32_e32 v250, 16, v155
	v_and_b32_e32 v221, 0xffff0000, v152
	v_and_b32_e32 v245, 0xffff0000, v153
	v_and_b32_e32 v249, 0xffff0000, v154
	v_and_b32_e32 v251, 0xffff0000, v155
	v_pk_fma_f32 v[120:121], v[120:121], v[170:171], v[220:221]
	v_pk_fma_f32 v[122:123], v[122:123], v[172:173], v[244:245]
	v_pk_fma_f32 v[116:117], v[116:117], v[210:211], v[248:249]
	v_pk_fma_f32 v[118:119], v[118:119], v[218:219], v[250:251]
	v_cvt_pk_bf16_f32 v120, v120, v121
	v_cvt_pk_bf16_f32 v121, v122, v123
	v_cvt_pk_bf16_f32 v122, v116, v117
	v_cvt_pk_bf16_f32 v123, v118, v119
	global_store_dwordx4 v166, v[120:123], s[98:99] offset:256
	s_add_u32 s42, s18, 0x10000
	s_addc_u32 s43, s19, 0
	global_load_dwordx4 v[136:139], v216, s[42:43] offset:256
	s_add_u32 s42, s20, 0x40000
	s_addc_u32 s43, s21, 0
	global_load_dwordx4 v[152:155], v166, s[42:43] offset:256
	s_waitcnt vmcnt(16)
	s_add_u32 s98, s48, 0x8000
	s_addc_u32 s99, s49, 0
	v_lshlrev_b32_e32 v170, 16, v140
	v_lshlrev_b32_e32 v172, 16, v141
	v_lshlrev_b32_e32 v210, 16, v142
	v_lshlrev_b32_e32 v218, 16, v143
	v_and_b32_e32 v171, 0xffff0000, v140
	v_and_b32_e32 v173, 0xffff0000, v141
	v_and_b32_e32 v211, 0xffff0000, v142
	v_and_b32_e32 v219, 0xffff0000, v143
	v_pk_mul_f32 v[170:171], v[170:171], s[60:61]
	v_pk_mul_f32 v[172:173], v[172:173], s[60:61]
	v_pk_mul_f32 v[210:211], v[210:211], s[60:61]
	v_pk_mul_f32 v[218:219], v[218:219], s[60:61]
	v_exp_f32_e32 v170, v170
	v_exp_f32_e32 v172, v172
	v_exp_f32_e32 v210, v210
	v_exp_f32_e32 v218, v218
	v_exp_f32_e32 v171, v171
	v_exp_f32_e32 v173, v173
	v_exp_f32_e32 v211, v211
	v_exp_f32_e32 v219, v219
	v_pk_add_f32 v[170:171], v[170:171], s[78:79]
	v_pk_add_f32 v[172:173], v[172:173], s[78:79]
	v_pk_add_f32 v[210:211], v[210:211], s[78:79]
	v_pk_add_f32 v[218:219], v[218:219], s[78:79]
	v_rcp_f32_e32 v170, v170
	v_rcp_f32_e32 v172, v172
	v_rcp_f32_e32 v210, v210
	v_rcp_f32_e32 v218, v218
	v_rcp_f32_e32 v171, v171
	v_rcp_f32_e32 v173, v173
	v_rcp_f32_e32 v211, v211
	v_rcp_f32_e32 v219, v219
	v_lshlrev_b32_e32 v220, 16, v184
	v_lshlrev_b32_e32 v244, 16, v185
	v_lshlrev_b32_e32 v248, 16, v186
	v_lshlrev_b32_e32 v250, 16, v187
	v_and_b32_e32 v221, 0xffff0000, v184
	v_and_b32_e32 v245, 0xffff0000, v185
	v_and_b32_e32 v249, 0xffff0000, v186
	v_and_b32_e32 v251, 0xffff0000, v187
	v_pk_fma_f32 v[112:113], v[112:113], v[170:171], v[220:221]
	v_pk_fma_f32 v[114:115], v[114:115], v[172:173], v[244:245]
	v_pk_fma_f32 v[108:109], v[108:109], v[210:211], v[248:249]
	v_pk_fma_f32 v[110:111], v[110:111], v[218:219], v[250:251]
	v_cvt_pk_bf16_f32 v112, v112, v113
	v_cvt_pk_bf16_f32 v113, v114, v115
	v_cvt_pk_bf16_f32 v114, v108, v109
	v_cvt_pk_bf16_f32 v115, v110, v111
	global_store_dwordx4 v166, v[112:115], s[98:99]
	s_add_u32 s42, s18, 0x12000
	s_addc_u32 s43, s19, 0
	global_load_dwordx4 v[140:143], v216, s[42:43]
	s_add_u32 s42, s20, 0x48000
	s_addc_u32 s43, s21, 0
	global_load_dwordx4 v[184:187], v166, s[42:43]
	s_waitcnt vmcnt(17)
	s_add_u32 s98, s48, 0x8000
	s_addc_u32 s99, s49, 0
	v_lshlrev_b32_e32 v170, 16, v144
	v_lshlrev_b32_e32 v172, 16, v145
	v_lshlrev_b32_e32 v210, 16, v146
	v_lshlrev_b32_e32 v218, 16, v147
	v_and_b32_e32 v171, 0xffff0000, v144
	v_and_b32_e32 v173, 0xffff0000, v145
	v_and_b32_e32 v211, 0xffff0000, v146
	v_and_b32_e32 v219, 0xffff0000, v147
	v_pk_mul_f32 v[170:171], v[170:171], s[60:61]
	v_pk_mul_f32 v[172:173], v[172:173], s[60:61]
	v_pk_mul_f32 v[210:211], v[210:211], s[60:61]
	v_pk_mul_f32 v[218:219], v[218:219], s[60:61]
	v_exp_f32_e32 v170, v170
	v_exp_f32_e32 v172, v172
	v_exp_f32_e32 v210, v210
	v_exp_f32_e32 v218, v218
	v_exp_f32_e32 v171, v171
	v_exp_f32_e32 v173, v173
	v_exp_f32_e32 v211, v211
	v_exp_f32_e32 v219, v219
	v_pk_add_f32 v[170:171], v[170:171], s[78:79]
	v_pk_add_f32 v[172:173], v[172:173], s[78:79]
	v_pk_add_f32 v[210:211], v[210:211], s[78:79]
	v_pk_add_f32 v[218:219], v[218:219], s[78:79]
	v_rcp_f32_e32 v170, v170
	v_rcp_f32_e32 v172, v172
	v_rcp_f32_e32 v210, v210
	v_rcp_f32_e32 v218, v218
	v_rcp_f32_e32 v171, v171
	v_rcp_f32_e32 v173, v173
	v_rcp_f32_e32 v211, v211
	v_rcp_f32_e32 v219, v219
	v_lshlrev_b32_e32 v220, 16, v188
	v_lshlrev_b32_e32 v244, 16, v189
	v_lshlrev_b32_e32 v248, 16, v190
	v_lshlrev_b32_e32 v250, 16, v191
	v_and_b32_e32 v221, 0xffff0000, v188
	v_and_b32_e32 v245, 0xffff0000, v189
	v_and_b32_e32 v249, 0xffff0000, v190
	v_and_b32_e32 v251, 0xffff0000, v191
	v_pk_fma_f32 v[104:105], v[104:105], v[170:171], v[220:221]
	v_pk_fma_f32 v[106:107], v[106:107], v[172:173], v[244:245]
	v_pk_fma_f32 v[100:101], v[100:101], v[210:211], v[248:249]
	v_pk_fma_f32 v[102:103], v[102:103], v[218:219], v[250:251]
	v_cvt_pk_bf16_f32 v104, v104, v105
	v_cvt_pk_bf16_f32 v105, v106, v107
	v_cvt_pk_bf16_f32 v106, v100, v101
	v_cvt_pk_bf16_f32 v107, v102, v103
	global_store_dwordx4 v166, v[104:107], s[98:99] offset:256
	s_add_u32 s42, s18, 0x12000
	s_addc_u32 s43, s19, 0
	global_load_dwordx4 v[144:147], v216, s[42:43] offset:256
	s_add_u32 s42, s20, 0x48000
	s_addc_u32 s43, s21, 0
	global_load_dwordx4 v[188:191], v166, s[42:43] offset:256
	s_waitcnt vmcnt(18)
	s_add_u32 s98, s48, 0x10000
	s_addc_u32 s99, s49, 0
	v_lshlrev_b32_e32 v170, 16, v224
	v_lshlrev_b32_e32 v172, 16, v225
	v_lshlrev_b32_e32 v210, 16, v226
	v_lshlrev_b32_e32 v218, 16, v227
	v_and_b32_e32 v171, 0xffff0000, v224
	v_and_b32_e32 v173, 0xffff0000, v225
	v_and_b32_e32 v211, 0xffff0000, v226
	v_and_b32_e32 v219, 0xffff0000, v227
	v_pk_mul_f32 v[170:171], v[170:171], s[60:61]
	v_pk_mul_f32 v[172:173], v[172:173], s[60:61]
	v_pk_mul_f32 v[210:211], v[210:211], s[60:61]
	v_pk_mul_f32 v[218:219], v[218:219], s[60:61]
	v_exp_f32_e32 v170, v170
	v_exp_f32_e32 v172, v172
	v_exp_f32_e32 v210, v210
	v_exp_f32_e32 v218, v218
	v_exp_f32_e32 v171, v171
	v_exp_f32_e32 v173, v173
	v_exp_f32_e32 v211, v211
	v_exp_f32_e32 v219, v219
	v_pk_add_f32 v[170:171], v[170:171], s[78:79]
	v_pk_add_f32 v[172:173], v[172:173], s[78:79]
	v_pk_add_f32 v[210:211], v[210:211], s[78:79]
	v_pk_add_f32 v[218:219], v[218:219], s[78:79]
	v_rcp_f32_e32 v170, v170
	v_rcp_f32_e32 v172, v172
	v_rcp_f32_e32 v210, v210
	v_rcp_f32_e32 v218, v218
	v_rcp_f32_e32 v171, v171
	v_rcp_f32_e32 v173, v173
	v_rcp_f32_e32 v211, v211
	v_rcp_f32_e32 v219, v219
	v_lshlrev_b32_e32 v220, 16, v192
	v_lshlrev_b32_e32 v244, 16, v193
	v_lshlrev_b32_e32 v248, 16, v194
	v_lshlrev_b32_e32 v250, 16, v195
	v_and_b32_e32 v221, 0xffff0000, v192
	v_and_b32_e32 v245, 0xffff0000, v193
	v_and_b32_e32 v249, 0xffff0000, v194
	v_and_b32_e32 v251, 0xffff0000, v195
	v_pk_fma_f32 v[96:97], v[96:97], v[170:171], v[220:221]
	v_pk_fma_f32 v[98:99], v[98:99], v[172:173], v[244:245]
	v_pk_fma_f32 v[92:93], v[92:93], v[210:211], v[248:249]
	v_pk_fma_f32 v[94:95], v[94:95], v[218:219], v[250:251]
	v_cvt_pk_bf16_f32 v96, v96, v97
	v_cvt_pk_bf16_f32 v97, v98, v99
	v_cvt_pk_bf16_f32 v98, v92, v93
	v_cvt_pk_bf16_f32 v99, v94, v95
	global_store_dwordx4 v166, v[96:99], s[98:99]
	s_add_u32 s42, s18, 0x14000
	s_addc_u32 s43, s19, 0
	global_load_dwordx4 v[224:227], v216, s[42:43]
	s_add_u32 s42, s20, 0x50000
	s_addc_u32 s43, s21, 0
	global_load_dwordx4 v[192:195], v166, s[42:43]
	s_waitcnt vmcnt(19)
	s_add_u32 s98, s48, 0x10000
	s_addc_u32 s99, s49, 0
	v_lshlrev_b32_e32 v170, 16, v228
	v_lshlrev_b32_e32 v172, 16, v229
	v_lshlrev_b32_e32 v210, 16, v230
	v_lshlrev_b32_e32 v218, 16, v231
	v_and_b32_e32 v171, 0xffff0000, v228
	v_and_b32_e32 v173, 0xffff0000, v229
	v_and_b32_e32 v211, 0xffff0000, v230
	v_and_b32_e32 v219, 0xffff0000, v231
	v_pk_mul_f32 v[170:171], v[170:171], s[60:61]
	v_pk_mul_f32 v[172:173], v[172:173], s[60:61]
	v_pk_mul_f32 v[210:211], v[210:211], s[60:61]
	v_pk_mul_f32 v[218:219], v[218:219], s[60:61]
	v_exp_f32_e32 v170, v170
	v_exp_f32_e32 v172, v172
	v_exp_f32_e32 v210, v210
	v_exp_f32_e32 v218, v218
	v_exp_f32_e32 v171, v171
	v_exp_f32_e32 v173, v173
	v_exp_f32_e32 v211, v211
	v_exp_f32_e32 v219, v219
	v_pk_add_f32 v[170:171], v[170:171], s[78:79]
	v_pk_add_f32 v[172:173], v[172:173], s[78:79]
	v_pk_add_f32 v[210:211], v[210:211], s[78:79]
	v_pk_add_f32 v[218:219], v[218:219], s[78:79]
	v_rcp_f32_e32 v170, v170
	v_rcp_f32_e32 v172, v172
	v_rcp_f32_e32 v210, v210
	v_rcp_f32_e32 v218, v218
	v_rcp_f32_e32 v171, v171
	v_rcp_f32_e32 v173, v173
	v_rcp_f32_e32 v211, v211
	v_rcp_f32_e32 v219, v219
	v_lshlrev_b32_e32 v220, 16, v200
	v_lshlrev_b32_e32 v244, 16, v201
	v_lshlrev_b32_e32 v248, 16, v202
	v_lshlrev_b32_e32 v250, 16, v203
	v_and_b32_e32 v221, 0xffff0000, v200
	v_and_b32_e32 v245, 0xffff0000, v201
	v_and_b32_e32 v249, 0xffff0000, v202
	v_and_b32_e32 v251, 0xffff0000, v203
	v_pk_fma_f32 v[88:89], v[88:89], v[170:171], v[220:221]
	v_pk_fma_f32 v[90:91], v[90:91], v[172:173], v[244:245]
	v_pk_fma_f32 v[84:85], v[84:85], v[210:211], v[248:249]
	v_pk_fma_f32 v[86:87], v[86:87], v[218:219], v[250:251]
	v_cvt_pk_bf16_f32 v88, v88, v89
	v_cvt_pk_bf16_f32 v89, v90, v91
	v_cvt_pk_bf16_f32 v90, v84, v85
	v_cvt_pk_bf16_f32 v91, v86, v87
	global_store_dwordx4 v166, v[88:91], s[98:99] offset:256
	s_add_u32 s42, s18, 0x14000
	s_addc_u32 s43, s19, 0
	global_load_dwordx4 v[228:231], v216, s[42:43] offset:256
	s_add_u32 s42, s20, 0x50000
	s_addc_u32 s43, s21, 0
	global_load_dwordx4 v[200:203], v166, s[42:43] offset:256
	s_waitcnt vmcnt(20)
	s_add_u32 s98, s48, 0x18000
	s_addc_u32 s99, s49, 0
	v_lshlrev_b32_e32 v170, 16, v232
	v_lshlrev_b32_e32 v172, 16, v233
	v_lshlrev_b32_e32 v210, 16, v234
	v_lshlrev_b32_e32 v218, 16, v235
	v_and_b32_e32 v171, 0xffff0000, v232
	v_and_b32_e32 v173, 0xffff0000, v233
	v_and_b32_e32 v211, 0xffff0000, v234
	v_and_b32_e32 v219, 0xffff0000, v235
	v_pk_mul_f32 v[170:171], v[170:171], s[60:61]
	v_pk_mul_f32 v[172:173], v[172:173], s[60:61]
	v_pk_mul_f32 v[210:211], v[210:211], s[60:61]
	v_pk_mul_f32 v[218:219], v[218:219], s[60:61]
	v_exp_f32_e32 v170, v170
	v_exp_f32_e32 v172, v172
	v_exp_f32_e32 v210, v210
	v_exp_f32_e32 v218, v218
	v_exp_f32_e32 v171, v171
	v_exp_f32_e32 v173, v173
	v_exp_f32_e32 v211, v211
	v_exp_f32_e32 v219, v219
	v_pk_add_f32 v[170:171], v[170:171], s[78:79]
	v_pk_add_f32 v[172:173], v[172:173], s[78:79]
	v_pk_add_f32 v[210:211], v[210:211], s[78:79]
	v_pk_add_f32 v[218:219], v[218:219], s[78:79]
	v_rcp_f32_e32 v170, v170
	v_rcp_f32_e32 v172, v172
	v_rcp_f32_e32 v210, v210
	v_rcp_f32_e32 v218, v218
	v_rcp_f32_e32 v171, v171
	v_rcp_f32_e32 v173, v173
	v_rcp_f32_e32 v211, v211
	v_rcp_f32_e32 v219, v219
	v_lshlrev_b32_e32 v220, 16, v204
	v_lshlrev_b32_e32 v244, 16, v205
	v_lshlrev_b32_e32 v248, 16, v206
	v_lshlrev_b32_e32 v250, 16, v207
	v_and_b32_e32 v221, 0xffff0000, v204
	v_and_b32_e32 v245, 0xffff0000, v205
	v_and_b32_e32 v249, 0xffff0000, v206
	v_and_b32_e32 v251, 0xffff0000, v207
	v_pk_fma_f32 v[76:77], v[76:77], v[170:171], v[220:221]
	v_pk_fma_f32 v[78:79], v[78:79], v[172:173], v[244:245]
	v_pk_fma_f32 v[72:73], v[72:73], v[210:211], v[248:249]
	v_pk_fma_f32 v[74:75], v[74:75], v[218:219], v[250:251]
	v_cvt_pk_bf16_f32 v76, v76, v77
	v_cvt_pk_bf16_f32 v77, v78, v79
	v_cvt_pk_bf16_f32 v78, v72, v73
	v_cvt_pk_bf16_f32 v79, v74, v75
	global_store_dwordx4 v166, v[76:79], s[98:99]
	s_add_u32 s42, s18, 0x16000
	s_addc_u32 s43, s19, 0
	global_load_dwordx4 v[232:235], v216, s[42:43]
	s_add_u32 s42, s20, 0x58000
	s_addc_u32 s43, s21, 0
	global_load_dwordx4 v[204:207], v166, s[42:43]
	s_waitcnt vmcnt(21)
	s_add_u32 s98, s48, 0x18000
	s_addc_u32 s99, s49, 0
	v_lshlrev_b32_e32 v170, 16, v236
	v_lshlrev_b32_e32 v172, 16, v237
	v_lshlrev_b32_e32 v210, 16, v238
	v_lshlrev_b32_e32 v218, 16, v239
	v_and_b32_e32 v171, 0xffff0000, v236
	v_and_b32_e32 v173, 0xffff0000, v237
	v_and_b32_e32 v211, 0xffff0000, v238
	v_and_b32_e32 v219, 0xffff0000, v239
	v_pk_mul_f32 v[170:171], v[170:171], s[60:61]
	v_pk_mul_f32 v[172:173], v[172:173], s[60:61]
	v_pk_mul_f32 v[210:211], v[210:211], s[60:61]
	v_pk_mul_f32 v[218:219], v[218:219], s[60:61]
	v_exp_f32_e32 v170, v170
	v_exp_f32_e32 v172, v172
	v_exp_f32_e32 v210, v210
	v_exp_f32_e32 v218, v218
	v_exp_f32_e32 v171, v171
	v_exp_f32_e32 v173, v173
	v_exp_f32_e32 v211, v211
	v_exp_f32_e32 v219, v219
	v_pk_add_f32 v[170:171], v[170:171], s[78:79]
	v_pk_add_f32 v[172:173], v[172:173], s[78:79]
	v_pk_add_f32 v[210:211], v[210:211], s[78:79]
	v_pk_add_f32 v[218:219], v[218:219], s[78:79]
	v_rcp_f32_e32 v170, v170
	v_rcp_f32_e32 v172, v172
	v_rcp_f32_e32 v210, v210
	v_rcp_f32_e32 v218, v218
	v_rcp_f32_e32 v171, v171
	v_rcp_f32_e32 v173, v173
	v_rcp_f32_e32 v211, v211
	v_rcp_f32_e32 v219, v219
	v_lshlrev_b32_e32 v220, 16, v240
	v_lshlrev_b32_e32 v244, 16, v241
	v_lshlrev_b32_e32 v248, 16, v242
	v_lshlrev_b32_e32 v250, 16, v243
	v_and_b32_e32 v221, 0xffff0000, v240
	v_and_b32_e32 v245, 0xffff0000, v241
	v_and_b32_e32 v249, 0xffff0000, v242
	v_and_b32_e32 v251, 0xffff0000, v243
	v_pk_fma_f32 v[68:69], v[68:69], v[170:171], v[220:221]
	v_pk_fma_f32 v[70:71], v[70:71], v[172:173], v[244:245]
	v_pk_fma_f32 v[64:65], v[64:65], v[210:211], v[248:249]
	v_pk_fma_f32 v[66:67], v[66:67], v[218:219], v[250:251]
	v_cvt_pk_bf16_f32 v68, v68, v69
	v_cvt_pk_bf16_f32 v69, v70, v71
	v_cvt_pk_bf16_f32 v70, v64, v65
	v_cvt_pk_bf16_f32 v71, v66, v67
	global_store_dwordx4 v166, v[68:71], s[98:99] offset:256
	s_add_u32 s42, s18, 0x16000
	s_addc_u32 s43, s19, 0
	global_load_dwordx4 v[236:239], v216, s[42:43] offset:256
	s_add_u32 s42, s20, 0x58000
	s_addc_u32 s43, s21, 0
	global_load_dwordx4 v[240:243], v166, s[42:43] offset:256
	s_waitcnt vmcnt(21)
	s_add_u32 s98, s48, 0x40000
	s_addc_u32 s99, s49, 0
	v_lshlrev_b32_e32 v170, 16, v132
	v_lshlrev_b32_e32 v172, 16, v133
	v_lshlrev_b32_e32 v210, 16, v134
	v_lshlrev_b32_e32 v218, 16, v135
	v_and_b32_e32 v171, 0xffff0000, v132
	v_and_b32_e32 v173, 0xffff0000, v133
	v_and_b32_e32 v211, 0xffff0000, v134
	v_and_b32_e32 v219, 0xffff0000, v135
	v_pk_mul_f32 v[170:171], v[170:171], s[60:61]
	v_pk_mul_f32 v[172:173], v[172:173], s[60:61]
	v_pk_mul_f32 v[210:211], v[210:211], s[60:61]
	v_pk_mul_f32 v[218:219], v[218:219], s[60:61]
	v_exp_f32_e32 v170, v170
	v_exp_f32_e32 v172, v172
	v_exp_f32_e32 v210, v210
	v_exp_f32_e32 v218, v218
	v_exp_f32_e32 v171, v171
	v_exp_f32_e32 v173, v173
	v_exp_f32_e32 v211, v211
	v_exp_f32_e32 v219, v219
	v_pk_add_f32 v[170:171], v[170:171], s[78:79]
	v_pk_add_f32 v[172:173], v[172:173], s[78:79]
	v_pk_add_f32 v[210:211], v[210:211], s[78:79]
	v_pk_add_f32 v[218:219], v[218:219], s[78:79]
	v_rcp_f32_e32 v170, v170
	v_rcp_f32_e32 v172, v172
	v_rcp_f32_e32 v210, v210
	v_rcp_f32_e32 v218, v218
	v_rcp_f32_e32 v171, v171
	v_rcp_f32_e32 v173, v173
	v_rcp_f32_e32 v211, v211
	v_rcp_f32_e32 v219, v219
	v_lshlrev_b32_e32 v220, 16, v148
	v_lshlrev_b32_e32 v244, 16, v149
	v_lshlrev_b32_e32 v248, 16, v150
	v_lshlrev_b32_e32 v250, 16, v151
	v_and_b32_e32 v221, 0xffff0000, v148
	v_and_b32_e32 v245, 0xffff0000, v149
	v_and_b32_e32 v249, 0xffff0000, v150
	v_and_b32_e32 v251, 0xffff0000, v151
	v_pk_fma_f32 v[60:61], v[60:61], v[170:171], v[220:221]
	v_pk_fma_f32 v[62:63], v[62:63], v[172:173], v[244:245]
	v_pk_fma_f32 v[56:57], v[56:57], v[210:211], v[248:249]
	v_pk_fma_f32 v[58:59], v[58:59], v[218:219], v[250:251]
	v_cvt_pk_bf16_f32 v60, v60, v61
	v_cvt_pk_bf16_f32 v61, v62, v63
	v_cvt_pk_bf16_f32 v62, v56, v57
	v_cvt_pk_bf16_f32 v63, v58, v59
	global_store_dwordx4 v166, v[60:63], s[98:99]
	s_waitcnt vmcnt(19)
	s_add_u32 s98, s48, 0x40000
	s_addc_u32 s99, s49, 0
	v_lshlrev_b32_e32 v170, 16, v136
	v_lshlrev_b32_e32 v172, 16, v137
	v_lshlrev_b32_e32 v210, 16, v138
	v_lshlrev_b32_e32 v218, 16, v139
	v_and_b32_e32 v171, 0xffff0000, v136
	v_and_b32_e32 v173, 0xffff0000, v137
	v_and_b32_e32 v211, 0xffff0000, v138
	v_and_b32_e32 v219, 0xffff0000, v139
	v_pk_mul_f32 v[170:171], v[170:171], s[60:61]
	v_pk_mul_f32 v[172:173], v[172:173], s[60:61]
	v_pk_mul_f32 v[210:211], v[210:211], s[60:61]
	v_pk_mul_f32 v[218:219], v[218:219], s[60:61]
	v_exp_f32_e32 v170, v170
	v_exp_f32_e32 v172, v172
	v_exp_f32_e32 v210, v210
	v_exp_f32_e32 v218, v218
	v_exp_f32_e32 v171, v171
	v_exp_f32_e32 v173, v173
	v_exp_f32_e32 v211, v211
	v_exp_f32_e32 v219, v219
	v_pk_add_f32 v[170:171], v[170:171], s[78:79]
	v_pk_add_f32 v[172:173], v[172:173], s[78:79]
	v_pk_add_f32 v[210:211], v[210:211], s[78:79]
	v_pk_add_f32 v[218:219], v[218:219], s[78:79]
	v_rcp_f32_e32 v170, v170
	v_rcp_f32_e32 v172, v172
	v_rcp_f32_e32 v210, v210
	v_rcp_f32_e32 v218, v218
	v_rcp_f32_e32 v171, v171
	v_rcp_f32_e32 v173, v173
	v_rcp_f32_e32 v211, v211
	v_rcp_f32_e32 v219, v219
	v_lshlrev_b32_e32 v220, 16, v152
	v_lshlrev_b32_e32 v244, 16, v153
	v_lshlrev_b32_e32 v248, 16, v154
	v_lshlrev_b32_e32 v250, 16, v155
	v_and_b32_e32 v221, 0xffff0000, v152
	v_and_b32_e32 v245, 0xffff0000, v153
	v_and_b32_e32 v249, 0xffff0000, v154
	v_and_b32_e32 v251, 0xffff0000, v155
	v_pk_fma_f32 v[52:53], v[52:53], v[170:171], v[220:221]
	v_pk_fma_f32 v[54:55], v[54:55], v[172:173], v[244:245]
	v_pk_fma_f32 v[48:49], v[48:49], v[210:211], v[248:249]
	v_pk_fma_f32 v[50:51], v[50:51], v[218:219], v[250:251]
	v_cvt_pk_bf16_f32 v52, v52, v53
	v_cvt_pk_bf16_f32 v53, v54, v55
	v_cvt_pk_bf16_f32 v54, v48, v49
	v_cvt_pk_bf16_f32 v55, v50, v51
	global_store_dwordx4 v166, v[52:55], s[98:99] offset:256
	s_waitcnt vmcnt(17)
	s_add_u32 s98, s48, 0x48000
	s_addc_u32 s99, s49, 0
	v_lshlrev_b32_e32 v170, 16, v140
	v_lshlrev_b32_e32 v172, 16, v141
	v_lshlrev_b32_e32 v210, 16, v142
	v_lshlrev_b32_e32 v218, 16, v143
	v_and_b32_e32 v171, 0xffff0000, v140
	v_and_b32_e32 v173, 0xffff0000, v141
	v_and_b32_e32 v211, 0xffff0000, v142
	v_and_b32_e32 v219, 0xffff0000, v143
	v_pk_mul_f32 v[170:171], v[170:171], s[60:61]
	v_pk_mul_f32 v[172:173], v[172:173], s[60:61]
	v_pk_mul_f32 v[210:211], v[210:211], s[60:61]
	v_pk_mul_f32 v[218:219], v[218:219], s[60:61]
	v_exp_f32_e32 v170, v170
	v_exp_f32_e32 v172, v172
	v_exp_f32_e32 v210, v210
	v_exp_f32_e32 v218, v218
	v_exp_f32_e32 v171, v171
	v_exp_f32_e32 v173, v173
	v_exp_f32_e32 v211, v211
	v_exp_f32_e32 v219, v219
	v_pk_add_f32 v[170:171], v[170:171], s[78:79]
	v_pk_add_f32 v[172:173], v[172:173], s[78:79]
	v_pk_add_f32 v[210:211], v[210:211], s[78:79]
	v_pk_add_f32 v[218:219], v[218:219], s[78:79]
	v_rcp_f32_e32 v170, v170
	v_rcp_f32_e32 v172, v172
	v_rcp_f32_e32 v210, v210
	v_rcp_f32_e32 v218, v218
	v_rcp_f32_e32 v171, v171
	v_rcp_f32_e32 v173, v173
	v_rcp_f32_e32 v211, v211
	v_rcp_f32_e32 v219, v219
	v_lshlrev_b32_e32 v220, 16, v184
	v_lshlrev_b32_e32 v244, 16, v185
	v_lshlrev_b32_e32 v248, 16, v186
	v_lshlrev_b32_e32 v250, 16, v187
	v_and_b32_e32 v221, 0xffff0000, v184
	v_and_b32_e32 v245, 0xffff0000, v185
	v_and_b32_e32 v249, 0xffff0000, v186
	v_and_b32_e32 v251, 0xffff0000, v187
	v_pk_fma_f32 v[44:45], v[44:45], v[170:171], v[220:221]
	v_pk_fma_f32 v[46:47], v[46:47], v[172:173], v[244:245]
	v_pk_fma_f32 v[40:41], v[40:41], v[210:211], v[248:249]
	v_pk_fma_f32 v[42:43], v[42:43], v[218:219], v[250:251]
	v_cvt_pk_bf16_f32 v44, v44, v45
	v_cvt_pk_bf16_f32 v45, v46, v47
	v_cvt_pk_bf16_f32 v46, v40, v41
	v_cvt_pk_bf16_f32 v47, v42, v43
	global_store_dwordx4 v166, v[44:47], s[98:99]
	s_waitcnt vmcnt(15)
	s_add_u32 s98, s48, 0x48000
	s_addc_u32 s99, s49, 0
	v_lshlrev_b32_e32 v170, 16, v144
	v_lshlrev_b32_e32 v172, 16, v145
	v_lshlrev_b32_e32 v210, 16, v146
	v_lshlrev_b32_e32 v218, 16, v147
	v_and_b32_e32 v171, 0xffff0000, v144
	v_and_b32_e32 v173, 0xffff0000, v145
	v_and_b32_e32 v211, 0xffff0000, v146
	v_and_b32_e32 v219, 0xffff0000, v147
	v_pk_mul_f32 v[170:171], v[170:171], s[60:61]
	v_pk_mul_f32 v[172:173], v[172:173], s[60:61]
	v_pk_mul_f32 v[210:211], v[210:211], s[60:61]
	v_pk_mul_f32 v[218:219], v[218:219], s[60:61]
	v_exp_f32_e32 v170, v170
	v_exp_f32_e32 v172, v172
	v_exp_f32_e32 v210, v210
	v_exp_f32_e32 v218, v218
	v_exp_f32_e32 v171, v171
	v_exp_f32_e32 v173, v173
	v_exp_f32_e32 v211, v211
	v_exp_f32_e32 v219, v219
	v_pk_add_f32 v[170:171], v[170:171], s[78:79]
	v_pk_add_f32 v[172:173], v[172:173], s[78:79]
	v_pk_add_f32 v[210:211], v[210:211], s[78:79]
	v_pk_add_f32 v[218:219], v[218:219], s[78:79]
	v_rcp_f32_e32 v170, v170
	v_rcp_f32_e32 v172, v172
	v_rcp_f32_e32 v210, v210
	v_rcp_f32_e32 v218, v218
	v_rcp_f32_e32 v171, v171
	v_rcp_f32_e32 v173, v173
	v_rcp_f32_e32 v211, v211
	v_rcp_f32_e32 v219, v219
	v_lshlrev_b32_e32 v220, 16, v188
	v_lshlrev_b32_e32 v244, 16, v189
	v_lshlrev_b32_e32 v248, 16, v190
	v_lshlrev_b32_e32 v250, 16, v191
	v_and_b32_e32 v221, 0xffff0000, v188
	v_and_b32_e32 v245, 0xffff0000, v189
	v_and_b32_e32 v249, 0xffff0000, v190
	v_and_b32_e32 v251, 0xffff0000, v191
	v_pk_fma_f32 v[36:37], v[36:37], v[170:171], v[220:221]
	v_pk_fma_f32 v[38:39], v[38:39], v[172:173], v[244:245]
	v_pk_fma_f32 v[32:33], v[32:33], v[210:211], v[248:249]
	v_pk_fma_f32 v[34:35], v[34:35], v[218:219], v[250:251]
	v_cvt_pk_bf16_f32 v36, v36, v37
	v_cvt_pk_bf16_f32 v37, v38, v39
	v_cvt_pk_bf16_f32 v38, v32, v33
	v_cvt_pk_bf16_f32 v39, v34, v35
	global_store_dwordx4 v166, v[36:39], s[98:99] offset:256
	s_waitcnt vmcnt(13)
	s_add_u32 s98, s48, 0x50000
	s_addc_u32 s99, s49, 0
	v_lshlrev_b32_e32 v170, 16, v224
	v_lshlrev_b32_e32 v172, 16, v225
	v_lshlrev_b32_e32 v210, 16, v226
	v_lshlrev_b32_e32 v218, 16, v227
	v_and_b32_e32 v171, 0xffff0000, v224
	v_and_b32_e32 v173, 0xffff0000, v225
	v_and_b32_e32 v211, 0xffff0000, v226
	v_and_b32_e32 v219, 0xffff0000, v227
	v_pk_mul_f32 v[170:171], v[170:171], s[60:61]
	v_pk_mul_f32 v[172:173], v[172:173], s[60:61]
	v_pk_mul_f32 v[210:211], v[210:211], s[60:61]
	v_pk_mul_f32 v[218:219], v[218:219], s[60:61]
	v_exp_f32_e32 v170, v170
	v_exp_f32_e32 v172, v172
	v_exp_f32_e32 v210, v210
	v_exp_f32_e32 v218, v218
	v_exp_f32_e32 v171, v171
	v_exp_f32_e32 v173, v173
	v_exp_f32_e32 v211, v211
	v_exp_f32_e32 v219, v219
	v_pk_add_f32 v[170:171], v[170:171], s[78:79]
	v_pk_add_f32 v[172:173], v[172:173], s[78:79]
	v_pk_add_f32 v[210:211], v[210:211], s[78:79]
	v_pk_add_f32 v[218:219], v[218:219], s[78:79]
	v_rcp_f32_e32 v170, v170
	v_rcp_f32_e32 v172, v172
	v_rcp_f32_e32 v210, v210
	v_rcp_f32_e32 v218, v218
	v_rcp_f32_e32 v171, v171
	v_rcp_f32_e32 v173, v173
	v_rcp_f32_e32 v211, v211
	v_rcp_f32_e32 v219, v219
	v_lshlrev_b32_e32 v220, 16, v192
	v_lshlrev_b32_e32 v244, 16, v193
	v_lshlrev_b32_e32 v248, 16, v194
	v_lshlrev_b32_e32 v250, 16, v195
	v_and_b32_e32 v221, 0xffff0000, v192
	v_and_b32_e32 v245, 0xffff0000, v193
	v_and_b32_e32 v249, 0xffff0000, v194
	v_and_b32_e32 v251, 0xffff0000, v195
	v_pk_fma_f32 v[28:29], v[28:29], v[170:171], v[220:221]
	v_pk_fma_f32 v[30:31], v[30:31], v[172:173], v[244:245]
	v_pk_fma_f32 v[24:25], v[24:25], v[210:211], v[248:249]
	v_pk_fma_f32 v[26:27], v[26:27], v[218:219], v[250:251]
	v_cvt_pk_bf16_f32 v28, v28, v29
	v_cvt_pk_bf16_f32 v29, v30, v31
	v_cvt_pk_bf16_f32 v30, v24, v25
	v_cvt_pk_bf16_f32 v31, v26, v27
	global_store_dwordx4 v166, v[28:31], s[98:99]
	s_waitcnt vmcnt(11)
	s_add_u32 s98, s48, 0x50000
	s_addc_u32 s99, s49, 0
	v_lshlrev_b32_e32 v170, 16, v228
	v_lshlrev_b32_e32 v172, 16, v229
	v_lshlrev_b32_e32 v210, 16, v230
	v_lshlrev_b32_e32 v218, 16, v231
	v_and_b32_e32 v171, 0xffff0000, v228
	v_and_b32_e32 v173, 0xffff0000, v229
	v_and_b32_e32 v211, 0xffff0000, v230
	v_and_b32_e32 v219, 0xffff0000, v231
	v_pk_mul_f32 v[170:171], v[170:171], s[60:61]
	v_pk_mul_f32 v[172:173], v[172:173], s[60:61]
	v_pk_mul_f32 v[210:211], v[210:211], s[60:61]
	v_pk_mul_f32 v[218:219], v[218:219], s[60:61]
	v_exp_f32_e32 v170, v170
	v_exp_f32_e32 v172, v172
	v_exp_f32_e32 v210, v210
	v_exp_f32_e32 v218, v218
	v_exp_f32_e32 v171, v171
	v_exp_f32_e32 v173, v173
	v_exp_f32_e32 v211, v211
	v_exp_f32_e32 v219, v219
	v_pk_add_f32 v[170:171], v[170:171], s[78:79]
	v_pk_add_f32 v[172:173], v[172:173], s[78:79]
	v_pk_add_f32 v[210:211], v[210:211], s[78:79]
	v_pk_add_f32 v[218:219], v[218:219], s[78:79]
	v_rcp_f32_e32 v170, v170
	v_rcp_f32_e32 v172, v172
	v_rcp_f32_e32 v210, v210
	v_rcp_f32_e32 v218, v218
	v_rcp_f32_e32 v171, v171
	v_rcp_f32_e32 v173, v173
	v_rcp_f32_e32 v211, v211
	v_rcp_f32_e32 v219, v219
	v_lshlrev_b32_e32 v220, 16, v200
	v_lshlrev_b32_e32 v244, 16, v201
	v_lshlrev_b32_e32 v248, 16, v202
	v_lshlrev_b32_e32 v250, 16, v203
	v_and_b32_e32 v221, 0xffff0000, v200
	v_and_b32_e32 v245, 0xffff0000, v201
	v_and_b32_e32 v249, 0xffff0000, v202
	v_and_b32_e32 v251, 0xffff0000, v203
	v_pk_fma_f32 v[20:21], v[20:21], v[170:171], v[220:221]
	v_pk_fma_f32 v[22:23], v[22:23], v[172:173], v[244:245]
	v_pk_fma_f32 v[16:17], v[16:17], v[210:211], v[248:249]
	v_pk_fma_f32 v[18:19], v[18:19], v[218:219], v[250:251]
	v_cvt_pk_bf16_f32 v20, v20, v21
	v_cvt_pk_bf16_f32 v21, v22, v23
	v_cvt_pk_bf16_f32 v22, v16, v17
	v_cvt_pk_bf16_f32 v23, v18, v19
	global_store_dwordx4 v166, v[20:23], s[98:99] offset:256
	s_waitcnt vmcnt(9)
	s_add_u32 s98, s48, 0x58000
	s_addc_u32 s99, s49, 0
	v_lshlrev_b32_e32 v170, 16, v232
	v_lshlrev_b32_e32 v172, 16, v233
	v_lshlrev_b32_e32 v210, 16, v234
	v_lshlrev_b32_e32 v218, 16, v235
	v_and_b32_e32 v171, 0xffff0000, v232
	v_and_b32_e32 v173, 0xffff0000, v233
	v_and_b32_e32 v211, 0xffff0000, v234
	v_and_b32_e32 v219, 0xffff0000, v235
	v_pk_mul_f32 v[170:171], v[170:171], s[60:61]
	v_pk_mul_f32 v[172:173], v[172:173], s[60:61]
	v_pk_mul_f32 v[210:211], v[210:211], s[60:61]
	v_pk_mul_f32 v[218:219], v[218:219], s[60:61]
	v_exp_f32_e32 v170, v170
	v_exp_f32_e32 v172, v172
	v_exp_f32_e32 v210, v210
	v_exp_f32_e32 v218, v218
	v_exp_f32_e32 v171, v171
	v_exp_f32_e32 v173, v173
	v_exp_f32_e32 v211, v211
	v_exp_f32_e32 v219, v219
	v_pk_add_f32 v[170:171], v[170:171], s[78:79]
	v_pk_add_f32 v[172:173], v[172:173], s[78:79]
	v_pk_add_f32 v[210:211], v[210:211], s[78:79]
	v_pk_add_f32 v[218:219], v[218:219], s[78:79]
	v_rcp_f32_e32 v170, v170
	v_rcp_f32_e32 v172, v172
	v_rcp_f32_e32 v210, v210
	v_rcp_f32_e32 v218, v218
	v_rcp_f32_e32 v171, v171
	v_rcp_f32_e32 v173, v173
	v_rcp_f32_e32 v211, v211
	v_rcp_f32_e32 v219, v219
	v_lshlrev_b32_e32 v220, 16, v204
	v_lshlrev_b32_e32 v244, 16, v205
	v_lshlrev_b32_e32 v248, 16, v206
	v_lshlrev_b32_e32 v250, 16, v207
	v_and_b32_e32 v221, 0xffff0000, v204
	v_and_b32_e32 v245, 0xffff0000, v205
	v_and_b32_e32 v249, 0xffff0000, v206
	v_and_b32_e32 v251, 0xffff0000, v207
	v_pk_fma_f32 v[12:13], v[12:13], v[170:171], v[220:221]
	v_pk_fma_f32 v[14:15], v[14:15], v[172:173], v[244:245]
	v_pk_fma_f32 v[8:9], v[8:9], v[210:211], v[248:249]
	v_pk_fma_f32 v[10:11], v[10:11], v[218:219], v[250:251]
	v_cvt_pk_bf16_f32 v12, v12, v13
	v_cvt_pk_bf16_f32 v13, v14, v15
	v_cvt_pk_bf16_f32 v14, v8, v9
	v_cvt_pk_bf16_f32 v15, v10, v11
	global_store_dwordx4 v166, v[12:15], s[98:99]
	s_waitcnt vmcnt(7)
	s_add_u32 s98, s48, 0x58000
	s_addc_u32 s99, s49, 0
	v_lshlrev_b32_e32 v170, 16, v236
	v_lshlrev_b32_e32 v172, 16, v237
	v_lshlrev_b32_e32 v210, 16, v238
	v_lshlrev_b32_e32 v218, 16, v239
	v_and_b32_e32 v171, 0xffff0000, v236
	v_and_b32_e32 v173, 0xffff0000, v237
	v_and_b32_e32 v211, 0xffff0000, v238
	v_and_b32_e32 v219, 0xffff0000, v239
	v_pk_mul_f32 v[170:171], v[170:171], s[60:61]
	v_pk_mul_f32 v[172:173], v[172:173], s[60:61]
	v_pk_mul_f32 v[210:211], v[210:211], s[60:61]
	v_pk_mul_f32 v[218:219], v[218:219], s[60:61]
	v_exp_f32_e32 v170, v170
	v_exp_f32_e32 v172, v172
	v_exp_f32_e32 v210, v210
	v_exp_f32_e32 v218, v218
	v_exp_f32_e32 v171, v171
	v_exp_f32_e32 v173, v173
	v_exp_f32_e32 v211, v211
	v_exp_f32_e32 v219, v219
	v_pk_add_f32 v[170:171], v[170:171], s[78:79]
	v_pk_add_f32 v[172:173], v[172:173], s[78:79]
	v_pk_add_f32 v[210:211], v[210:211], s[78:79]
	v_pk_add_f32 v[218:219], v[218:219], s[78:79]
	v_rcp_f32_e32 v170, v170
	v_rcp_f32_e32 v172, v172
	v_rcp_f32_e32 v210, v210
	v_rcp_f32_e32 v218, v218
	v_rcp_f32_e32 v171, v171
	v_rcp_f32_e32 v173, v173
	v_rcp_f32_e32 v211, v211
	v_rcp_f32_e32 v219, v219
	v_lshlrev_b32_e32 v220, 16, v240
	v_lshlrev_b32_e32 v244, 16, v241
	v_lshlrev_b32_e32 v248, 16, v242
	v_lshlrev_b32_e32 v250, 16, v243
	v_and_b32_e32 v221, 0xffff0000, v240
	v_and_b32_e32 v245, 0xffff0000, v241
	v_and_b32_e32 v249, 0xffff0000, v242
	v_and_b32_e32 v251, 0xffff0000, v243
	v_pk_fma_f32 v[4:5], v[4:5], v[170:171], v[220:221]
	v_pk_fma_f32 v[6:7], v[6:7], v[172:173], v[244:245]
	v_pk_fma_f32 v[0:1], v[0:1], v[210:211], v[248:249]
	v_pk_fma_f32 v[2:3], v[2:3], v[218:219], v[250:251]
	v_cvt_pk_bf16_f32 v4, v4, v5
	v_cvt_pk_bf16_f32 v5, v6, v7
	v_cvt_pk_bf16_f32 v6, v0, v1
	v_cvt_pk_bf16_f32 v7, v2, v3
	global_store_dwordx4 v166, v[4:7], s[98:99] offset:256
	s_branch .Lp6e2_done
	s_mul_i32 s18, s43, 49
	s_add_i32 s18, s42, s18
	v_lshl_or_b32 v132, s42, 8, v197
	s_add_i32 s18, s18, 45
	v_lshl_add_u32 v186, s43, 8, v169
	s_ashr_i32 s19, s18, 31
	v_ashrrev_i32_e32 v133, 31, v132
	s_lshl_b64 s[18:19], s[18:19], 17
	v_lshlrev_b64 v[170:171], 1, v[132:133]
	v_lshlrev_b32_e32 v132, 9, v186
	v_lshl_add_u64 v[188:189], v[178:179], 0, s[18:19]
	v_ashrrev_i32_e32 v187, 31, v186
	v_and_b32_e32 v166, 0x19e00, v132
	v_lshl_add_u64 v[190:191], v[176:177], 0, v[170:171]
	v_lshl_add_u64 v[132:133], v[188:189], 0, v[166:167]
	v_lshlrev_b64 v[172:173], 11, v[186:187]
	v_lshl_add_u64 v[134:135], v[190:191], 0, v[172:173]
	global_load_dwordx4 v[200:203], v[132:133], off
	global_load_dwordx4 v[152:155], v[132:133], off offset:256
	global_load_dwordx4 v[204:207], v[134:135], off
	global_load_dwordx4 v[148:151], v[134:135], off offset:256
	v_or_b32_e32 v132, 16, v186
	v_ashrrev_i32_e32 v133, 31, v132
	v_lshlrev_b32_e32 v134, 9, v132
	v_and_b32_e32 v166, 0x1fe00, v134
	v_lshlrev_b64 v[192:193], 11, v[132:133]
	v_lshl_add_u64 v[134:135], v[188:189], 0, v[166:167]
	v_lshl_add_u64 v[132:133], v[190:191], 0, v[192:193]
	global_load_dwordx4 v[144:147], v[134:135], off
	global_load_dwordx4 v[136:139], v[134:135], off offset:256
	global_load_dwordx4 v[140:143], v[132:133], off
	s_nop 0
	global_load_dwordx4 v[132:135], v[132:133], off offset:256
	v_lshl_add_u64 v[184:185], v[164:165], 0, v[170:171]
	s_waitcnt vmcnt(0)
	v_lshlrev_b32_e32 v166, 16, v200
	v_mul_f32_e32 v166, 0xbfb8aa3b, v166
	v_exp_f32_e32 v166, v166
	v_lshl_add_u64 v[194:195], v[184:185], 0, v[172:173]
	v_lshlrev_b32_e32 v172, 16, v204
	v_and_b32_e32 v173, 0xffff0000, v204
	v_add_f32_e32 v166, 1.0, v166
	v_rcp_f32_e32 v170, v166
	v_and_b32_e32 v166, 0xffff0000, v200
	v_mul_f32_e32 v166, 0xbfb8aa3b, v166
	v_exp_f32_e32 v166, v166
	s_nop 0
	v_add_f32_e32 v166, 1.0, v166
	v_rcp_f32_e32 v171, v166
	v_lshlrev_b32_e32 v166, 16, v201
	v_mul_f32_e32 v166, 0xbfb8aa3b, v166
	v_exp_f32_e32 v166, v166
	v_pk_fma_f32 v[128:129], v[128:129], v[170:171], v[172:173]
	v_lshlrev_b32_e32 v172, 16, v205
	v_and_b32_e32 v173, 0xffff0000, v205
	v_add_f32_e32 v166, 1.0, v166
	v_rcp_f32_e32 v170, v166
	v_and_b32_e32 v166, 0xffff0000, v201
	v_mul_f32_e32 v166, 0xbfb8aa3b, v166
	v_exp_f32_e32 v166, v166
	s_nop 0
	v_add_f32_e32 v166, 1.0, v166
	v_rcp_f32_e32 v171, v166
	v_lshlrev_b32_e32 v166, 16, v202
	v_mul_f32_e32 v166, 0xbfb8aa3b, v166
	v_exp_f32_e32 v166, v166
	v_pk_fma_f32 v[130:131], v[130:131], v[170:171], v[172:173]
	v_lshlrev_b32_e32 v172, 16, v206
	v_and_b32_e32 v173, 0xffff0000, v206
	v_add_f32_e32 v166, 1.0, v166
	v_rcp_f32_e32 v170, v166
	v_and_b32_e32 v166, 0xffff0000, v202
	v_mul_f32_e32 v166, 0xbfb8aa3b, v166
	v_exp_f32_e32 v166, v166
	s_nop 0
	v_add_f32_e32 v166, 1.0, v166
	v_rcp_f32_e32 v171, v166
	s_nop 0
	v_pk_fma_f32 v[170:171], v[124:125], v[170:171], v[172:173]
	v_lshlrev_b32_e32 v124, 16, v203
	v_and_b32_e32 v125, 0xffff0000, v203
	v_mul_f32_e32 v124, 0xbfb8aa3b, v124
	v_mul_f32_e32 v125, 0xbfb8aa3b, v125
	v_exp_f32_e32 v124, v124
	v_exp_f32_e32 v125, v125
	v_lshlrev_b32_e32 v172, 16, v207
	v_and_b32_e32 v173, 0xffff0000, v207
	v_add_f32_e32 v124, 1.0, v124
	v_add_f32_e32 v125, 1.0, v125
	v_rcp_f32_e32 v124, v124
	v_rcp_f32_e32 v125, v125
	s_nop 0
	v_pk_fma_f32 v[172:173], v[126:127], v[124:125], v[172:173]
	v_cvt_pk_bf16_f32 v124, v128, v129
	v_cvt_pk_bf16_f32 v125, v130, v131
	v_cvt_pk_bf16_f32 v126, v170, v171
	v_cvt_pk_bf16_f32 v127, v172, v173
	global_store_dwordx4 v[194:195], v[124:127], off
	s_nop 1
	v_lshlrev_b32_e32 v124, 16, v152
	v_and_b32_e32 v125, 0xffff0000, v152
	v_mul_f32_e32 v124, 0xbfb8aa3b, v124
	v_mul_f32_e32 v125, 0xbfb8aa3b, v125
	v_exp_f32_e32 v124, v124
	v_exp_f32_e32 v125, v125
	v_lshlrev_b32_e32 v126, 16, v148
	v_and_b32_e32 v127, 0xffff0000, v148
	v_add_f32_e32 v124, 1.0, v124
	v_add_f32_e32 v125, 1.0, v125
	v_rcp_f32_e32 v124, v124
	v_rcp_f32_e32 v125, v125
	s_nop 0
	v_pk_fma_f32 v[120:121], v[120:121], v[124:125], v[126:127]
	v_lshlrev_b32_e32 v124, 16, v153
	v_and_b32_e32 v125, 0xffff0000, v153
	v_mul_f32_e32 v124, 0xbfb8aa3b, v124
	v_mul_f32_e32 v125, 0xbfb8aa3b, v125
	v_exp_f32_e32 v124, v124
	v_exp_f32_e32 v125, v125
	v_lshlrev_b32_e32 v126, 16, v149
	v_and_b32_e32 v127, 0xffff0000, v149
	v_add_f32_e32 v124, 1.0, v124
	v_add_f32_e32 v125, 1.0, v125
	v_rcp_f32_e32 v124, v124
	v_rcp_f32_e32 v125, v125
	s_nop 0
	v_pk_fma_f32 v[122:123], v[122:123], v[124:125], v[126:127]
	v_lshlrev_b32_e32 v124, 16, v154
	v_and_b32_e32 v125, 0xffff0000, v154
	v_mul_f32_e32 v124, 0xbfb8aa3b, v124
	v_mul_f32_e32 v125, 0xbfb8aa3b, v125
	v_exp_f32_e32 v124, v124
	v_exp_f32_e32 v125, v125
	v_lshlrev_b32_e32 v126, 16, v150
	v_and_b32_e32 v127, 0xffff0000, v150
	v_add_f32_e32 v124, 1.0, v124
	v_add_f32_e32 v125, 1.0, v125
	v_rcp_f32_e32 v124, v124
	v_rcp_f32_e32 v125, v125
	s_nop 0
	v_pk_fma_f32 v[124:125], v[116:117], v[124:125], v[126:127]
	v_lshlrev_b32_e32 v116, 16, v155
	v_and_b32_e32 v117, 0xffff0000, v155
	v_mul_f32_e32 v116, 0xbfb8aa3b, v116
	v_mul_f32_e32 v117, 0xbfb8aa3b, v117
	v_exp_f32_e32 v116, v116
	v_exp_f32_e32 v117, v117
	v_lshlrev_b32_e32 v126, 16, v151
	v_and_b32_e32 v127, 0xffff0000, v151
	v_add_f32_e32 v116, 1.0, v116
	v_add_f32_e32 v117, 1.0, v117
	v_rcp_f32_e32 v116, v116
	v_rcp_f32_e32 v117, v117
	s_nop 0
	v_pk_fma_f32 v[126:127], v[118:119], v[116:117], v[126:127]
	v_cvt_pk_bf16_f32 v116, v120, v121
	v_cvt_pk_bf16_f32 v117, v122, v123
	v_cvt_pk_bf16_f32 v118, v124, v125
	v_cvt_pk_bf16_f32 v119, v126, v127
	global_store_dwordx4 v[194:195], v[116:119], off offset:256
	v_lshlrev_b32_e32 v120, 16, v140
	v_and_b32_e32 v121, 0xffff0000, v140
	v_lshlrev_b32_e32 v118, 16, v144
	v_and_b32_e32 v119, 0xffff0000, v144
	v_mul_f32_e32 v118, 0xbfb8aa3b, v118
	v_mul_f32_e32 v119, 0xbfb8aa3b, v119
	v_exp_f32_e32 v118, v118
	v_exp_f32_e32 v119, v119
	v_lshl_add_u64 v[116:117], v[184:185], 0, v[192:193]
	v_add_f32_e32 v118, 1.0, v118
	v_add_f32_e32 v119, 1.0, v119
	v_rcp_f32_e32 v118, v118
	v_rcp_f32_e32 v119, v119
	s_nop 0
	v_pk_fma_f32 v[112:113], v[112:113], v[118:119], v[120:121]
	v_lshlrev_b32_e32 v118, 16, v145
	v_and_b32_e32 v119, 0xffff0000, v145
	v_mul_f32_e32 v118, 0xbfb8aa3b, v118
	v_mul_f32_e32 v119, 0xbfb8aa3b, v119
	v_exp_f32_e32 v118, v118
	v_exp_f32_e32 v119, v119
	v_lshlrev_b32_e32 v120, 16, v141
	v_and_b32_e32 v121, 0xffff0000, v141
	v_add_f32_e32 v118, 1.0, v118
	v_add_f32_e32 v119, 1.0, v119
	v_rcp_f32_e32 v118, v118
	v_rcp_f32_e32 v119, v119
	s_nop 0
	v_pk_fma_f32 v[114:115], v[114:115], v[118:119], v[120:121]
	v_lshlrev_b32_e32 v118, 16, v146
	v_and_b32_e32 v119, 0xffff0000, v146
	v_mul_f32_e32 v118, 0xbfb8aa3b, v118
	v_mul_f32_e32 v119, 0xbfb8aa3b, v119
	v_exp_f32_e32 v118, v118
	v_exp_f32_e32 v119, v119
	v_lshlrev_b32_e32 v120, 16, v142
	v_and_b32_e32 v121, 0xffff0000, v142
	v_add_f32_e32 v118, 1.0, v118
	v_add_f32_e32 v119, 1.0, v119
	v_rcp_f32_e32 v118, v118
	v_rcp_f32_e32 v119, v119
	s_nop 0
	v_pk_fma_f32 v[118:119], v[108:109], v[118:119], v[120:121]
	v_lshlrev_b32_e32 v108, 16, v147
	v_and_b32_e32 v109, 0xffff0000, v147
	v_mul_f32_e32 v108, 0xbfb8aa3b, v108
	v_mul_f32_e32 v109, 0xbfb8aa3b, v109
	v_exp_f32_e32 v108, v108
	v_exp_f32_e32 v109, v109
	v_lshlrev_b32_e32 v120, 16, v143
	v_and_b32_e32 v121, 0xffff0000, v143
	v_add_f32_e32 v108, 1.0, v108
	v_add_f32_e32 v109, 1.0, v109
	v_rcp_f32_e32 v108, v108
	v_rcp_f32_e32 v109, v109
	s_nop 0
	v_pk_fma_f32 v[120:121], v[110:111], v[108:109], v[120:121]
	v_cvt_pk_bf16_f32 v108, v112, v113
	v_cvt_pk_bf16_f32 v109, v114, v115
	v_cvt_pk_bf16_f32 v110, v118, v119
	v_cvt_pk_bf16_f32 v111, v120, v121
	global_store_dwordx4 v[116:117], v[108:111], off
	s_nop 1
	v_lshlrev_b32_e32 v108, 16, v136
	v_and_b32_e32 v109, 0xffff0000, v136
	v_mul_f32_e32 v108, 0xbfb8aa3b, v108
	v_mul_f32_e32 v109, 0xbfb8aa3b, v109
	v_exp_f32_e32 v108, v108
	v_exp_f32_e32 v109, v109
	v_lshlrev_b32_e32 v110, 16, v132
	v_and_b32_e32 v111, 0xffff0000, v132
	v_add_f32_e32 v108, 1.0, v108
	v_add_f32_e32 v109, 1.0, v109
	v_rcp_f32_e32 v108, v108
	v_rcp_f32_e32 v109, v109
	s_nop 0
	v_pk_fma_f32 v[104:105], v[104:105], v[108:109], v[110:111]
	v_lshlrev_b32_e32 v108, 16, v137
	v_and_b32_e32 v109, 0xffff0000, v137
	v_mul_f32_e32 v108, 0xbfb8aa3b, v108
	v_mul_f32_e32 v109, 0xbfb8aa3b, v109
	v_exp_f32_e32 v108, v108
	v_exp_f32_e32 v109, v109
	v_lshlrev_b32_e32 v110, 16, v133
	v_and_b32_e32 v111, 0xffff0000, v133
	v_add_f32_e32 v108, 1.0, v108
	v_add_f32_e32 v109, 1.0, v109
	v_rcp_f32_e32 v108, v108
	v_rcp_f32_e32 v109, v109
	s_nop 0
	v_pk_fma_f32 v[106:107], v[106:107], v[108:109], v[110:111]
	v_lshlrev_b32_e32 v108, 16, v138
	v_and_b32_e32 v109, 0xffff0000, v138
	v_mul_f32_e32 v108, 0xbfb8aa3b, v108
	v_mul_f32_e32 v109, 0xbfb8aa3b, v109
	v_exp_f32_e32 v108, v108
	v_exp_f32_e32 v109, v109
	v_lshlrev_b32_e32 v110, 16, v134
	v_and_b32_e32 v111, 0xffff0000, v134
	v_add_f32_e32 v108, 1.0, v108
	v_add_f32_e32 v109, 1.0, v109
	v_rcp_f32_e32 v108, v108
	v_rcp_f32_e32 v109, v109
	s_nop 0
	v_pk_fma_f32 v[108:109], v[100:101], v[108:109], v[110:111]
	v_lshlrev_b32_e32 v100, 16, v139
	v_and_b32_e32 v101, 0xffff0000, v139
	v_mul_f32_e32 v100, 0xbfb8aa3b, v100
	v_mul_f32_e32 v101, 0xbfb8aa3b, v101
	v_exp_f32_e32 v100, v100
	v_exp_f32_e32 v101, v101
	v_lshlrev_b32_e32 v110, 16, v135
	v_and_b32_e32 v111, 0xffff0000, v135
	v_add_f32_e32 v100, 1.0, v100
	v_add_f32_e32 v101, 1.0, v101
	v_rcp_f32_e32 v100, v100
	v_rcp_f32_e32 v101, v101
	s_nop 0
	v_pk_fma_f32 v[110:111], v[102:103], v[100:101], v[110:111]
	v_cvt_pk_bf16_f32 v100, v104, v105
	v_cvt_pk_bf16_f32 v101, v106, v107
	v_cvt_pk_bf16_f32 v102, v108, v109
	v_cvt_pk_bf16_f32 v103, v110, v111
	global_store_dwordx4 v[116:117], v[100:103], off offset:256
	s_nop 1
	v_or_b32_e32 v100, 32, v186
	v_ashrrev_i32_e32 v101, 31, v100
	v_lshlrev_b32_e32 v102, 9, v100
	v_and_b32_e32 v166, 0x1fe00, v102
	v_lshlrev_b64 v[126:127], 11, v[100:101]
	v_lshl_add_u64 v[102:103], v[188:189], 0, v[166:167]
	v_lshl_add_u64 v[100:101], v[190:191], 0, v[126:127]
	global_load_dwordx4 v[128:131], v[102:103], off
	global_load_dwordx4 v[120:123], v[102:103], off offset:256
	global_load_dwordx4 v[132:135], v[100:101], off
	global_load_dwordx4 v[116:119], v[100:101], off offset:256
	v_or_b32_e32 v100, 48, v186
	v_ashrrev_i32_e32 v101, 31, v100
	v_lshlrev_b32_e32 v102, 9, v100
	v_and_b32_e32 v166, 0x1fe00, v102
	v_lshlrev_b64 v[124:125], 11, v[100:101]
	v_lshl_add_u64 v[102:103], v[188:189], 0, v[166:167]
	v_lshl_add_u64 v[100:101], v[190:191], 0, v[124:125]
	global_load_dwordx4 v[112:115], v[102:103], off
	global_load_dwordx4 v[104:107], v[102:103], off offset:256
	global_load_dwordx4 v[108:111], v[100:101], off
	s_nop 0
	global_load_dwordx4 v[100:103], v[100:101], off offset:256
	s_waitcnt vmcnt(0)
	v_lshlrev_b32_e32 v136, 16, v128
	v_and_b32_e32 v128, 0xffff0000, v128
	v_mul_f32_e32 v128, 0xbfb8aa3b, v128
	v_exp_f32_e32 v128, v128
	v_lshlrev_b32_e32 v138, 16, v132
	v_and_b32_e32 v139, 0xffff0000, v132
	v_lshlrev_b32_e32 v132, 16, v133
	v_add_f32_e32 v128, 1.0, v128
	v_rcp_f32_e32 v137, v128
	v_lshlrev_b32_e32 v128, 16, v129
	v_and_b32_e32 v129, 0xffff0000, v129
	v_mul_f32_e32 v128, 0xbfb8aa3b, v128
	v_mul_f32_e32 v129, 0xbfb8aa3b, v129
	v_exp_f32_e32 v128, v128
	v_exp_f32_e32 v129, v129
	v_and_b32_e32 v133, 0xffff0000, v133
	v_mul_f32_e32 v136, 0xbfb8aa3b, v136
	v_add_f32_e32 v128, 1.0, v128
	v_add_f32_e32 v129, 1.0, v129
	v_rcp_f32_e32 v128, v128
	v_rcp_f32_e32 v129, v129
	v_exp_f32_e32 v136, v136
	v_lshl_add_u64 v[126:127], v[184:185], 0, v[126:127]
	v_pk_fma_f32 v[98:99], v[98:99], v[128:129], v[132:133]
	v_lshlrev_b32_e32 v128, 16, v130
	v_and_b32_e32 v129, 0xffff0000, v130
	v_mul_f32_e32 v128, 0xbfb8aa3b, v128
	v_mul_f32_e32 v129, 0xbfb8aa3b, v129
	v_exp_f32_e32 v128, v128
	v_exp_f32_e32 v129, v129
	v_lshlrev_b32_e32 v132, 16, v134
	v_and_b32_e32 v133, 0xffff0000, v134
	v_add_f32_e32 v128, 1.0, v128
	v_add_f32_e32 v129, 1.0, v129
	v_rcp_f32_e32 v128, v128
	v_rcp_f32_e32 v129, v129
	v_add_f32_e32 v136, 1.0, v136
	v_rcp_f32_e32 v136, v136
	v_lshlrev_b32_e32 v130, 16, v135
	v_pk_fma_f32 v[128:129], v[92:93], v[128:129], v[132:133]
	v_lshlrev_b32_e32 v92, 16, v131
	v_and_b32_e32 v93, 0xffff0000, v131
	v_mul_f32_e32 v92, 0xbfb8aa3b, v92
	v_mul_f32_e32 v93, 0xbfb8aa3b, v93
	v_exp_f32_e32 v92, v92
	v_exp_f32_e32 v93, v93
	v_and_b32_e32 v131, 0xffff0000, v135
	v_pk_fma_f32 v[96:97], v[96:97], v[136:137], v[138:139]
	v_add_f32_e32 v92, 1.0, v92
	v_add_f32_e32 v93, 1.0, v93
	v_rcp_f32_e32 v92, v92
	v_rcp_f32_e32 v93, v93
	s_nop 0
	v_pk_fma_f32 v[130:131], v[94:95], v[92:93], v[130:131]
	v_cvt_pk_bf16_f32 v92, v96, v97
	v_cvt_pk_bf16_f32 v93, v98, v99
	v_cvt_pk_bf16_f32 v94, v128, v129
	v_cvt_pk_bf16_f32 v95, v130, v131
	global_store_dwordx4 v[126:127], v[92:95], off
	s_nop 1
	v_lshlrev_b32_e32 v92, 16, v120
	v_and_b32_e32 v93, 0xffff0000, v120
	v_mul_f32_e32 v92, 0xbfb8aa3b, v92
	v_mul_f32_e32 v93, 0xbfb8aa3b, v93
	v_exp_f32_e32 v92, v92
	v_exp_f32_e32 v93, v93
	v_lshlrev_b32_e32 v94, 16, v116
	v_and_b32_e32 v95, 0xffff0000, v116
	v_add_f32_e32 v92, 1.0, v92
	v_add_f32_e32 v93, 1.0, v93
	v_rcp_f32_e32 v92, v92
	v_rcp_f32_e32 v93, v93
	s_nop 0
	v_pk_fma_f32 v[88:89], v[88:89], v[92:93], v[94:95]
	v_lshlrev_b32_e32 v92, 16, v121
	v_and_b32_e32 v93, 0xffff0000, v121
	v_mul_f32_e32 v92, 0xbfb8aa3b, v92
	v_mul_f32_e32 v93, 0xbfb8aa3b, v93
	v_exp_f32_e32 v92, v92
	v_exp_f32_e32 v93, v93
	v_lshlrev_b32_e32 v94, 16, v117
	v_and_b32_e32 v95, 0xffff0000, v117
	v_add_f32_e32 v92, 1.0, v92
	v_add_f32_e32 v93, 1.0, v93
	v_rcp_f32_e32 v92, v92
	v_rcp_f32_e32 v93, v93
	s_nop 0
	v_pk_fma_f32 v[90:91], v[90:91], v[92:93], v[94:95]
	v_lshlrev_b32_e32 v92, 16, v122
	v_and_b32_e32 v93, 0xffff0000, v122
	v_mul_f32_e32 v92, 0xbfb8aa3b, v92
	v_mul_f32_e32 v93, 0xbfb8aa3b, v93
	v_exp_f32_e32 v92, v92
	v_exp_f32_e32 v93, v93
	v_lshlrev_b32_e32 v94, 16, v118
	v_and_b32_e32 v95, 0xffff0000, v118
	v_add_f32_e32 v92, 1.0, v92
	v_add_f32_e32 v93, 1.0, v93
	v_rcp_f32_e32 v92, v92
	v_rcp_f32_e32 v93, v93
	s_nop 0
	v_pk_fma_f32 v[92:93], v[84:85], v[92:93], v[94:95]
	v_lshlrev_b32_e32 v84, 16, v123
	v_and_b32_e32 v85, 0xffff0000, v123
	v_mul_f32_e32 v84, 0xbfb8aa3b, v84
	v_mul_f32_e32 v85, 0xbfb8aa3b, v85
	v_exp_f32_e32 v84, v84
	v_exp_f32_e32 v85, v85
	v_lshlrev_b32_e32 v94, 16, v119
	v_and_b32_e32 v95, 0xffff0000, v119
	v_add_f32_e32 v84, 1.0, v84
	v_add_f32_e32 v85, 1.0, v85
	v_rcp_f32_e32 v84, v84
	v_rcp_f32_e32 v85, v85
	s_nop 0
	v_pk_fma_f32 v[94:95], v[86:87], v[84:85], v[94:95]
	v_cvt_pk_bf16_f32 v84, v88, v89
	v_cvt_pk_bf16_f32 v85, v90, v91
	v_cvt_pk_bf16_f32 v86, v92, v93
	v_cvt_pk_bf16_f32 v87, v94, v95
	global_store_dwordx4 v[126:127], v[84:87], off offset:256
	v_lshlrev_b32_e32 v88, 16, v108
	v_and_b32_e32 v89, 0xffff0000, v108
	v_lshlrev_b32_e32 v86, 16, v112
	v_and_b32_e32 v87, 0xffff0000, v112
	v_mul_f32_e32 v86, 0xbfb8aa3b, v86
	v_mul_f32_e32 v87, 0xbfb8aa3b, v87
	v_exp_f32_e32 v86, v86
	v_exp_f32_e32 v87, v87
	v_lshl_add_u64 v[84:85], v[184:185], 0, v[124:125]
	v_add_f32_e32 v86, 1.0, v86
	v_add_f32_e32 v87, 1.0, v87
	v_rcp_f32_e32 v86, v86
	v_rcp_f32_e32 v87, v87
	s_nop 0
	v_pk_fma_f32 v[76:77], v[76:77], v[86:87], v[88:89]
	v_lshlrev_b32_e32 v86, 16, v113
	v_and_b32_e32 v87, 0xffff0000, v113
	v_mul_f32_e32 v86, 0xbfb8aa3b, v86
	v_mul_f32_e32 v87, 0xbfb8aa3b, v87
	v_exp_f32_e32 v86, v86
	v_exp_f32_e32 v87, v87
	v_lshlrev_b32_e32 v88, 16, v109
	v_and_b32_e32 v89, 0xffff0000, v109
	v_add_f32_e32 v86, 1.0, v86
	v_add_f32_e32 v87, 1.0, v87
	v_rcp_f32_e32 v86, v86
	v_rcp_f32_e32 v87, v87
	s_nop 0
	v_pk_fma_f32 v[78:79], v[78:79], v[86:87], v[88:89]
	v_lshlrev_b32_e32 v86, 16, v114
	v_and_b32_e32 v87, 0xffff0000, v114
	v_mul_f32_e32 v86, 0xbfb8aa3b, v86
	v_mul_f32_e32 v87, 0xbfb8aa3b, v87
	v_exp_f32_e32 v86, v86
	v_exp_f32_e32 v87, v87
	v_lshlrev_b32_e32 v88, 16, v110
	v_and_b32_e32 v89, 0xffff0000, v110
	v_add_f32_e32 v86, 1.0, v86
	v_add_f32_e32 v87, 1.0, v87
	v_rcp_f32_e32 v86, v86
	v_rcp_f32_e32 v87, v87
	s_nop 0
	v_pk_fma_f32 v[86:87], v[72:73], v[86:87], v[88:89]
	v_lshlrev_b32_e32 v72, 16, v115
	v_and_b32_e32 v73, 0xffff0000, v115
	v_mul_f32_e32 v72, 0xbfb8aa3b, v72
	v_mul_f32_e32 v73, 0xbfb8aa3b, v73
	v_exp_f32_e32 v72, v72
	v_exp_f32_e32 v73, v73
	v_lshlrev_b32_e32 v88, 16, v111
	v_and_b32_e32 v89, 0xffff0000, v111
	v_add_f32_e32 v72, 1.0, v72
	v_add_f32_e32 v73, 1.0, v73
	v_rcp_f32_e32 v72, v72
	v_rcp_f32_e32 v73, v73
	s_nop 0
	v_pk_fma_f32 v[88:89], v[74:75], v[72:73], v[88:89]
	v_cvt_pk_bf16_f32 v72, v76, v77
	v_cvt_pk_bf16_f32 v73, v78, v79
	v_cvt_pk_bf16_f32 v74, v86, v87
	v_cvt_pk_bf16_f32 v75, v88, v89
	global_store_dwordx4 v[84:85], v[72:75], off
	s_nop 1
	v_lshlrev_b32_e32 v72, 16, v104
	v_and_b32_e32 v73, 0xffff0000, v104
	v_mul_f32_e32 v72, 0xbfb8aa3b, v72
	v_mul_f32_e32 v73, 0xbfb8aa3b, v73
	v_exp_f32_e32 v72, v72
	v_exp_f32_e32 v73, v73
	v_lshlrev_b32_e32 v74, 16, v100
	v_and_b32_e32 v75, 0xffff0000, v100
	v_add_f32_e32 v72, 1.0, v72
	v_add_f32_e32 v73, 1.0, v73
	v_rcp_f32_e32 v72, v72
	v_rcp_f32_e32 v73, v73
	s_nop 0
	v_pk_fma_f32 v[68:69], v[68:69], v[72:73], v[74:75]
	v_lshlrev_b32_e32 v72, 16, v105
	v_and_b32_e32 v73, 0xffff0000, v105
	v_mul_f32_e32 v72, 0xbfb8aa3b, v72
	v_mul_f32_e32 v73, 0xbfb8aa3b, v73
	v_exp_f32_e32 v72, v72
	v_exp_f32_e32 v73, v73
	v_lshlrev_b32_e32 v74, 16, v101
	v_and_b32_e32 v75, 0xffff0000, v101
	v_add_f32_e32 v72, 1.0, v72
	v_add_f32_e32 v73, 1.0, v73
	v_rcp_f32_e32 v72, v72
	v_rcp_f32_e32 v73, v73
	s_nop 0
	v_pk_fma_f32 v[70:71], v[70:71], v[72:73], v[74:75]
	v_lshlrev_b32_e32 v72, 16, v106
	v_and_b32_e32 v73, 0xffff0000, v106
	v_mul_f32_e32 v72, 0xbfb8aa3b, v72
	v_mul_f32_e32 v73, 0xbfb8aa3b, v73
	v_exp_f32_e32 v72, v72
	v_exp_f32_e32 v73, v73
	v_lshlrev_b32_e32 v74, 16, v102
	v_and_b32_e32 v75, 0xffff0000, v102
	v_add_f32_e32 v72, 1.0, v72
	v_add_f32_e32 v73, 1.0, v73
	v_rcp_f32_e32 v72, v72
	v_rcp_f32_e32 v73, v73
	s_nop 0
	v_pk_fma_f32 v[72:73], v[64:65], v[72:73], v[74:75]
	v_lshlrev_b32_e32 v64, 16, v107
	v_and_b32_e32 v65, 0xffff0000, v107
	v_mul_f32_e32 v64, 0xbfb8aa3b, v64
	v_mul_f32_e32 v65, 0xbfb8aa3b, v65
	v_exp_f32_e32 v64, v64
	v_exp_f32_e32 v65, v65
	v_lshlrev_b32_e32 v74, 16, v103
	v_and_b32_e32 v75, 0xffff0000, v103
	v_add_f32_e32 v64, 1.0, v64
	v_add_f32_e32 v65, 1.0, v65
	v_rcp_f32_e32 v64, v64
	v_rcp_f32_e32 v65, v65
	s_nop 0
	v_pk_fma_f32 v[74:75], v[66:67], v[64:65], v[74:75]
	v_cvt_pk_bf16_f32 v64, v68, v69
	v_cvt_pk_bf16_f32 v65, v70, v71
	v_cvt_pk_bf16_f32 v66, v72, v73
	v_cvt_pk_bf16_f32 v67, v74, v75
	global_store_dwordx4 v[84:85], v[64:67], off offset:256
	s_nop 1
	v_add_u32_e32 v64, 0x80, v186
	v_ashrrev_i32_e32 v65, 31, v64
	v_lshlrev_b32_e32 v66, 9, v64
	v_and_b32_e32 v166, 0x1fe00, v66
	v_lshlrev_b64 v[94:95], 11, v[64:65]
	v_lshl_add_u64 v[66:67], v[188:189], 0, v[166:167]
	v_lshl_add_u64 v[64:65], v[190:191], 0, v[94:95]
	global_load_dwordx4 v[96:99], v[66:67], off
	global_load_dwordx4 v[88:91], v[66:67], off offset:256
	global_load_dwordx4 v[100:103], v[64:65], off
	global_load_dwordx4 v[84:87], v[64:65], off offset:256
	v_add_u32_e32 v64, 0x90, v186
	v_ashrrev_i32_e32 v65, 31, v64
	v_lshlrev_b32_e32 v66, 9, v64
	v_and_b32_e32 v166, 0x1fe00, v66
	v_lshlrev_b64 v[92:93], 11, v[64:65]
	v_lshl_add_u64 v[66:67], v[188:189], 0, v[166:167]
	v_lshl_add_u64 v[64:65], v[190:191], 0, v[92:93]
	global_load_dwordx4 v[76:79], v[66:67], off
	global_load_dwordx4 v[68:71], v[66:67], off offset:256
	global_load_dwordx4 v[72:75], v[64:65], off
	s_nop 0
	global_load_dwordx4 v[64:67], v[64:65], off offset:256
	s_waitcnt vmcnt(0)
	v_lshlrev_b32_e32 v104, 16, v96
	v_and_b32_e32 v96, 0xffff0000, v96
	v_mul_f32_e32 v96, 0xbfb8aa3b, v96
	v_exp_f32_e32 v96, v96
	v_lshlrev_b32_e32 v106, 16, v100
	v_and_b32_e32 v107, 0xffff0000, v100
	v_lshlrev_b32_e32 v100, 16, v101
	v_add_f32_e32 v96, 1.0, v96
	v_rcp_f32_e32 v105, v96
	v_lshlrev_b32_e32 v96, 16, v97
	v_and_b32_e32 v97, 0xffff0000, v97
	v_mul_f32_e32 v96, 0xbfb8aa3b, v96
	v_mul_f32_e32 v97, 0xbfb8aa3b, v97
	v_exp_f32_e32 v96, v96
	v_exp_f32_e32 v97, v97
	v_and_b32_e32 v101, 0xffff0000, v101
	v_mul_f32_e32 v104, 0xbfb8aa3b, v104
	v_add_f32_e32 v96, 1.0, v96
	v_add_f32_e32 v97, 1.0, v97
	v_rcp_f32_e32 v96, v96
	v_rcp_f32_e32 v97, v97
	v_exp_f32_e32 v104, v104
	v_lshl_add_u64 v[94:95], v[184:185], 0, v[94:95]
	v_pk_fma_f32 v[62:63], v[62:63], v[96:97], v[100:101]
	v_lshlrev_b32_e32 v96, 16, v98
	v_and_b32_e32 v97, 0xffff0000, v98
	v_mul_f32_e32 v96, 0xbfb8aa3b, v96
	v_mul_f32_e32 v97, 0xbfb8aa3b, v97
	v_exp_f32_e32 v96, v96
	v_exp_f32_e32 v97, v97
	v_lshlrev_b32_e32 v100, 16, v102
	v_and_b32_e32 v101, 0xffff0000, v102
	v_add_f32_e32 v96, 1.0, v96
	v_add_f32_e32 v97, 1.0, v97
	v_rcp_f32_e32 v96, v96
	v_rcp_f32_e32 v97, v97
	v_add_f32_e32 v104, 1.0, v104
	v_rcp_f32_e32 v104, v104
	v_lshlrev_b32_e32 v98, 16, v103
	v_pk_fma_f32 v[96:97], v[56:57], v[96:97], v[100:101]
	v_lshlrev_b32_e32 v56, 16, v99
	v_and_b32_e32 v57, 0xffff0000, v99
	v_mul_f32_e32 v56, 0xbfb8aa3b, v56
	v_mul_f32_e32 v57, 0xbfb8aa3b, v57
	v_exp_f32_e32 v56, v56
	v_exp_f32_e32 v57, v57
	v_and_b32_e32 v99, 0xffff0000, v103
	v_pk_fma_f32 v[60:61], v[60:61], v[104:105], v[106:107]
	v_add_f32_e32 v56, 1.0, v56
	v_add_f32_e32 v57, 1.0, v57
	v_rcp_f32_e32 v56, v56
	v_rcp_f32_e32 v57, v57
	s_nop 0
	v_pk_fma_f32 v[98:99], v[58:59], v[56:57], v[98:99]
	v_cvt_pk_bf16_f32 v56, v60, v61
	v_cvt_pk_bf16_f32 v57, v62, v63
	v_cvt_pk_bf16_f32 v58, v96, v97
	v_cvt_pk_bf16_f32 v59, v98, v99
	global_store_dwordx4 v[94:95], v[56:59], off
	s_nop 1
	v_lshlrev_b32_e32 v56, 16, v88
	v_and_b32_e32 v57, 0xffff0000, v88
	v_mul_f32_e32 v56, 0xbfb8aa3b, v56
	v_mul_f32_e32 v57, 0xbfb8aa3b, v57
	v_exp_f32_e32 v56, v56
	v_exp_f32_e32 v57, v57
	v_lshlrev_b32_e32 v58, 16, v84
	v_and_b32_e32 v59, 0xffff0000, v84
	v_add_f32_e32 v56, 1.0, v56
	v_add_f32_e32 v57, 1.0, v57
	v_rcp_f32_e32 v56, v56
	v_rcp_f32_e32 v57, v57
	s_nop 0
	v_pk_fma_f32 v[52:53], v[52:53], v[56:57], v[58:59]
	v_lshlrev_b32_e32 v56, 16, v89
	v_and_b32_e32 v57, 0xffff0000, v89
	v_mul_f32_e32 v56, 0xbfb8aa3b, v56
	v_mul_f32_e32 v57, 0xbfb8aa3b, v57
	v_exp_f32_e32 v56, v56
	v_exp_f32_e32 v57, v57
	v_lshlrev_b32_e32 v58, 16, v85
	v_and_b32_e32 v59, 0xffff0000, v85
	v_add_f32_e32 v56, 1.0, v56
	v_add_f32_e32 v57, 1.0, v57
	v_rcp_f32_e32 v56, v56
	v_rcp_f32_e32 v57, v57
	s_nop 0
	v_pk_fma_f32 v[54:55], v[54:55], v[56:57], v[58:59]
	v_lshlrev_b32_e32 v56, 16, v90
	v_and_b32_e32 v57, 0xffff0000, v90
	v_mul_f32_e32 v56, 0xbfb8aa3b, v56
	v_mul_f32_e32 v57, 0xbfb8aa3b, v57
	v_exp_f32_e32 v56, v56
	v_exp_f32_e32 v57, v57
	v_lshlrev_b32_e32 v58, 16, v86
	v_and_b32_e32 v59, 0xffff0000, v86
	v_add_f32_e32 v56, 1.0, v56
	v_add_f32_e32 v57, 1.0, v57
	v_rcp_f32_e32 v56, v56
	v_rcp_f32_e32 v57, v57
	s_nop 0
	v_pk_fma_f32 v[56:57], v[48:49], v[56:57], v[58:59]
	v_lshlrev_b32_e32 v48, 16, v91
	v_and_b32_e32 v49, 0xffff0000, v91
	v_mul_f32_e32 v48, 0xbfb8aa3b, v48
	v_mul_f32_e32 v49, 0xbfb8aa3b, v49
	v_exp_f32_e32 v48, v48
	v_exp_f32_e32 v49, v49
	v_lshlrev_b32_e32 v58, 16, v87
	v_and_b32_e32 v59, 0xffff0000, v87
	v_add_f32_e32 v48, 1.0, v48
	v_add_f32_e32 v49, 1.0, v49
	v_rcp_f32_e32 v48, v48
	v_rcp_f32_e32 v49, v49
	s_nop 0
	v_pk_fma_f32 v[58:59], v[50:51], v[48:49], v[58:59]
	v_cvt_pk_bf16_f32 v48, v52, v53
	v_cvt_pk_bf16_f32 v49, v54, v55
	v_cvt_pk_bf16_f32 v50, v56, v57
	v_cvt_pk_bf16_f32 v51, v58, v59
	global_store_dwordx4 v[94:95], v[48:51], off offset:256
	v_lshlrev_b32_e32 v52, 16, v72
	v_and_b32_e32 v53, 0xffff0000, v72
	v_lshlrev_b32_e32 v50, 16, v76
	v_and_b32_e32 v51, 0xffff0000, v76
	v_mul_f32_e32 v50, 0xbfb8aa3b, v50
	v_mul_f32_e32 v51, 0xbfb8aa3b, v51
	v_exp_f32_e32 v50, v50
	v_exp_f32_e32 v51, v51
	v_lshl_add_u64 v[48:49], v[184:185], 0, v[92:93]
	v_add_f32_e32 v50, 1.0, v50
	v_add_f32_e32 v51, 1.0, v51
	v_rcp_f32_e32 v50, v50
	v_rcp_f32_e32 v51, v51
	s_nop 0
	v_pk_fma_f32 v[44:45], v[44:45], v[50:51], v[52:53]
	v_lshlrev_b32_e32 v50, 16, v77
	v_and_b32_e32 v51, 0xffff0000, v77
	v_mul_f32_e32 v50, 0xbfb8aa3b, v50
	v_mul_f32_e32 v51, 0xbfb8aa3b, v51
	v_exp_f32_e32 v50, v50
	v_exp_f32_e32 v51, v51
	v_lshlrev_b32_e32 v52, 16, v73
	v_and_b32_e32 v53, 0xffff0000, v73
	v_add_f32_e32 v50, 1.0, v50
	v_add_f32_e32 v51, 1.0, v51
	v_rcp_f32_e32 v50, v50
	v_rcp_f32_e32 v51, v51
	s_nop 0
	v_pk_fma_f32 v[46:47], v[46:47], v[50:51], v[52:53]
	v_lshlrev_b32_e32 v50, 16, v78
	v_and_b32_e32 v51, 0xffff0000, v78
	v_mul_f32_e32 v50, 0xbfb8aa3b, v50
	v_mul_f32_e32 v51, 0xbfb8aa3b, v51
	v_exp_f32_e32 v50, v50
	v_exp_f32_e32 v51, v51
	v_lshlrev_b32_e32 v52, 16, v74
	v_and_b32_e32 v53, 0xffff0000, v74
	v_add_f32_e32 v50, 1.0, v50
	v_add_f32_e32 v51, 1.0, v51
	v_rcp_f32_e32 v50, v50
	v_rcp_f32_e32 v51, v51
	s_nop 0
	v_pk_fma_f32 v[50:51], v[40:41], v[50:51], v[52:53]
	v_lshlrev_b32_e32 v40, 16, v79
	v_and_b32_e32 v41, 0xffff0000, v79
	v_mul_f32_e32 v40, 0xbfb8aa3b, v40
	v_mul_f32_e32 v41, 0xbfb8aa3b, v41
	v_exp_f32_e32 v40, v40
	v_exp_f32_e32 v41, v41
	v_lshlrev_b32_e32 v52, 16, v75
	v_and_b32_e32 v53, 0xffff0000, v75
	v_add_f32_e32 v40, 1.0, v40
	v_add_f32_e32 v41, 1.0, v41
	v_rcp_f32_e32 v40, v40
	v_rcp_f32_e32 v41, v41
	s_nop 0
	v_pk_fma_f32 v[52:53], v[42:43], v[40:41], v[52:53]
	v_cvt_pk_bf16_f32 v40, v44, v45
	v_cvt_pk_bf16_f32 v41, v46, v47
	v_cvt_pk_bf16_f32 v42, v50, v51
	v_cvt_pk_bf16_f32 v43, v52, v53
	global_store_dwordx4 v[48:49], v[40:43], off
	s_nop 1
	v_lshlrev_b32_e32 v40, 16, v68
	v_and_b32_e32 v41, 0xffff0000, v68
	v_mul_f32_e32 v40, 0xbfb8aa3b, v40
	v_mul_f32_e32 v41, 0xbfb8aa3b, v41
	v_exp_f32_e32 v40, v40
	v_exp_f32_e32 v41, v41
	v_lshlrev_b32_e32 v42, 16, v64
	v_and_b32_e32 v43, 0xffff0000, v64
	v_add_f32_e32 v40, 1.0, v40
	v_add_f32_e32 v41, 1.0, v41
	v_rcp_f32_e32 v40, v40
	v_rcp_f32_e32 v41, v41
	s_nop 0
	v_pk_fma_f32 v[36:37], v[36:37], v[40:41], v[42:43]
	v_lshlrev_b32_e32 v40, 16, v69
	v_and_b32_e32 v41, 0xffff0000, v69
	v_mul_f32_e32 v40, 0xbfb8aa3b, v40
	v_mul_f32_e32 v41, 0xbfb8aa3b, v41
	v_exp_f32_e32 v40, v40
	v_exp_f32_e32 v41, v41
	v_lshlrev_b32_e32 v42, 16, v65
	v_and_b32_e32 v43, 0xffff0000, v65
	v_add_f32_e32 v40, 1.0, v40
	v_add_f32_e32 v41, 1.0, v41
	v_rcp_f32_e32 v40, v40
	v_rcp_f32_e32 v41, v41
	s_nop 0
	v_pk_fma_f32 v[38:39], v[38:39], v[40:41], v[42:43]
	v_lshlrev_b32_e32 v40, 16, v70
	v_and_b32_e32 v41, 0xffff0000, v70
	v_mul_f32_e32 v40, 0xbfb8aa3b, v40
	v_mul_f32_e32 v41, 0xbfb8aa3b, v41
	v_exp_f32_e32 v40, v40
	v_exp_f32_e32 v41, v41
	v_lshlrev_b32_e32 v42, 16, v66
	v_and_b32_e32 v43, 0xffff0000, v66
	v_add_f32_e32 v40, 1.0, v40
	v_add_f32_e32 v41, 1.0, v41
	v_rcp_f32_e32 v40, v40
	v_rcp_f32_e32 v41, v41
	s_nop 0
	v_pk_fma_f32 v[40:41], v[32:33], v[40:41], v[42:43]
	v_lshlrev_b32_e32 v32, 16, v71
	v_and_b32_e32 v33, 0xffff0000, v71
	v_mul_f32_e32 v32, 0xbfb8aa3b, v32
	v_mul_f32_e32 v33, 0xbfb8aa3b, v33
	v_exp_f32_e32 v32, v32
	v_exp_f32_e32 v33, v33
	v_lshlrev_b32_e32 v42, 16, v67
	v_and_b32_e32 v43, 0xffff0000, v67
	v_add_f32_e32 v32, 1.0, v32
	v_add_f32_e32 v33, 1.0, v33
	v_rcp_f32_e32 v32, v32
	v_rcp_f32_e32 v33, v33
	s_nop 0
	v_pk_fma_f32 v[42:43], v[34:35], v[32:33], v[42:43]
	v_cvt_pk_bf16_f32 v32, v36, v37
	v_cvt_pk_bf16_f32 v33, v38, v39
	v_cvt_pk_bf16_f32 v34, v40, v41
	v_cvt_pk_bf16_f32 v35, v42, v43
	global_store_dwordx4 v[48:49], v[32:35], off offset:256
	s_nop 1
	v_add_u32_e32 v32, 0xa0, v186
	v_ashrrev_i32_e32 v33, 31, v32
	v_lshlrev_b32_e32 v34, 9, v32
	v_and_b32_e32 v166, 0x1fe00, v34
	v_lshlrev_b64 v[58:59], 11, v[32:33]
	v_lshl_add_u64 v[34:35], v[188:189], 0, v[166:167]
	v_lshl_add_u64 v[32:33], v[190:191], 0, v[58:59]
	global_load_dwordx4 v[60:63], v[34:35], off
	global_load_dwordx4 v[52:55], v[34:35], off offset:256
	global_load_dwordx4 v[64:67], v[32:33], off
	global_load_dwordx4 v[48:51], v[32:33], off offset:256
	v_add_u32_e32 v32, 0xb0, v186
	v_ashrrev_i32_e32 v33, 31, v32
	v_lshlrev_b32_e32 v34, 9, v32
	v_and_b32_e32 v166, 0x1fe00, v34
	v_lshlrev_b64 v[56:57], 11, v[32:33]
	v_lshl_add_u64 v[34:35], v[188:189], 0, v[166:167]
	v_lshl_add_u64 v[32:33], v[190:191], 0, v[56:57]
	global_load_dwordx4 v[44:47], v[34:35], off
	global_load_dwordx4 v[36:39], v[34:35], off offset:256
	global_load_dwordx4 v[40:43], v[32:33], off
	s_nop 0
	global_load_dwordx4 v[32:35], v[32:33], off offset:256
	s_waitcnt vmcnt(0)
	v_lshlrev_b32_e32 v68, 16, v60
	v_and_b32_e32 v60, 0xffff0000, v60
	v_mul_f32_e32 v60, 0xbfb8aa3b, v60
	v_exp_f32_e32 v60, v60
	v_lshlrev_b32_e32 v70, 16, v64
	v_and_b32_e32 v71, 0xffff0000, v64
	v_lshlrev_b32_e32 v64, 16, v65
	v_add_f32_e32 v60, 1.0, v60
	v_rcp_f32_e32 v69, v60
	v_lshlrev_b32_e32 v60, 16, v61
	v_and_b32_e32 v61, 0xffff0000, v61
	v_mul_f32_e32 v60, 0xbfb8aa3b, v60
	v_mul_f32_e32 v61, 0xbfb8aa3b, v61
	v_exp_f32_e32 v60, v60
	v_exp_f32_e32 v61, v61
	v_and_b32_e32 v65, 0xffff0000, v65
	v_mul_f32_e32 v68, 0xbfb8aa3b, v68
	v_add_f32_e32 v60, 1.0, v60
	v_add_f32_e32 v61, 1.0, v61
	v_rcp_f32_e32 v60, v60
	v_rcp_f32_e32 v61, v61
	v_exp_f32_e32 v68, v68
	v_lshl_add_u64 v[58:59], v[184:185], 0, v[58:59]
	v_pk_fma_f32 v[30:31], v[30:31], v[60:61], v[64:65]
	v_lshlrev_b32_e32 v60, 16, v62
	v_and_b32_e32 v61, 0xffff0000, v62
	v_mul_f32_e32 v60, 0xbfb8aa3b, v60
	v_mul_f32_e32 v61, 0xbfb8aa3b, v61
	v_exp_f32_e32 v60, v60
	v_exp_f32_e32 v61, v61
	v_lshlrev_b32_e32 v64, 16, v66
	v_and_b32_e32 v65, 0xffff0000, v66
	v_add_f32_e32 v60, 1.0, v60
	v_add_f32_e32 v61, 1.0, v61
	v_rcp_f32_e32 v60, v60
	v_rcp_f32_e32 v61, v61
	v_add_f32_e32 v68, 1.0, v68
	v_rcp_f32_e32 v68, v68
	v_lshlrev_b32_e32 v62, 16, v67
	v_pk_fma_f32 v[60:61], v[24:25], v[60:61], v[64:65]
	v_lshlrev_b32_e32 v24, 16, v63
	v_and_b32_e32 v25, 0xffff0000, v63
	v_mul_f32_e32 v24, 0xbfb8aa3b, v24
	v_mul_f32_e32 v25, 0xbfb8aa3b, v25
	v_exp_f32_e32 v24, v24
	v_exp_f32_e32 v25, v25
	v_and_b32_e32 v63, 0xffff0000, v67
	v_pk_fma_f32 v[28:29], v[28:29], v[68:69], v[70:71]
	v_add_f32_e32 v24, 1.0, v24
	v_add_f32_e32 v25, 1.0, v25
	v_rcp_f32_e32 v24, v24
	v_rcp_f32_e32 v25, v25
	s_nop 0
	v_pk_fma_f32 v[62:63], v[26:27], v[24:25], v[62:63]
	v_cvt_pk_bf16_f32 v24, v28, v29
	v_cvt_pk_bf16_f32 v25, v30, v31
	v_cvt_pk_bf16_f32 v26, v60, v61
	v_cvt_pk_bf16_f32 v27, v62, v63
	global_store_dwordx4 v[58:59], v[24:27], off
	s_nop 1
	v_lshlrev_b32_e32 v24, 16, v52
	v_and_b32_e32 v25, 0xffff0000, v52
	v_mul_f32_e32 v24, 0xbfb8aa3b, v24
	v_mul_f32_e32 v25, 0xbfb8aa3b, v25
	v_exp_f32_e32 v24, v24
	v_exp_f32_e32 v25, v25
	v_lshlrev_b32_e32 v26, 16, v48
	v_and_b32_e32 v27, 0xffff0000, v48
	v_add_f32_e32 v24, 1.0, v24
	v_add_f32_e32 v25, 1.0, v25
	v_rcp_f32_e32 v24, v24
	v_rcp_f32_e32 v25, v25
	s_nop 0
	v_pk_fma_f32 v[20:21], v[20:21], v[24:25], v[26:27]
	v_lshlrev_b32_e32 v24, 16, v53
	v_and_b32_e32 v25, 0xffff0000, v53
	v_mul_f32_e32 v24, 0xbfb8aa3b, v24
	v_mul_f32_e32 v25, 0xbfb8aa3b, v25
	v_exp_f32_e32 v24, v24
	v_exp_f32_e32 v25, v25
	v_lshlrev_b32_e32 v26, 16, v49
	v_and_b32_e32 v27, 0xffff0000, v49
	v_add_f32_e32 v24, 1.0, v24
	v_add_f32_e32 v25, 1.0, v25
	v_rcp_f32_e32 v24, v24
	v_rcp_f32_e32 v25, v25
	s_nop 0
	v_pk_fma_f32 v[22:23], v[22:23], v[24:25], v[26:27]
	v_lshlrev_b32_e32 v24, 16, v54
	v_and_b32_e32 v25, 0xffff0000, v54
	v_mul_f32_e32 v24, 0xbfb8aa3b, v24
	v_mul_f32_e32 v25, 0xbfb8aa3b, v25
	v_exp_f32_e32 v24, v24
	v_exp_f32_e32 v25, v25
	v_lshlrev_b32_e32 v26, 16, v50
	v_and_b32_e32 v27, 0xffff0000, v50
	v_add_f32_e32 v24, 1.0, v24
	v_add_f32_e32 v25, 1.0, v25
	v_rcp_f32_e32 v24, v24
	v_rcp_f32_e32 v25, v25
	s_nop 0
	v_pk_fma_f32 v[24:25], v[16:17], v[24:25], v[26:27]
	v_lshlrev_b32_e32 v16, 16, v55
	v_and_b32_e32 v17, 0xffff0000, v55
	v_mul_f32_e32 v16, 0xbfb8aa3b, v16
	v_mul_f32_e32 v17, 0xbfb8aa3b, v17
	v_exp_f32_e32 v16, v16
	v_exp_f32_e32 v17, v17
	v_lshlrev_b32_e32 v26, 16, v51
	v_and_b32_e32 v27, 0xffff0000, v51
	v_add_f32_e32 v16, 1.0, v16
	v_add_f32_e32 v17, 1.0, v17
	v_rcp_f32_e32 v16, v16
	v_rcp_f32_e32 v17, v17
	s_nop 0
	v_pk_fma_f32 v[26:27], v[18:19], v[16:17], v[26:27]
	v_cvt_pk_bf16_f32 v16, v20, v21
	v_cvt_pk_bf16_f32 v17, v22, v23
	v_cvt_pk_bf16_f32 v18, v24, v25
	v_cvt_pk_bf16_f32 v19, v26, v27
	global_store_dwordx4 v[58:59], v[16:19], off offset:256
	v_lshlrev_b32_e32 v20, 16, v40
	v_and_b32_e32 v21, 0xffff0000, v40
	v_lshlrev_b32_e32 v18, 16, v44
	v_and_b32_e32 v19, 0xffff0000, v44
	v_mul_f32_e32 v18, 0xbfb8aa3b, v18
	v_mul_f32_e32 v19, 0xbfb8aa3b, v19
	v_exp_f32_e32 v18, v18
	v_exp_f32_e32 v19, v19
	v_lshl_add_u64 v[16:17], v[184:185], 0, v[56:57]
	v_add_f32_e32 v18, 1.0, v18
	v_add_f32_e32 v19, 1.0, v19
	v_rcp_f32_e32 v18, v18
	v_rcp_f32_e32 v19, v19
	s_nop 0
	v_pk_fma_f32 v[12:13], v[12:13], v[18:19], v[20:21]
	v_lshlrev_b32_e32 v18, 16, v45
	v_and_b32_e32 v19, 0xffff0000, v45
	v_mul_f32_e32 v18, 0xbfb8aa3b, v18
	v_mul_f32_e32 v19, 0xbfb8aa3b, v19
	v_exp_f32_e32 v18, v18
	v_exp_f32_e32 v19, v19
	v_lshlrev_b32_e32 v20, 16, v41
	v_and_b32_e32 v21, 0xffff0000, v41
	v_add_f32_e32 v18, 1.0, v18
	v_add_f32_e32 v19, 1.0, v19
	v_rcp_f32_e32 v18, v18
	v_rcp_f32_e32 v19, v19
	s_nop 0
	v_pk_fma_f32 v[14:15], v[14:15], v[18:19], v[20:21]
	v_lshlrev_b32_e32 v18, 16, v46
	v_and_b32_e32 v19, 0xffff0000, v46
	v_mul_f32_e32 v18, 0xbfb8aa3b, v18
	v_mul_f32_e32 v19, 0xbfb8aa3b, v19
	v_exp_f32_e32 v18, v18
	v_exp_f32_e32 v19, v19
	v_lshlrev_b32_e32 v20, 16, v42
	v_and_b32_e32 v21, 0xffff0000, v42
	v_add_f32_e32 v18, 1.0, v18
	v_add_f32_e32 v19, 1.0, v19
	v_rcp_f32_e32 v18, v18
	v_rcp_f32_e32 v19, v19
	s_nop 0
	v_pk_fma_f32 v[18:19], v[8:9], v[18:19], v[20:21]
	v_lshlrev_b32_e32 v8, 16, v47
	v_and_b32_e32 v9, 0xffff0000, v47
	v_mul_f32_e32 v8, 0xbfb8aa3b, v8
	v_mul_f32_e32 v9, 0xbfb8aa3b, v9
	v_exp_f32_e32 v8, v8
	v_exp_f32_e32 v9, v9
	v_lshlrev_b32_e32 v20, 16, v43
	v_and_b32_e32 v21, 0xffff0000, v43
	v_add_f32_e32 v8, 1.0, v8
	v_add_f32_e32 v9, 1.0, v9
	v_rcp_f32_e32 v8, v8
	v_rcp_f32_e32 v9, v9
	s_nop 0
	v_pk_fma_f32 v[20:21], v[10:11], v[8:9], v[20:21]
	v_cvt_pk_bf16_f32 v8, v12, v13
	v_cvt_pk_bf16_f32 v9, v14, v15
	v_cvt_pk_bf16_f32 v10, v18, v19
	v_cvt_pk_bf16_f32 v11, v20, v21
	global_store_dwordx4 v[16:17], v[8:11], off
	s_nop 1
	v_lshlrev_b32_e32 v8, 16, v36
	v_and_b32_e32 v9, 0xffff0000, v36
	v_mul_f32_e32 v8, 0xbfb8aa3b, v8
	v_mul_f32_e32 v9, 0xbfb8aa3b, v9
	v_exp_f32_e32 v8, v8
	v_exp_f32_e32 v9, v9
	v_lshlrev_b32_e32 v10, 16, v32
	v_and_b32_e32 v11, 0xffff0000, v32
	v_add_f32_e32 v8, 1.0, v8
	v_add_f32_e32 v9, 1.0, v9
	v_rcp_f32_e32 v8, v8
	v_rcp_f32_e32 v9, v9
	s_nop 0
	v_pk_fma_f32 v[4:5], v[4:5], v[8:9], v[10:11]
	v_lshlrev_b32_e32 v8, 16, v37
	v_and_b32_e32 v9, 0xffff0000, v37
	v_mul_f32_e32 v8, 0xbfb8aa3b, v8
	v_mul_f32_e32 v9, 0xbfb8aa3b, v9
	v_exp_f32_e32 v8, v8
	v_exp_f32_e32 v9, v9
	v_lshlrev_b32_e32 v10, 16, v33
	v_and_b32_e32 v11, 0xffff0000, v33
	v_add_f32_e32 v8, 1.0, v8
	v_add_f32_e32 v9, 1.0, v9
	v_rcp_f32_e32 v8, v8
	v_rcp_f32_e32 v9, v9
	s_nop 0
	v_pk_fma_f32 v[6:7], v[6:7], v[8:9], v[10:11]
	v_lshlrev_b32_e32 v8, 16, v38
	v_and_b32_e32 v9, 0xffff0000, v38
	v_mul_f32_e32 v8, 0xbfb8aa3b, v8
	v_mul_f32_e32 v9, 0xbfb8aa3b, v9
	v_exp_f32_e32 v8, v8
	v_exp_f32_e32 v9, v9
	v_lshlrev_b32_e32 v10, 16, v34
	v_and_b32_e32 v11, 0xffff0000, v34
	v_add_f32_e32 v8, 1.0, v8
	v_add_f32_e32 v9, 1.0, v9
	v_rcp_f32_e32 v8, v8
	v_rcp_f32_e32 v9, v9
	s_nop 0
	v_pk_fma_f32 v[8:9], v[0:1], v[8:9], v[10:11]
	v_lshlrev_b32_e32 v0, 16, v39
	v_and_b32_e32 v1, 0xffff0000, v39
	v_mul_f32_e32 v0, 0xbfb8aa3b, v0
	v_mul_f32_e32 v1, 0xbfb8aa3b, v1
	v_exp_f32_e32 v0, v0
	v_exp_f32_e32 v1, v1
	v_lshlrev_b32_e32 v10, 16, v35
	v_and_b32_e32 v11, 0xffff0000, v35
	v_add_f32_e32 v0, 1.0, v0
	v_add_f32_e32 v1, 1.0, v1
	v_rcp_f32_e32 v0, v0
	v_rcp_f32_e32 v1, v1
	s_nop 0
	v_pk_fma_f32 v[10:11], v[2:3], v[0:1], v[10:11]
	v_cvt_pk_bf16_f32 v0, v4, v5
	v_cvt_pk_bf16_f32 v1, v6, v7
	v_cvt_pk_bf16_f32 v2, v8, v9
	v_cvt_pk_bf16_f32 v3, v10, v11
	global_store_dwordx4 v[16:17], v[0:3], off offset:256
